# MFMA blocks run at wave priority 3 instead of 1
# baseline (speedup 1.0000x reference)
;     __host__ __device__ bool next(int i, Unit& u) const { if (!b.next(i >> 1, u)) return false; u.sel = i & 1; return true; }
; #define PG8_STAGE(bufoff, gbase, voff) do { _Pragma("unroll") for (int _i = 0; _i < 2; ++_i) \
;         __builtin_amdgcn_global_load_lds((const unsigned*)((const char*)(gbase) + (voff)[_i]), (PG8_LAS unsigned*)(lds + (bufoff) + ldsw + _i * 8192), 16, 0, 0); } while (0)
; #define PG8_LDA(dst, b, h) do { _Pragma("unroll") for (int m = 0; m < 4; ++m) _Pragma("unroll") for (int k = 0; k < 2; ++k) dst[m][k] = *(const PG8_LAS bf16x8*)(lds + PG8_SA(b, h) + aoff + m * 2048 + k * 1024); } while (0)
; #define PG8_LDB(dst, b, h) do { _Pragma("unroll") for (int n = 0; n < 2; ++n) _Pragma("unroll") for (int k = 0; k < 2; ++k) dst[n][k] = *(const PG8_LAS bf16x8*)(lds + PG8_SB(b, h) + boff + n * 2048 + k * 1024); } while (0)
; #define PG8_WAIT_V(n) asm volatile("s_waitcnt vmcnt(" #n ")" ::: "memory")
; #define PG8_BAR __builtin_amdgcn_s_barrier()
; template <class Epi, class Sched, bool ALIGN_EPI = false, bool SP2 = false>
; __device__ __forceinline__ void gemm_phase(PG8_LAS unsigned char* lds, const Gemm g, const Sched& S, const Epi& E) {
;     ...
;         const bool has_next = S.next(ui + 1, nxt);
;         const char* nA = has_next ? PG8_ABASE(nxt) : cA; const char* nB = has_next ? PG8_BBASE(nxt) : cB;
;         for (int t = 0; t < nt; t += 2) {
;             const bool last = (t == nt - 2);
;             const char* a1 = cA + (size_t)(t + 1) * kstepA;
;             const char* a2 = last ? nA : cA + (size_t)(t + 2) * kstepA; const char* b2 = last ? nB : cB + (size_t)(t + 2) * kstep;
;             const char* a3 = a2 + kstepA; const char* b3 = b2 + kstep;
;             if (last && has_next) S.a_ready(nxt);
;             if constexpr (SP2) {
;             PG8_LDB(B0, 0, 0); PG8_LDB(B1, 0, 1); PG8_SCHED; PG8_LDA(At, 0, 0); PG8_STAGE(PG8_SA(1, 1), a1 + hstep, voffA);
;             PG8_WAIT_V(8); PG8_WAIT_L(0); PG8_BAR; PG8_MMA(0, 0, At, B0); PG8_MMA(0, 1, At, B1); PG8_BAR; PG8_SCHED;
;             if constexpr (Epi::PREFETCH) { if (t == tpf) E.prefetch(cur, wid, lane); }
;             PG8_LDA(At, 0, 1); PG8_STAGE(PG8_SB(0, 0), b2, voffB); PG8_STAGE(PG8_SB(0, 1), b2 + hstep, voffB); PG8_STAGE(PG8_SA(0, 0), a2, voffA);
;             PG8_WAIT_V(8); PG8_WAIT_L(0); PG8_BAR; PG8_MMA(1, 0, At, B0); PG8_MMA(1, 1, At, B1); PG8_BAR; PG8_SCHED;
.LBB0_205:
	s_add_u32 s22, s22, 0x40080
	s_addc_u32 s23, s23, 0
	s_add_u32 s52, s24, 0x100
	s_addc_u32 s53, s25, 0
	s_mov_b32 s54, -2
	ds_read_b128 v[154:157], v150
	ds_read_b128 v[158:161], v150 offset:1024
	ds_read_b128 v[162:165], v150 offset:2048
	ds_read_b128 v[166:169], v150 offset:3072
	ds_read_b128 v[170:173], v151
	ds_read_b128 v[174:177], v151 offset:1024
	ds_read_b128 v[178:181], v151 offset:2048
	ds_read_b128 v[182:185], v151 offset:3072
	s_add_u32 s24, s22, 0xfffc0080
	s_addc_u32 s25, s23, -1
	s_cmp_eq_u32 s54, 12
	s_cselect_b32 s27, s15, s25
	s_cselect_b32 s26, s50, s24
	s_cselect_b32 s25, s13, s53
	s_cselect_b32 s24, s51, s52
	v_lshl_add_u64 v[218:219], s[22:23], 0, v[140:141]
	s_add_i32 m0, s37, 0xc000
	ds_read_b128 v[186:189], v152
	ds_read_b128 v[190:193], v152 offset:1024
	ds_read_b128 v[194:197], v152 offset:2048
	ds_read_b128 v[198:201], v152 offset:3072
	ds_read_b128 v[202:205], v152 offset:4096
	ds_read_b128 v[206:209], v152 offset:5120
	ds_read_b128 v[210:213], v152 offset:6144
	ds_read_b128 v[214:217], v152 offset:7168
	global_load_lds_dwordx4 v[218:219], off
	v_lshl_add_u64 v[218:219], s[22:23], 0, v[142:143]
	s_add_i32 m0, s37, 0xe000
	s_nop 0
	global_load_lds_dwordx4 v[218:219], off
	s_add_i32 s44, s44, 1
	s_mul_i32 s0, s44, s46
	s_mul_hi_u32 s1, s44, s33
	s_add_i32 s1, s1, s0
	s_mul_i32 s0, s44, s33
	s_add_u32 s16, s0, s87
	s_addc_u32 s17, s1, s35
	v_cmp_lt_i64_e64 s[0:1], s[16:17], v[144:145]
	s_ashr_i32 s12, s16, 31
	s_lshr_b32 s12, s12, 29
	s_add_i32 s12, s16, s12
	s_ashr_i32 s13, s12, 3
	s_and_b32 s12, s12, -8
	s_sub_i32 s12, s16, s12
	s_cmp_lt_i32 s12, 0
	s_cselect_b32 s14, s36, 0x160
	s_mul_i32 s12, s12, s14
	s_add_i32 s12, s12, s13
	s_mul_hi_i32 s13, s12, 0x2e8ba2e9
	s_lshr_b32 s14, s13, 31
	s_ashr_i32 s13, s13, 3
	s_add_i32 s13, s13, s14
	s_lshl_b32 s14, s13, 1
	s_mul_i32 s13, s13, 44
	s_sub_i32 s13, s12, s13
	s_lshr_b32 s12, s13, 1
	s_and_b32 s13, s13, 1
	s_add_i32 s14, s14, s13
	s_ashr_i32 s15, s14, 31
	s_lshl_b64 s[16:17], s[14:15], 19
	s_add_u32 s16, s28, s16
	s_addc_u32 s17, s29, s17
	s_and_b64 s[18:19], s[0:1], exec
	s_cselect_b32 s15, s17, s29
	s_cselect_b32 s50, s16, s28
	s_ashr_i32 s13, s12, 31
	s_lshl_b64 s[18:19], s[12:13], 19
	s_add_u32 s18, s30, s18
	s_addc_u32 s19, s31, s19
	s_and_b64 s[98:99], s[0:1], exec
	s_cselect_b32 s13, s19, s31
	s_cselect_b32 s51, s18, s30
	s_waitcnt vmcnt(8)
	s_waitcnt lgkmcnt(0)
	s_barrier
	s_setprio 3
	s_waitcnt lgkmcnt(0)
	v_mfma_f32_16x16x32_bf16 v[126:129], v[154:157], v[186:189], 0
	v_mfma_f32_16x16x32_bf16 v[122:125], v[162:165], v[186:189], 0
	v_mfma_f32_16x16x32_bf16 v[110:113], v[154:157], v[194:197], 0
	v_mfma_f32_16x16x32_bf16 v[106:109], v[162:165], v[194:197], 0
	v_mfma_f32_16x16x32_bf16 v[94:97], v[154:157], v[202:205], 0
	v_mfma_f32_16x16x32_bf16 v[90:93], v[162:165], v[202:205], 0
	v_mfma_f32_16x16x32_bf16 v[78:81], v[154:157], v[210:213], 0
	v_mfma_f32_16x16x32_bf16 v[74:77], v[162:165], v[210:213], 0
	v_mfma_f32_16x16x32_bf16 v[126:129], v[158:161], v[190:193], v[126:129]
	v_mfma_f32_16x16x32_bf16 v[122:125], v[166:169], v[190:193], v[122:125]
	v_mfma_f32_16x16x32_bf16 v[110:113], v[158:161], v[198:201], v[110:113]
	v_mfma_f32_16x16x32_bf16 v[106:109], v[166:169], v[198:201], v[106:109]
	v_mfma_f32_16x16x32_bf16 v[94:97], v[158:161], v[206:209], v[94:97]
	v_mfma_f32_16x16x32_bf16 v[90:93], v[166:169], v[206:209], v[90:93]
	v_mfma_f32_16x16x32_bf16 v[78:81], v[158:161], v[214:217], v[78:81]
	v_mfma_f32_16x16x32_bf16 v[74:77], v[166:169], v[214:217], v[74:77]
	s_setprio 0
	s_setprio 3
	v_mfma_f32_16x16x32_bf16 v[118:121], v[170:173], v[186:189], 0
	v_mfma_f32_16x16x32_bf16 v[114:117], v[178:181], v[186:189], 0
	v_mfma_f32_16x16x32_bf16 v[102:105], v[170:173], v[194:197], 0
	v_mfma_f32_16x16x32_bf16 v[98:101], v[178:181], v[194:197], 0
	v_mfma_f32_16x16x32_bf16 v[86:89], v[170:173], v[202:205], 0
	v_mfma_f32_16x16x32_bf16 v[82:85], v[178:181], v[202:205], 0
	v_mfma_f32_16x16x32_bf16 v[70:73], v[170:173], v[210:213], 0
	v_mfma_f32_16x16x32_bf16 v[66:69], v[178:181], v[210:213], 0
	v_mfma_f32_16x16x32_bf16 v[118:121], v[174:177], v[190:193], v[118:121]
	v_mfma_f32_16x16x32_bf16 v[114:117], v[182:185], v[190:193], v[114:117]
	v_mfma_f32_16x16x32_bf16 v[102:105], v[174:177], v[198:201], v[102:105]
	v_mfma_f32_16x16x32_bf16 v[98:101], v[182:185], v[198:201], v[98:101]
	v_mfma_f32_16x16x32_bf16 v[86:89], v[174:177], v[206:209], v[86:89]
	v_mfma_f32_16x16x32_bf16 v[82:85], v[182:185], v[206:209], v[82:85]
	v_mfma_f32_16x16x32_bf16 v[70:73], v[174:177], v[214:217], v[70:73]
	v_mfma_f32_16x16x32_bf16 v[66:69], v[182:185], v[214:217], v[66:69]
	s_setprio 0
	s_barrier
	s_add_i32 s55, s47, s34
	v_lshl_add_u64 v[218:219], s[24:25], 0, v[134:135]
	s_mov_b32 m0, s55
	ds_read_b128 v[186:189], v152 offset:16384
	ds_read_b128 v[190:193], v152 offset:17408
	ds_read_b128 v[194:197], v152 offset:18432
	ds_read_b128 v[198:201], v152 offset:19456
	ds_read_b128 v[202:205], v152 offset:20480
	ds_read_b128 v[206:209], v152 offset:21504
	ds_read_b128 v[210:213], v152 offset:22528
	ds_read_b128 v[214:217], v152 offset:23552
	global_load_lds_dwordx4 v[218:219], off
	s_add_i32 m0, s55, 0x2000
	s_add_u32 s56, s24, 0x40000
	v_lshl_add_u64 v[222:223], s[24:25], 0, v[130:131]
	s_addc_u32 s57, s25, 0
	s_add_i32 s55, s48, s34
	global_load_lds_dwordx4 v[222:223], off
	v_lshl_add_u64 v[224:225], s[56:57], 0, v[134:135]
	s_mov_b32 m0, s55
	v_lshl_add_u64 v[226:227], s[26:27], 0, v[132:133]
	global_load_lds_dwordx4 v[224:225], off
	v_lshl_add_u64 v[224:225], s[56:57], 0, v[130:131]
	s_add_i32 m0, s55, 0x2000
	s_nop 0
	global_load_lds_dwordx4 v[224:225], off
	v_lshl_add_u64 v[224:225], s[26:27], 0, v[136:137]
	s_mov_b32 m0, s37
	s_nop 0
	global_load_lds_dwordx4 v[224:225], off
	s_mov_b32 m0, s38
	s_nop 0
	global_load_lds_dwordx4 v[226:227], off
	s_waitcnt vmcnt(8)
	s_waitcnt lgkmcnt(0)
	s_barrier
; #define PG8_STAGE(bufoff, gbase, voff) do { _Pragma("unroll") for (int _i = 0; _i < 2; ++_i) \
;         __builtin_amdgcn_global_load_lds((const unsigned*)((const char*)(gbase) + (voff)[_i]), (PG8_LAS unsigned*)(lds + (bufoff) + ldsw + _i * 8192), 16, 0, 0); } while (0)
; #define PG8_LDA(dst, b, h) do { _Pragma("unroll") for (int m = 0; m < 4; ++m) _Pragma("unroll") for (int k = 0; k < 2; ++k) dst[m][k] = *(const PG8_LAS bf16x8*)(lds + PG8_SA(b, h) + aoff + m * 2048 + k * 1024); } while (0)
; #define PG8_LDB(dst, b, h) do { _Pragma("unroll") for (int n = 0; n < 2; ++n) _Pragma("unroll") for (int k = 0; k < 2; ++k) dst[n][k] = *(const PG8_LAS bf16x8*)(lds + PG8_SB(b, h) + boff + n * 2048 + k * 1024); } while (0)
; #define PG8_WAIT_V(n) asm volatile("s_waitcnt vmcnt(" #n ")" ::: "memory")
; #define PG8_WAIT_L(n) asm volatile("s_waitcnt lgkmcnt(" #n ")" ::: "memory")
; #define PG8_BAR __builtin_amdgcn_s_barrier()
; #define PG8_SCHED __builtin_amdgcn_sched_barrier(0)
; template <class Epi, class Sched, bool ALIGN_EPI = false, bool SP2 = false>
; __device__ __forceinline__ void gemm_phase(PG8_LAS unsigned char* lds, const Gemm g, const Sched& S, const Epi& E) {
;     ...
;             PG8_LDB(B0, 0, 0); PG8_LDB(B1, 0, 1); PG8_SCHED; PG8_LDA(At, 0, 0); PG8_STAGE(PG8_SA(1, 1), a1 + hstep, voffA);
;             PG8_WAIT_V(8); PG8_WAIT_L(0); PG8_BAR; PG8_MMA(0, 0, At, B0); PG8_MMA(0, 1, At, B1); PG8_BAR; PG8_SCHED;
;             if constexpr (Epi::PREFETCH) { if (t == tpf) E.prefetch(cur, wid, lane); }
;             PG8_LDA(At, 0, 1); PG8_STAGE(PG8_SB(0, 0), b2, voffB); PG8_STAGE(PG8_SB(0, 1), b2 + hstep, voffB); PG8_STAGE(PG8_SA(0, 0), a2, voffA);
;             PG8_WAIT_V(8); PG8_WAIT_L(0); PG8_BAR; PG8_MMA(1, 0, At, B0); PG8_MMA(1, 1, At, B1); PG8_BAR; PG8_SCHED;
;             PG8_LDB(B0, 1, 0); PG8_LDB(B1, 1, 1); PG8_SCHED; PG8_LDA(At, 1, 0); PG8_STAGE(PG8_SA(0, 1), a2 + hstep, voffA);
;             PG8_WAIT_V(8); PG8_WAIT_L(0); PG8_BAR; PG8_MMA(0, 0, At, B0); PG8_MMA(0, 1, At, B1); PG8_BAR; PG8_SCHED;
;             PG8_LDA(At, 1, 1); PG8_STAGE(PG8_SB(1, 0), b3, voffB); PG8_STAGE(PG8_SB(1, 1), b3 + hstep, voffB); PG8_STAGE(PG8_SA(1, 0), a3, voffA);
;             PG8_WAIT_V(8); PG8_WAIT_L(0); PG8_BAR; PG8_MMA(1, 0, At, B0); PG8_MMA(1, 1, At, B1); PG8_BAR; PG8_SCHED;
	s_setprio 3
	s_waitcnt lgkmcnt(0)
	v_mfma_f32_16x16x32_bf16 v[62:65], v[154:157], v[186:189], 0
	v_mfma_f32_16x16x32_bf16 v[58:61], v[162:165], v[186:189], 0
	v_mfma_f32_16x16x32_bf16 v[46:49], v[154:157], v[194:197], 0
	v_mfma_f32_16x16x32_bf16 v[42:45], v[162:165], v[194:197], 0
	v_mfma_f32_16x16x32_bf16 v[30:33], v[154:157], v[202:205], 0
	v_mfma_f32_16x16x32_bf16 v[26:29], v[162:165], v[202:205], 0
	v_mfma_f32_16x16x32_bf16 v[14:17], v[154:157], v[210:213], 0
	v_mfma_f32_16x16x32_bf16 v[10:13], v[162:165], v[210:213], 0
	v_mfma_f32_16x16x32_bf16 v[62:65], v[158:161], v[190:193], v[62:65]
	v_mfma_f32_16x16x32_bf16 v[58:61], v[166:169], v[190:193], v[58:61]
	v_mfma_f32_16x16x32_bf16 v[46:49], v[158:161], v[198:201], v[46:49]
	v_mfma_f32_16x16x32_bf16 v[42:45], v[166:169], v[198:201], v[42:45]
	v_mfma_f32_16x16x32_bf16 v[30:33], v[158:161], v[206:209], v[30:33]
	v_mfma_f32_16x16x32_bf16 v[26:29], v[166:169], v[206:209], v[26:29]
	v_mfma_f32_16x16x32_bf16 v[14:17], v[158:161], v[214:217], v[14:17]
	v_mfma_f32_16x16x32_bf16 v[10:13], v[166:169], v[214:217], v[10:13]
	s_setprio 0
	s_setprio 3
	v_mfma_f32_16x16x32_bf16 v[54:57], v[170:173], v[186:189], 0
	v_mfma_f32_16x16x32_bf16 v[50:53], v[178:181], v[186:189], 0
	v_mfma_f32_16x16x32_bf16 v[38:41], v[170:173], v[194:197], 0
	v_mfma_f32_16x16x32_bf16 v[34:37], v[178:181], v[194:197], 0
	v_mfma_f32_16x16x32_bf16 v[22:25], v[170:173], v[202:205], 0
	v_mfma_f32_16x16x32_bf16 v[18:21], v[178:181], v[202:205], 0
	v_mfma_f32_16x16x32_bf16 v[6:9], v[170:173], v[210:213], 0
	v_mfma_f32_16x16x32_bf16 v[2:5], v[178:181], v[210:213], 0
	v_mfma_f32_16x16x32_bf16 v[54:57], v[174:177], v[190:193], v[54:57]
	v_mfma_f32_16x16x32_bf16 v[50:53], v[182:185], v[190:193], v[50:53]
	v_mfma_f32_16x16x32_bf16 v[38:41], v[174:177], v[198:201], v[38:41]
	v_mfma_f32_16x16x32_bf16 v[34:37], v[182:185], v[198:201], v[34:37]
	v_mfma_f32_16x16x32_bf16 v[22:25], v[174:177], v[206:209], v[22:25]
	v_mfma_f32_16x16x32_bf16 v[18:21], v[182:185], v[206:209], v[18:21]
	v_mfma_f32_16x16x32_bf16 v[6:9], v[174:177], v[214:217], v[6:9]
	v_mfma_f32_16x16x32_bf16 v[2:5], v[182:185], v[214:217], v[2:5]
	s_setprio 0
	s_barrier
	s_branch .Lpz1_mid
.LBB0_208:
	ds_read_b128 v[154:157], v150
	ds_read_b128 v[158:161], v150 offset:1024
	ds_read_b128 v[162:165], v150 offset:2048
	ds_read_b128 v[166:169], v150 offset:3072
	ds_read_b128 v[170:173], v151
	ds_read_b128 v[174:177], v151 offset:1024
	ds_read_b128 v[178:181], v151 offset:2048
	ds_read_b128 v[182:185], v151 offset:3072
	s_add_u32 s24, s22, 0xfffc0080
	s_addc_u32 s25, s23, -1
	s_cmp_eq_u32 s54, 12
	s_cselect_b32 s27, s15, s25
	s_cselect_b32 s26, s50, s24
	s_cselect_b32 s25, s13, s53
	s_cselect_b32 s24, s51, s52
	v_lshl_add_u64 v[218:219], s[22:23], 0, v[140:141]
	s_add_i32 m0, s37, 0xc000
	ds_read_b128 v[186:189], v152
	ds_read_b128 v[190:193], v152 offset:1024
	ds_read_b128 v[194:197], v152 offset:2048
	ds_read_b128 v[198:201], v152 offset:3072
	ds_read_b128 v[202:205], v152 offset:4096
	ds_read_b128 v[206:209], v152 offset:5120
	ds_read_b128 v[210:213], v152 offset:6144
	ds_read_b128 v[214:217], v152 offset:7168
	global_load_lds_dwordx4 v[218:219], off
	v_lshl_add_u64 v[218:219], s[22:23], 0, v[142:143]
	s_add_i32 m0, s37, 0xe000
	s_nop 0
	global_load_lds_dwordx4 v[218:219], off
	s_waitcnt vmcnt(8)
	s_waitcnt lgkmcnt(0)
	s_barrier
	s_setprio 3
	s_waitcnt lgkmcnt(0)
	v_mfma_f32_16x16x32_bf16 v[126:129], v[154:157], v[186:189], v[126:129]
	v_mfma_f32_16x16x32_bf16 v[122:125], v[162:165], v[186:189], v[122:125]
	v_mfma_f32_16x16x32_bf16 v[110:113], v[154:157], v[194:197], v[110:113]
	v_mfma_f32_16x16x32_bf16 v[106:109], v[162:165], v[194:197], v[106:109]
	v_mfma_f32_16x16x32_bf16 v[94:97], v[154:157], v[202:205], v[94:97]
	v_mfma_f32_16x16x32_bf16 v[90:93], v[162:165], v[202:205], v[90:93]
	v_mfma_f32_16x16x32_bf16 v[78:81], v[154:157], v[210:213], v[78:81]
	v_mfma_f32_16x16x32_bf16 v[74:77], v[162:165], v[210:213], v[74:77]
	v_mfma_f32_16x16x32_bf16 v[126:129], v[158:161], v[190:193], v[126:129]
	v_mfma_f32_16x16x32_bf16 v[122:125], v[166:169], v[190:193], v[122:125]
	v_mfma_f32_16x16x32_bf16 v[110:113], v[158:161], v[198:201], v[110:113]
	v_mfma_f32_16x16x32_bf16 v[106:109], v[166:169], v[198:201], v[106:109]
	v_mfma_f32_16x16x32_bf16 v[94:97], v[158:161], v[206:209], v[94:97]
	v_mfma_f32_16x16x32_bf16 v[90:93], v[166:169], v[206:209], v[90:93]
	v_mfma_f32_16x16x32_bf16 v[78:81], v[158:161], v[214:217], v[78:81]
	v_mfma_f32_16x16x32_bf16 v[74:77], v[166:169], v[214:217], v[74:77]
	s_setprio 0
	s_setprio 3
	v_mfma_f32_16x16x32_bf16 v[118:121], v[170:173], v[186:189], v[118:121]
	v_mfma_f32_16x16x32_bf16 v[114:117], v[178:181], v[186:189], v[114:117]
	v_mfma_f32_16x16x32_bf16 v[102:105], v[170:173], v[194:197], v[102:105]
	v_mfma_f32_16x16x32_bf16 v[98:101], v[178:181], v[194:197], v[98:101]
	v_mfma_f32_16x16x32_bf16 v[86:89], v[170:173], v[202:205], v[86:89]
	v_mfma_f32_16x16x32_bf16 v[82:85], v[178:181], v[202:205], v[82:85]
	v_mfma_f32_16x16x32_bf16 v[70:73], v[170:173], v[210:213], v[70:73]
	v_mfma_f32_16x16x32_bf16 v[66:69], v[178:181], v[210:213], v[66:69]
	v_mfma_f32_16x16x32_bf16 v[118:121], v[174:177], v[190:193], v[118:121]
	v_mfma_f32_16x16x32_bf16 v[114:117], v[182:185], v[190:193], v[114:117]
	v_mfma_f32_16x16x32_bf16 v[102:105], v[174:177], v[198:201], v[102:105]
	v_mfma_f32_16x16x32_bf16 v[98:101], v[182:185], v[198:201], v[98:101]
	v_mfma_f32_16x16x32_bf16 v[86:89], v[174:177], v[206:209], v[86:89]
	v_mfma_f32_16x16x32_bf16 v[82:85], v[182:185], v[206:209], v[82:85]
	v_mfma_f32_16x16x32_bf16 v[70:73], v[174:177], v[214:217], v[70:73]
	v_mfma_f32_16x16x32_bf16 v[66:69], v[182:185], v[214:217], v[66:69]
	s_setprio 0
	s_barrier
; #define PG8_STAGE(bufoff, gbase, voff) do { _Pragma("unroll") for (int _i = 0; _i < 2; ++_i) \
;         __builtin_amdgcn_global_load_lds((const unsigned*)((const char*)(gbase) + (voff)[_i]), (PG8_LAS unsigned*)(lds + (bufoff) + ldsw + _i * 8192), 16, 0, 0); } while (0)
; #define PG8_LDA(dst, b, h) do { _Pragma("unroll") for (int m = 0; m < 4; ++m) _Pragma("unroll") for (int k = 0; k < 2; ++k) dst[m][k] = *(const PG8_LAS bf16x8*)(lds + PG8_SA(b, h) + aoff + m * 2048 + k * 1024); } while (0)
; #define PG8_LDB(dst, b, h) do { _Pragma("unroll") for (int n = 0; n < 2; ++n) _Pragma("unroll") for (int k = 0; k < 2; ++k) dst[n][k] = *(const PG8_LAS bf16x8*)(lds + PG8_SB(b, h) + boff + n * 2048 + k * 1024); } while (0)
; #define PG8_MMA(ai, bj, At, Bt) do { __builtin_amdgcn_s_setprio(1); _Pragma("unroll") for (int m = 0; m < 4; ++m) _Pragma("unroll") for (int n = 0; n < 2; ++n) _Pragma("unroll") for (int k = 0; k < 2; ++k) \
;         acc[ai][bj][m][n] = __builtin_amdgcn_mfma_f32_16x16x32_bf16(Bt[n][k], At[m][k], acc[ai][bj][m][n], 0, 0, 0); __builtin_amdgcn_s_setprio(0); } while (0)
; #define PG8_WAIT_V(n) asm volatile("s_waitcnt vmcnt(" #n ")" ::: "memory")
; #define PG8_WAIT_L(n) asm volatile("s_waitcnt lgkmcnt(" #n ")" ::: "memory")
; #define PG8_BAR __builtin_amdgcn_s_barrier()
; #define PG8_SCHED __builtin_amdgcn_sched_barrier(0)
; template <class Epi, class Sched, bool ALIGN_EPI = false, bool SP2 = false>
; __device__ __forceinline__ void gemm_phase(PG8_LAS unsigned char* lds, const Gemm g, const Sched& S, const Epi& E) {
;     ...
;             PG8_LDA(At, 0, 1); PG8_STAGE(PG8_SB(0, 0), b2, voffB); PG8_STAGE(PG8_SB(0, 1), b2 + hstep, voffB); PG8_STAGE(PG8_SA(0, 0), a2, voffA);
;             PG8_WAIT_V(8); PG8_WAIT_L(0); PG8_BAR; PG8_MMA(1, 0, At, B0); PG8_MMA(1, 1, At, B1); PG8_BAR; PG8_SCHED;
;             PG8_LDB(B0, 1, 0); PG8_LDB(B1, 1, 1); PG8_SCHED; PG8_LDA(At, 1, 0); PG8_STAGE(PG8_SA(0, 1), a2 + hstep, voffA);
;             PG8_WAIT_V(8); PG8_WAIT_L(0); PG8_BAR; PG8_MMA(0, 0, At, B0); PG8_MMA(0, 1, At, B1); PG8_BAR; PG8_SCHED;
	s_add_i32 s55, s47, s34
	v_lshl_add_u64 v[218:219], s[24:25], 0, v[134:135]
	s_mov_b32 m0, s55
	ds_read_b128 v[186:189], v152 offset:16384
	ds_read_b128 v[190:193], v152 offset:17408
	ds_read_b128 v[194:197], v152 offset:18432
	ds_read_b128 v[198:201], v152 offset:19456
	ds_read_b128 v[202:205], v152 offset:20480
	ds_read_b128 v[206:209], v152 offset:21504
	ds_read_b128 v[210:213], v152 offset:22528
	ds_read_b128 v[214:217], v152 offset:23552
	global_load_lds_dwordx4 v[218:219], off
	s_add_i32 m0, s55, 0x2000
	s_add_u32 s56, s24, 0x40000
	v_lshl_add_u64 v[222:223], s[24:25], 0, v[130:131]
	s_addc_u32 s57, s25, 0
	s_add_i32 s55, s48, s34
	global_load_lds_dwordx4 v[222:223], off
	v_lshl_add_u64 v[224:225], s[56:57], 0, v[134:135]
	s_mov_b32 m0, s55
	v_lshl_add_u64 v[226:227], s[26:27], 0, v[132:133]
	global_load_lds_dwordx4 v[224:225], off
	v_lshl_add_u64 v[224:225], s[56:57], 0, v[130:131]
	s_add_i32 m0, s55, 0x2000
	s_nop 0
	global_load_lds_dwordx4 v[224:225], off
	v_lshl_add_u64 v[224:225], s[26:27], 0, v[136:137]
	s_mov_b32 m0, s37
	s_nop 0
	global_load_lds_dwordx4 v[224:225], off
	s_mov_b32 m0, s38
	s_nop 0
	global_load_lds_dwordx4 v[226:227], off
	s_waitcnt vmcnt(8)
	s_waitcnt lgkmcnt(0)
	s_barrier
	s_setprio 3
	s_waitcnt lgkmcnt(0)
	v_mfma_f32_16x16x32_bf16 v[62:65], v[154:157], v[186:189], v[62:65]
	v_mfma_f32_16x16x32_bf16 v[58:61], v[162:165], v[186:189], v[58:61]
	v_mfma_f32_16x16x32_bf16 v[46:49], v[154:157], v[194:197], v[46:49]
	v_mfma_f32_16x16x32_bf16 v[42:45], v[162:165], v[194:197], v[42:45]
	v_mfma_f32_16x16x32_bf16 v[30:33], v[154:157], v[202:205], v[30:33]
	v_mfma_f32_16x16x32_bf16 v[26:29], v[162:165], v[202:205], v[26:29]
	v_mfma_f32_16x16x32_bf16 v[14:17], v[154:157], v[210:213], v[14:17]
	v_mfma_f32_16x16x32_bf16 v[10:13], v[162:165], v[210:213], v[10:13]
	v_mfma_f32_16x16x32_bf16 v[62:65], v[158:161], v[190:193], v[62:65]
	v_mfma_f32_16x16x32_bf16 v[58:61], v[166:169], v[190:193], v[58:61]
	v_mfma_f32_16x16x32_bf16 v[46:49], v[158:161], v[198:201], v[46:49]
	v_mfma_f32_16x16x32_bf16 v[42:45], v[166:169], v[198:201], v[42:45]
	v_mfma_f32_16x16x32_bf16 v[30:33], v[158:161], v[206:209], v[30:33]
	v_mfma_f32_16x16x32_bf16 v[26:29], v[166:169], v[206:209], v[26:29]
	v_mfma_f32_16x16x32_bf16 v[14:17], v[158:161], v[214:217], v[14:17]
	v_mfma_f32_16x16x32_bf16 v[10:13], v[166:169], v[214:217], v[10:13]
	s_setprio 0
	s_setprio 3
	v_mfma_f32_16x16x32_bf16 v[54:57], v[170:173], v[186:189], v[54:57]
	v_mfma_f32_16x16x32_bf16 v[50:53], v[178:181], v[186:189], v[50:53]
	v_mfma_f32_16x16x32_bf16 v[38:41], v[170:173], v[194:197], v[38:41]
	v_mfma_f32_16x16x32_bf16 v[34:37], v[178:181], v[194:197], v[34:37]
	v_mfma_f32_16x16x32_bf16 v[22:25], v[170:173], v[202:205], v[22:25]
	v_mfma_f32_16x16x32_bf16 v[18:21], v[178:181], v[202:205], v[18:21]
	v_mfma_f32_16x16x32_bf16 v[6:9], v[170:173], v[210:213], v[6:9]
	v_mfma_f32_16x16x32_bf16 v[2:5], v[178:181], v[210:213], v[2:5]
	v_mfma_f32_16x16x32_bf16 v[54:57], v[174:177], v[190:193], v[54:57]
	v_mfma_f32_16x16x32_bf16 v[50:53], v[182:185], v[190:193], v[50:53]
	v_mfma_f32_16x16x32_bf16 v[38:41], v[174:177], v[198:201], v[38:41]
	v_mfma_f32_16x16x32_bf16 v[34:37], v[182:185], v[198:201], v[34:37]
	v_mfma_f32_16x16x32_bf16 v[22:25], v[174:177], v[206:209], v[22:25]
	v_mfma_f32_16x16x32_bf16 v[18:21], v[182:185], v[206:209], v[18:21]
	v_mfma_f32_16x16x32_bf16 v[6:9], v[174:177], v[214:217], v[6:9]
	v_mfma_f32_16x16x32_bf16 v[2:5], v[182:185], v[214:217], v[2:5]
	s_setprio 0
	s_barrier
.Lpz1_mid:
	s_add_i32 s55, 0, 0x18000
	v_add_u32_e32 v138, s55, v149
	s_add_i32 s56, 0, 0x1c000
	ds_read_b128 v[154:157], v138
	ds_read_b128 v[158:161], v138 offset:1024
	ds_read_b128 v[162:165], v138 offset:2048
	ds_read_b128 v[166:169], v138 offset:3072
	v_add_u32_e32 v138, s56, v149
	ds_read_b128 v[170:173], v138
	ds_read_b128 v[174:177], v138 offset:1024
	ds_read_b128 v[178:181], v138 offset:2048
	ds_read_b128 v[182:185], v138 offset:3072
	s_add_u32 s26, s26, 0x40000
	s_addc_u32 s27, s27, 0
	s_mov_b32 m0, s39
	v_lshl_add_u64 v[228:229], s[26:27], 0, v[136:137]
	ds_read_b128 v[186:189], v152 offset:32768
	ds_read_b128 v[190:193], v152 offset:33792
	ds_read_b128 v[194:197], v152 offset:34816
	ds_read_b128 v[198:201], v152 offset:35840
	ds_read_b128 v[202:205], v152 offset:36864
	ds_read_b128 v[206:209], v152 offset:37888
	ds_read_b128 v[210:213], v152 offset:38912
	ds_read_b128 v[214:217], v152 offset:39936
	global_load_lds_dwordx4 v[228:229], off
	v_lshl_add_u64 v[228:229], s[26:27], 0, v[132:133]
	s_mov_b32 m0, s40
	s_nop 0
	global_load_lds_dwordx4 v[228:229], off
	s_waitcnt vmcnt(8)
	s_waitcnt lgkmcnt(0)
	s_barrier
; #define PG8_STAGE(bufoff, gbase, voff) do { _Pragma("unroll") for (int _i = 0; _i < 2; ++_i) \
;         __builtin_amdgcn_global_load_lds((const unsigned*)((const char*)(gbase) + (voff)[_i]), (PG8_LAS unsigned*)(lds + (bufoff) + ldsw + _i * 8192), 16, 0, 0); } while (0)
; #define PG8_LDA(dst, b, h) do { _Pragma("unroll") for (int m = 0; m < 4; ++m) _Pragma("unroll") for (int k = 0; k < 2; ++k) dst[m][k] = *(const PG8_LAS bf16x8*)(lds + PG8_SA(b, h) + aoff + m * 2048 + k * 1024); } while (0)
; #define PG8_MMA(ai, bj, At, Bt) do { __builtin_amdgcn_s_setprio(1); _Pragma("unroll") for (int m = 0; m < 4; ++m) _Pragma("unroll") for (int n = 0; n < 2; ++n) _Pragma("unroll") for (int k = 0; k < 2; ++k) \
;         acc[ai][bj][m][n] = __builtin_amdgcn_mfma_f32_16x16x32_bf16(Bt[n][k], At[m][k], acc[ai][bj][m][n], 0, 0, 0); __builtin_amdgcn_s_setprio(0); } while (0)
; #define PG8_WAIT_V(n) asm volatile("s_waitcnt vmcnt(" #n ")" ::: "memory")
; #define PG8_WAIT_L(n) asm volatile("s_waitcnt lgkmcnt(" #n ")" ::: "memory")
; #define PG8_BAR __builtin_amdgcn_s_barrier()
; #define PG8_SCHED __builtin_amdgcn_sched_barrier(0)
; template <class Epi, class Sched, bool ALIGN_EPI = false, bool SP2 = false>
; __device__ __forceinline__ void gemm_phase(PG8_LAS unsigned char* lds, const Gemm g, const Sched& S, const Epi& E) {
;     ...
;         for (int t = 0; t < nt; t += 2) {
;     ...
;             PG8_WAIT_V(8); PG8_WAIT_L(0); PG8_BAR; PG8_MMA(0, 0, At, B0); PG8_MMA(0, 1, At, B1); PG8_BAR; PG8_SCHED;
;             PG8_LDA(At, 1, 1); PG8_STAGE(PG8_SB(1, 0), b3, voffB); PG8_STAGE(PG8_SB(1, 1), b3 + hstep, voffB); PG8_STAGE(PG8_SA(1, 0), a3, voffA);
;             PG8_WAIT_V(8); PG8_WAIT_L(0); PG8_BAR; PG8_MMA(1, 0, At, B0); PG8_MMA(1, 1, At, B1); PG8_BAR; PG8_SCHED;
	s_setprio 3
	s_waitcnt lgkmcnt(0)
	v_mfma_f32_16x16x32_bf16 v[126:129], v[154:157], v[186:189], v[126:129]
	v_mfma_f32_16x16x32_bf16 v[122:125], v[162:165], v[186:189], v[122:125]
	v_mfma_f32_16x16x32_bf16 v[110:113], v[154:157], v[194:197], v[110:113]
	v_mfma_f32_16x16x32_bf16 v[106:109], v[162:165], v[194:197], v[106:109]
	v_mfma_f32_16x16x32_bf16 v[94:97], v[154:157], v[202:205], v[94:97]
	v_mfma_f32_16x16x32_bf16 v[90:93], v[162:165], v[202:205], v[90:93]
	v_mfma_f32_16x16x32_bf16 v[78:81], v[154:157], v[210:213], v[78:81]
	v_mfma_f32_16x16x32_bf16 v[74:77], v[162:165], v[210:213], v[74:77]
	v_mfma_f32_16x16x32_bf16 v[126:129], v[158:161], v[190:193], v[126:129]
	v_mfma_f32_16x16x32_bf16 v[122:125], v[166:169], v[190:193], v[122:125]
	v_mfma_f32_16x16x32_bf16 v[110:113], v[158:161], v[198:201], v[110:113]
	v_mfma_f32_16x16x32_bf16 v[106:109], v[166:169], v[198:201], v[106:109]
	v_mfma_f32_16x16x32_bf16 v[94:97], v[158:161], v[206:209], v[94:97]
	v_mfma_f32_16x16x32_bf16 v[90:93], v[166:169], v[206:209], v[90:93]
	v_mfma_f32_16x16x32_bf16 v[78:81], v[158:161], v[214:217], v[78:81]
	v_mfma_f32_16x16x32_bf16 v[74:77], v[166:169], v[214:217], v[74:77]
	s_setprio 0
	s_setprio 3
	v_mfma_f32_16x16x32_bf16 v[118:121], v[170:173], v[186:189], v[118:121]
	v_mfma_f32_16x16x32_bf16 v[114:117], v[178:181], v[186:189], v[114:117]
	v_mfma_f32_16x16x32_bf16 v[102:105], v[170:173], v[194:197], v[102:105]
	v_mfma_f32_16x16x32_bf16 v[98:101], v[178:181], v[194:197], v[98:101]
	v_mfma_f32_16x16x32_bf16 v[86:89], v[170:173], v[202:205], v[86:89]
	v_mfma_f32_16x16x32_bf16 v[82:85], v[178:181], v[202:205], v[82:85]
	v_mfma_f32_16x16x32_bf16 v[70:73], v[170:173], v[210:213], v[70:73]
	v_mfma_f32_16x16x32_bf16 v[66:69], v[178:181], v[210:213], v[66:69]
	v_mfma_f32_16x16x32_bf16 v[118:121], v[174:177], v[190:193], v[118:121]
	v_mfma_f32_16x16x32_bf16 v[114:117], v[182:185], v[190:193], v[114:117]
	v_mfma_f32_16x16x32_bf16 v[102:105], v[174:177], v[198:201], v[102:105]
	v_mfma_f32_16x16x32_bf16 v[98:101], v[182:185], v[198:201], v[98:101]
	v_mfma_f32_16x16x32_bf16 v[86:89], v[174:177], v[206:209], v[86:89]
	v_mfma_f32_16x16x32_bf16 v[82:85], v[182:185], v[206:209], v[82:85]
	v_mfma_f32_16x16x32_bf16 v[70:73], v[174:177], v[214:217], v[70:73]
	v_mfma_f32_16x16x32_bf16 v[66:69], v[182:185], v[214:217], v[66:69]
	s_setprio 0
	s_barrier
	s_add_i32 s26, s55, s34
	v_lshl_add_u64 v[218:219], v[218:219], 0, s[8:9]
	s_mov_b32 m0, s26
	ds_read_b128 v[186:189], v152 offset:49152
	ds_read_b128 v[190:193], v152 offset:50176
	ds_read_b128 v[194:197], v152 offset:51200
	ds_read_b128 v[198:201], v152 offset:52224
	ds_read_b128 v[202:205], v152 offset:53248
	ds_read_b128 v[206:209], v152 offset:54272
	ds_read_b128 v[210:213], v152 offset:55296
	ds_read_b128 v[214:217], v152 offset:56320
	global_load_lds_dwordx4 v[218:219], off
	s_add_i32 m0, s26, 0x2000
	s_add_u32 s24, s24, 0x40080
	v_lshl_add_u64 v[218:219], v[222:223], 0, s[8:9]
	s_addc_u32 s25, s25, 0
	s_add_i32 s26, s56, s34
	global_load_lds_dwordx4 v[218:219], off
	v_lshl_add_u64 v[218:219], s[24:25], 0, v[134:135]
	s_mov_b32 m0, s26
	s_nop 0
	global_load_lds_dwordx4 v[218:219], off
	v_lshl_add_u64 v[218:219], s[24:25], 0, v[130:131]
	s_add_i32 m0, s26, 0x2000
	s_nop 0
	global_load_lds_dwordx4 v[218:219], off
	v_lshl_add_u64 v[218:219], v[224:225], 0, s[8:9]
	s_mov_b32 m0, s42
	s_nop 0
	global_load_lds_dwordx4 v[218:219], off
	v_lshl_add_u64 v[218:219], v[226:227], 0, s[8:9]
	s_mov_b32 m0, s43
	s_nop 0
	global_load_lds_dwordx4 v[218:219], off
	s_waitcnt vmcnt(8)
	s_waitcnt lgkmcnt(0)
	s_barrier
	s_setprio 3
	s_waitcnt lgkmcnt(0)
	v_mfma_f32_16x16x32_bf16 v[62:65], v[154:157], v[186:189], v[62:65]
	v_mfma_f32_16x16x32_bf16 v[58:61], v[162:165], v[186:189], v[58:61]
	v_mfma_f32_16x16x32_bf16 v[46:49], v[154:157], v[194:197], v[46:49]
	v_mfma_f32_16x16x32_bf16 v[42:45], v[162:165], v[194:197], v[42:45]
	v_mfma_f32_16x16x32_bf16 v[30:33], v[154:157], v[202:205], v[30:33]
	v_mfma_f32_16x16x32_bf16 v[26:29], v[162:165], v[202:205], v[26:29]
	v_mfma_f32_16x16x32_bf16 v[14:17], v[154:157], v[210:213], v[14:17]
	v_mfma_f32_16x16x32_bf16 v[10:13], v[162:165], v[210:213], v[10:13]
	v_mfma_f32_16x16x32_bf16 v[62:65], v[158:161], v[190:193], v[62:65]
	v_mfma_f32_16x16x32_bf16 v[58:61], v[166:169], v[190:193], v[58:61]
	v_mfma_f32_16x16x32_bf16 v[46:49], v[158:161], v[198:201], v[46:49]
	v_mfma_f32_16x16x32_bf16 v[42:45], v[166:169], v[198:201], v[42:45]
	v_mfma_f32_16x16x32_bf16 v[30:33], v[158:161], v[206:209], v[30:33]
	v_mfma_f32_16x16x32_bf16 v[26:29], v[166:169], v[206:209], v[26:29]
	v_mfma_f32_16x16x32_bf16 v[14:17], v[158:161], v[214:217], v[14:17]
	v_mfma_f32_16x16x32_bf16 v[10:13], v[166:169], v[214:217], v[10:13]
	s_setprio 0
	s_setprio 3
	v_mfma_f32_16x16x32_bf16 v[54:57], v[170:173], v[186:189], v[54:57]
	v_mfma_f32_16x16x32_bf16 v[50:53], v[178:181], v[186:189], v[50:53]
	v_mfma_f32_16x16x32_bf16 v[38:41], v[170:173], v[194:197], v[38:41]
	v_mfma_f32_16x16x32_bf16 v[34:37], v[178:181], v[194:197], v[34:37]
	v_mfma_f32_16x16x32_bf16 v[22:25], v[170:173], v[202:205], v[22:25]
	v_mfma_f32_16x16x32_bf16 v[18:21], v[178:181], v[202:205], v[18:21]
	v_mfma_f32_16x16x32_bf16 v[6:9], v[170:173], v[210:213], v[6:9]
	v_mfma_f32_16x16x32_bf16 v[2:5], v[178:181], v[210:213], v[2:5]
	v_mfma_f32_16x16x32_bf16 v[54:57], v[174:177], v[190:193], v[54:57]
	v_mfma_f32_16x16x32_bf16 v[50:53], v[182:185], v[190:193], v[50:53]
	v_mfma_f32_16x16x32_bf16 v[38:41], v[174:177], v[198:201], v[38:41]
	v_mfma_f32_16x16x32_bf16 v[34:37], v[182:185], v[198:201], v[34:37]
	v_mfma_f32_16x16x32_bf16 v[22:25], v[174:177], v[206:209], v[22:25]
	v_mfma_f32_16x16x32_bf16 v[18:21], v[182:185], v[206:209], v[18:21]
	v_mfma_f32_16x16x32_bf16 v[6:9], v[174:177], v[214:217], v[6:9]
	v_mfma_f32_16x16x32_bf16 v[2:5], v[182:185], v[214:217], v[2:5]
	s_setprio 0
	s_barrier
	s_add_i32 s54, s54, 2
	s_add_u32 s22, s22, 0x100
	s_addc_u32 s23, s23, 0
	s_add_u32 s52, s52, 0x100
	s_addc_u32 s53, s53, 0
	s_cmp_gt_u32 s54, 13
	s_cbranch_scc0 .LBB0_208
	s_and_b64 vcc, exec, s[10:11]
	s_cbranch_vccz .LBB0_211
	s_barrier

; #define PG8_STAGE(bufoff, gbase, voff) do { _Pragma("unroll") for (int _i = 0; _i < 2; ++_i) \
;         __builtin_amdgcn_global_load_lds((const unsigned*)((const char*)(gbase) + (voff)[_i]), (PG8_LAS unsigned*)(lds + (bufoff) + ldsw + _i * 8192), 16, 0, 0); } while (0)
; #define PG8_LDA(dst, b, h) do { _Pragma("unroll") for (int m = 0; m < 4; ++m) _Pragma("unroll") for (int k = 0; k < 2; ++k) dst[m][k] = *(const PG8_LAS bf16x8*)(lds + PG8_SA(b, h) + aoff + m * 2048 + k * 1024); } while (0)
; #define PG8_LDB(dst, b, h) do { _Pragma("unroll") for (int n = 0; n < 2; ++n) _Pragma("unroll") for (int k = 0; k < 2; ++k) dst[n][k] = *(const PG8_LAS bf16x8*)(lds + PG8_SB(b, h) + boff + n * 2048 + k * 1024); } while (0)
; #define PG8_MMA(ai, bj, At, Bt) do { __builtin_amdgcn_s_setprio(1); _Pragma("unroll") for (int m = 0; m < 4; ++m) _Pragma("unroll") for (int n = 0; n < 2; ++n) _Pragma("unroll") for (int k = 0; k < 2; ++k) \
;         acc[ai][bj][m][n] = __builtin_amdgcn_mfma_f32_16x16x32_bf16(Bt[n][k], At[m][k], acc[ai][bj][m][n], 0, 0, 0); __builtin_amdgcn_s_setprio(0); } while (0)
; #define PG8_WAIT_V(n) asm volatile("s_waitcnt vmcnt(" #n ")" ::: "memory")
; #define PG8_WAIT_L(n) asm volatile("s_waitcnt lgkmcnt(" #n ")" ::: "memory")
; #define PG8_BAR __builtin_amdgcn_s_barrier()
; #define PG8_SCHED __builtin_amdgcn_sched_barrier(0)
;     __device__ __forceinline__ void prefetch(const Unit& u, int wid, int lane) const { epi_prefetch(scr, ssq, bias + (size_t)(u.pm >> 5) * NGU + u.pn * BM, u, wid, lane); }
; template <class Epi, class Sched, bool ALIGN_EPI = false, bool SP2 = false>
; __device__ __forceinline__ void gemm_phase(PG8_LAS unsigned char* lds, const Gemm g, const Sched& S, const Epi& E) {
;     ...
;             PG8_LDB(B0, 0, 0); PG8_LDB(B1, 0, 1); PG8_SCHED; PG8_LDA(At, 0, 0); PG8_STAGE(PG8_SA(1, 1), a1 + hstep, voffA);
;             PG8_WAIT_V(8); PG8_WAIT_L(0); PG8_BAR; PG8_MMA(0, 0, At, B0); PG8_MMA(0, 1, At, B1); PG8_BAR; PG8_SCHED;
;             if constexpr (Epi::PREFETCH) { if (t == tpf) E.prefetch(cur, wid, lane); }
;             PG8_LDA(At, 0, 1); PG8_STAGE(PG8_SB(0, 0), b2, voffB); PG8_STAGE(PG8_SB(0, 1), b2 + hstep, voffB); PG8_STAGE(PG8_SA(0, 0), a2, voffA);
;             PG8_WAIT_V(8); PG8_WAIT_L(0); PG8_BAR; PG8_MMA(1, 0, At, B0); PG8_MMA(1, 1, At, B1); PG8_BAR; PG8_SCHED;
.LBB0_288:
	s_add_u32 s39, s6, 0x100
	s_addc_u32 s40, s7, 0
	s_mov_b32 s41, -2
	ds_read_b128 v[130:133], v223
	ds_read_b128 v[134:137], v223 offset:1024
	ds_read_b128 v[138:141], v223 offset:2048
	ds_read_b128 v[142:145], v223 offset:3072
	ds_read_b128 v[164:167], v224
	ds_read_b128 v[168:171], v224 offset:1024
	ds_read_b128 v[172:175], v224 offset:2048
	ds_read_b128 v[176:179], v224 offset:3072
	s_add_u32 s0, s4, 0x200
	s_addc_u32 s1, s5, 0
	s_cmp_eq_u32 s41, 40
	s_cselect_b32 s37, s31, s1
	s_cselect_b32 s36, s30, s0
	s_cselect_b32 s7, s35, s40
	s_cselect_b32 s6, s34, s39
	v_lshl_add_u64 v[160:161], s[4:5], 0, v[156:157]
	s_add_i32 m0, s51, 0xc000
	ds_read_b128 v[180:183], v225
	ds_read_b128 v[184:187], v225 offset:1024
	ds_read_b128 v[188:191], v225 offset:2048
	ds_read_b128 v[192:195], v225 offset:3072
	ds_read_b128 v[196:199], v225 offset:4096
	ds_read_b128 v[200:203], v225 offset:5120
	ds_read_b128 v[204:207], v225 offset:6144
	ds_read_b128 v[208:211], v225 offset:7168
	global_load_lds_dwordx4 v[160:161], off
	v_lshl_add_u64 v[160:161], s[4:5], 0, v[158:159]
	s_add_i32 m0, s51, 0xe000
	s_nop 0
	global_load_lds_dwordx4 v[160:161], off
	s_waitcnt vmcnt(8)
	s_waitcnt lgkmcnt(0)
	s_barrier
	s_setprio 3
	s_waitcnt lgkmcnt(0)
	v_mfma_f32_16x16x32_bf16 v[126:129], v[130:133], v[180:183], 0
	v_mfma_f32_16x16x32_bf16 v[122:125], v[138:141], v[180:183], 0
	v_mfma_f32_16x16x32_bf16 v[110:113], v[130:133], v[188:191], 0
	v_mfma_f32_16x16x32_bf16 v[106:109], v[138:141], v[188:191], 0
	v_mfma_f32_16x16x32_bf16 v[94:97], v[130:133], v[196:199], 0
	v_mfma_f32_16x16x32_bf16 v[90:93], v[138:141], v[196:199], 0
	v_mfma_f32_16x16x32_bf16 v[78:81], v[130:133], v[204:207], 0
	v_mfma_f32_16x16x32_bf16 v[74:77], v[138:141], v[204:207], 0
	v_mfma_f32_16x16x32_bf16 v[126:129], v[134:137], v[184:187], v[126:129]
	v_mfma_f32_16x16x32_bf16 v[122:125], v[142:145], v[184:187], v[122:125]
	v_mfma_f32_16x16x32_bf16 v[110:113], v[134:137], v[192:195], v[110:113]
	v_mfma_f32_16x16x32_bf16 v[106:109], v[142:145], v[192:195], v[106:109]
	v_mfma_f32_16x16x32_bf16 v[94:97], v[134:137], v[200:203], v[94:97]
	v_mfma_f32_16x16x32_bf16 v[90:93], v[142:145], v[200:203], v[90:93]
	v_mfma_f32_16x16x32_bf16 v[78:81], v[134:137], v[208:211], v[78:81]
	v_mfma_f32_16x16x32_bf16 v[74:77], v[142:145], v[208:211], v[74:77]
	s_setprio 0
	s_setprio 3
	v_mfma_f32_16x16x32_bf16 v[118:121], v[164:167], v[180:183], 0
	v_mfma_f32_16x16x32_bf16 v[114:117], v[172:175], v[180:183], 0
	v_mfma_f32_16x16x32_bf16 v[102:105], v[164:167], v[188:191], 0
	v_mfma_f32_16x16x32_bf16 v[98:101], v[172:175], v[188:191], 0
	v_mfma_f32_16x16x32_bf16 v[86:89], v[164:167], v[196:199], 0
	v_mfma_f32_16x16x32_bf16 v[82:85], v[172:175], v[196:199], 0
	v_mfma_f32_16x16x32_bf16 v[70:73], v[164:167], v[204:207], 0
	v_mfma_f32_16x16x32_bf16 v[66:69], v[172:175], v[204:207], 0
	v_mfma_f32_16x16x32_bf16 v[118:121], v[168:171], v[184:187], v[118:121]
	v_mfma_f32_16x16x32_bf16 v[114:117], v[176:179], v[184:187], v[114:117]
	v_mfma_f32_16x16x32_bf16 v[102:105], v[168:171], v[192:195], v[102:105]
	v_mfma_f32_16x16x32_bf16 v[98:101], v[176:179], v[192:195], v[98:101]
	v_mfma_f32_16x16x32_bf16 v[86:89], v[168:171], v[200:203], v[86:89]
	v_mfma_f32_16x16x32_bf16 v[82:85], v[176:179], v[200:203], v[82:85]
	v_mfma_f32_16x16x32_bf16 v[70:73], v[168:171], v[208:211], v[70:73]
	v_mfma_f32_16x16x32_bf16 v[66:69], v[176:179], v[208:211], v[66:69]
	s_setprio 0
	s_barrier
	s_add_i32 s4, s68, s50
	v_lshl_add_u64 v[160:161], s[6:7], 0, v[148:149]
	s_mov_b32 m0, s4
	ds_read_b128 v[180:183], v225 offset:16384
	ds_read_b128 v[184:187], v225 offset:17408
	ds_read_b128 v[188:191], v225 offset:18432
	ds_read_b128 v[192:195], v225 offset:19456
	ds_read_b128 v[196:199], v225 offset:20480
	ds_read_b128 v[200:203], v225 offset:21504
	ds_read_b128 v[204:207], v225 offset:22528
	ds_read_b128 v[208:211], v225 offset:23552
	global_load_lds_dwordx4 v[160:161], off
	s_add_i32 m0, s4, 0x2000
	s_add_u32 s4, s6, 0xb0000
	v_lshl_add_u64 v[162:163], s[6:7], 0, v[152:153]
	s_addc_u32 s5, s7, 0
	s_add_i32 s42, s69, s50
	global_load_lds_dwordx4 v[162:163], off
	v_lshl_add_u64 v[212:213], s[4:5], 0, v[148:149]
	s_mov_b32 m0, s42
	v_lshl_add_u64 v[214:215], s[36:37], 0, v[150:151]
	global_load_lds_dwordx4 v[212:213], off
	v_lshl_add_u64 v[212:213], s[4:5], 0, v[152:153]
	s_add_i32 m0, s42, 0x2000
	s_nop 0
	global_load_lds_dwordx4 v[212:213], off
	v_lshl_add_u64 v[212:213], s[36:37], 0, v[146:147]
	s_mov_b32 m0, s51
	s_nop 0
	global_load_lds_dwordx4 v[212:213], off
	s_mov_b32 m0, s52
	s_nop 0
	global_load_lds_dwordx4 v[214:215], off
	s_waitcnt vmcnt(8)
	s_waitcnt lgkmcnt(0)
	s_barrier
	s_setprio 3
	s_waitcnt lgkmcnt(0)
	v_mfma_f32_16x16x32_bf16 v[62:65], v[130:133], v[180:183], 0
	v_mfma_f32_16x16x32_bf16 v[58:61], v[138:141], v[180:183], 0
	v_mfma_f32_16x16x32_bf16 v[46:49], v[130:133], v[188:191], 0
	v_mfma_f32_16x16x32_bf16 v[42:45], v[138:141], v[188:191], 0
	v_mfma_f32_16x16x32_bf16 v[30:33], v[130:133], v[196:199], 0
	v_mfma_f32_16x16x32_bf16 v[26:29], v[138:141], v[196:199], 0
	v_mfma_f32_16x16x32_bf16 v[14:17], v[130:133], v[204:207], 0
	v_mfma_f32_16x16x32_bf16 v[10:13], v[138:141], v[204:207], 0
	v_mfma_f32_16x16x32_bf16 v[62:65], v[134:137], v[184:187], v[62:65]
	v_mfma_f32_16x16x32_bf16 v[58:61], v[142:145], v[184:187], v[58:61]
	v_mfma_f32_16x16x32_bf16 v[46:49], v[134:137], v[192:195], v[46:49]
	v_mfma_f32_16x16x32_bf16 v[42:45], v[142:145], v[192:195], v[42:45]
	v_mfma_f32_16x16x32_bf16 v[30:33], v[134:137], v[200:203], v[30:33]
	v_mfma_f32_16x16x32_bf16 v[26:29], v[142:145], v[200:203], v[26:29]
	v_mfma_f32_16x16x32_bf16 v[14:17], v[134:137], v[208:211], v[14:17]
	v_mfma_f32_16x16x32_bf16 v[10:13], v[142:145], v[208:211], v[10:13]
	s_setprio 0
	s_setprio 3
	v_mfma_f32_16x16x32_bf16 v[54:57], v[164:167], v[180:183], 0
	v_mfma_f32_16x16x32_bf16 v[50:53], v[172:175], v[180:183], 0
	v_mfma_f32_16x16x32_bf16 v[38:41], v[164:167], v[188:191], 0
	v_mfma_f32_16x16x32_bf16 v[34:37], v[172:175], v[188:191], 0
	v_mfma_f32_16x16x32_bf16 v[22:25], v[164:167], v[196:199], 0
	v_mfma_f32_16x16x32_bf16 v[18:21], v[172:175], v[196:199], 0
	v_mfma_f32_16x16x32_bf16 v[6:9], v[164:167], v[204:207], 0
	v_mfma_f32_16x16x32_bf16 v[2:5], v[172:175], v[204:207], 0
	v_mfma_f32_16x16x32_bf16 v[54:57], v[168:171], v[184:187], v[54:57]
	v_mfma_f32_16x16x32_bf16 v[50:53], v[176:179], v[184:187], v[50:53]
	v_mfma_f32_16x16x32_bf16 v[38:41], v[168:171], v[192:195], v[38:41]
	v_mfma_f32_16x16x32_bf16 v[34:37], v[176:179], v[192:195], v[34:37]
	v_mfma_f32_16x16x32_bf16 v[22:25], v[168:171], v[200:203], v[22:25]
	v_mfma_f32_16x16x32_bf16 v[18:21], v[176:179], v[200:203], v[18:21]
	v_mfma_f32_16x16x32_bf16 v[6:9], v[168:171], v[208:211], v[6:9]
	v_mfma_f32_16x16x32_bf16 v[2:5], v[176:179], v[208:211], v[2:5]
	s_setprio 0
	s_barrier
	s_branch .Lpz2_mid
; #define PG8_STAGE(bufoff, gbase, voff) do { _Pragma("unroll") for (int _i = 0; _i < 2; ++_i) \
;         __builtin_amdgcn_global_load_lds((const unsigned*)((const char*)(gbase) + (voff)[_i]), (PG8_LAS unsigned*)(lds + (bufoff) + ldsw + _i * 8192), 16, 0, 0); } while (0)
; #define PG8_LDA(dst, b, h) do { _Pragma("unroll") for (int m = 0; m < 4; ++m) _Pragma("unroll") for (int k = 0; k < 2; ++k) dst[m][k] = *(const PG8_LAS bf16x8*)(lds + PG8_SA(b, h) + aoff + m * 2048 + k * 1024); } while (0)
; #define PG8_LDB(dst, b, h) do { _Pragma("unroll") for (int n = 0; n < 2; ++n) _Pragma("unroll") for (int k = 0; k < 2; ++k) dst[n][k] = *(const PG8_LAS bf16x8*)(lds + PG8_SB(b, h) + boff + n * 2048 + k * 1024); } while (0)
; #define PG8_MMA(ai, bj, At, Bt) do { __builtin_amdgcn_s_setprio(1); _Pragma("unroll") for (int m = 0; m < 4; ++m) _Pragma("unroll") for (int n = 0; n < 2; ++n) _Pragma("unroll") for (int k = 0; k < 2; ++k) \
;         acc[ai][bj][m][n] = __builtin_amdgcn_mfma_f32_16x16x32_bf16(Bt[n][k], At[m][k], acc[ai][bj][m][n], 0, 0, 0); __builtin_amdgcn_s_setprio(0); } while (0)
; #define PG8_WAIT_V(n) asm volatile("s_waitcnt vmcnt(" #n ")" ::: "memory")
; #define PG8_WAIT_L(n) asm volatile("s_waitcnt lgkmcnt(" #n ")" ::: "memory")
; #define PG8_BAR __builtin_amdgcn_s_barrier()
; #define PG8_SCHED __builtin_amdgcn_sched_barrier(0)
; template <class Epi, class Sched, bool ALIGN_EPI = false, bool SP2 = false>
; __device__ __forceinline__ void gemm_phase(PG8_LAS unsigned char* lds, const Gemm g, const Sched& S, const Epi& E) {
;     ...
;             PG8_LDB(B0, 0, 0); PG8_LDB(B1, 0, 1); PG8_SCHED; PG8_LDA(At, 0, 0); PG8_STAGE(PG8_SA(1, 1), a1 + hstep, voffA);
;             PG8_WAIT_V(8); PG8_WAIT_L(0); PG8_BAR; PG8_MMA(0, 0, At, B0); PG8_MMA(0, 1, At, B1); PG8_BAR; PG8_SCHED;
;             if constexpr (Epi::PREFETCH) { if (t == tpf) E.prefetch(cur, wid, lane); }
;             PG8_LDA(At, 0, 1); PG8_STAGE(PG8_SB(0, 0), b2, voffB); PG8_STAGE(PG8_SB(0, 1), b2 + hstep, voffB); PG8_STAGE(PG8_SA(0, 0), a2, voffA);
;             PG8_WAIT_V(8); PG8_WAIT_L(0); PG8_BAR; PG8_MMA(1, 0, At, B0); PG8_MMA(1, 1, At, B1); PG8_BAR; PG8_SCHED;
;             PG8_LDB(B0, 1, 0); PG8_LDB(B1, 1, 1); PG8_SCHED; PG8_LDA(At, 1, 0); PG8_STAGE(PG8_SA(0, 1), a2 + hstep, voffA);
;             PG8_WAIT_V(8); PG8_WAIT_L(0); PG8_BAR; PG8_MMA(0, 0, At, B0); PG8_MMA(0, 1, At, B1); PG8_BAR; PG8_SCHED;
.LBB0_289:
	ds_read_b128 v[130:133], v223
	ds_read_b128 v[134:137], v223 offset:1024
	ds_read_b128 v[138:141], v223 offset:2048
	ds_read_b128 v[142:145], v223 offset:3072
	ds_read_b128 v[164:167], v224
	ds_read_b128 v[168:171], v224 offset:1024
	ds_read_b128 v[172:175], v224 offset:2048
	ds_read_b128 v[176:179], v224 offset:3072
	s_add_u32 s0, s4, 0x200
	s_addc_u32 s1, s5, 0
	s_cmp_eq_u32 s41, 40
	s_cselect_b32 s37, s31, s1
	s_cselect_b32 s36, s30, s0
	s_cselect_b32 s7, s35, s40
	s_cselect_b32 s6, s34, s39
	v_lshl_add_u64 v[160:161], s[4:5], 0, v[156:157]
	s_add_i32 m0, s51, 0xc000
	ds_read_b128 v[180:183], v225
	ds_read_b128 v[184:187], v225 offset:1024
	ds_read_b128 v[188:191], v225 offset:2048
	ds_read_b128 v[192:195], v225 offset:3072
	ds_read_b128 v[196:199], v225 offset:4096
	ds_read_b128 v[200:203], v225 offset:5120
	ds_read_b128 v[204:207], v225 offset:6144
	ds_read_b128 v[208:211], v225 offset:7168
	global_load_lds_dwordx4 v[160:161], off
	v_lshl_add_u64 v[160:161], s[4:5], 0, v[158:159]
	s_add_i32 m0, s51, 0xe000
	s_nop 0
	global_load_lds_dwordx4 v[160:161], off
	s_waitcnt vmcnt(8)
	s_waitcnt lgkmcnt(0)
	s_barrier
	s_setprio 3
	s_waitcnt lgkmcnt(0)
	v_mfma_f32_16x16x32_bf16 v[126:129], v[130:133], v[180:183], v[126:129]
	v_mfma_f32_16x16x32_bf16 v[122:125], v[138:141], v[180:183], v[122:125]
	v_mfma_f32_16x16x32_bf16 v[110:113], v[130:133], v[188:191], v[110:113]
	v_mfma_f32_16x16x32_bf16 v[106:109], v[138:141], v[188:191], v[106:109]
	v_mfma_f32_16x16x32_bf16 v[94:97], v[130:133], v[196:199], v[94:97]
	v_mfma_f32_16x16x32_bf16 v[90:93], v[138:141], v[196:199], v[90:93]
	v_mfma_f32_16x16x32_bf16 v[78:81], v[130:133], v[204:207], v[78:81]
	v_mfma_f32_16x16x32_bf16 v[74:77], v[138:141], v[204:207], v[74:77]
	v_mfma_f32_16x16x32_bf16 v[126:129], v[134:137], v[184:187], v[126:129]
	v_mfma_f32_16x16x32_bf16 v[122:125], v[142:145], v[184:187], v[122:125]
	v_mfma_f32_16x16x32_bf16 v[110:113], v[134:137], v[192:195], v[110:113]
	v_mfma_f32_16x16x32_bf16 v[106:109], v[142:145], v[192:195], v[106:109]
	v_mfma_f32_16x16x32_bf16 v[94:97], v[134:137], v[200:203], v[94:97]
	v_mfma_f32_16x16x32_bf16 v[90:93], v[142:145], v[200:203], v[90:93]
	v_mfma_f32_16x16x32_bf16 v[78:81], v[134:137], v[208:211], v[78:81]
	v_mfma_f32_16x16x32_bf16 v[74:77], v[142:145], v[208:211], v[74:77]
	s_setprio 0
	s_setprio 3
	v_mfma_f32_16x16x32_bf16 v[118:121], v[164:167], v[180:183], v[118:121]
	v_mfma_f32_16x16x32_bf16 v[114:117], v[172:175], v[180:183], v[114:117]
	v_mfma_f32_16x16x32_bf16 v[102:105], v[164:167], v[188:191], v[102:105]
	v_mfma_f32_16x16x32_bf16 v[98:101], v[172:175], v[188:191], v[98:101]
	v_mfma_f32_16x16x32_bf16 v[86:89], v[164:167], v[196:199], v[86:89]
	v_mfma_f32_16x16x32_bf16 v[82:85], v[172:175], v[196:199], v[82:85]
	v_mfma_f32_16x16x32_bf16 v[70:73], v[164:167], v[204:207], v[70:73]
	v_mfma_f32_16x16x32_bf16 v[66:69], v[172:175], v[204:207], v[66:69]
	v_mfma_f32_16x16x32_bf16 v[118:121], v[168:171], v[184:187], v[118:121]
	v_mfma_f32_16x16x32_bf16 v[114:117], v[176:179], v[184:187], v[114:117]
	v_mfma_f32_16x16x32_bf16 v[102:105], v[168:171], v[192:195], v[102:105]
	v_mfma_f32_16x16x32_bf16 v[98:101], v[176:179], v[192:195], v[98:101]
	v_mfma_f32_16x16x32_bf16 v[86:89], v[168:171], v[200:203], v[86:89]
	v_mfma_f32_16x16x32_bf16 v[82:85], v[176:179], v[200:203], v[82:85]
	v_mfma_f32_16x16x32_bf16 v[70:73], v[168:171], v[208:211], v[70:73]
	v_mfma_f32_16x16x32_bf16 v[66:69], v[176:179], v[208:211], v[66:69]
	s_setprio 0
	s_barrier
	s_add_i32 s4, s68, s50
	v_lshl_add_u64 v[160:161], s[6:7], 0, v[148:149]
	s_mov_b32 m0, s4
	ds_read_b128 v[180:183], v225 offset:16384
	ds_read_b128 v[184:187], v225 offset:17408
	ds_read_b128 v[188:191], v225 offset:18432
	ds_read_b128 v[192:195], v225 offset:19456
	ds_read_b128 v[196:199], v225 offset:20480
	ds_read_b128 v[200:203], v225 offset:21504
	ds_read_b128 v[204:207], v225 offset:22528
	ds_read_b128 v[208:211], v225 offset:23552
	global_load_lds_dwordx4 v[160:161], off
	s_add_i32 m0, s4, 0x2000
	s_add_u32 s4, s6, 0xb0000
	v_lshl_add_u64 v[162:163], s[6:7], 0, v[152:153]
	s_addc_u32 s5, s7, 0
	s_add_i32 s42, s69, s50
	global_load_lds_dwordx4 v[162:163], off
	v_lshl_add_u64 v[212:213], s[4:5], 0, v[148:149]
	s_mov_b32 m0, s42
	v_lshl_add_u64 v[214:215], s[36:37], 0, v[150:151]
	global_load_lds_dwordx4 v[212:213], off
	v_lshl_add_u64 v[212:213], s[4:5], 0, v[152:153]
	s_add_i32 m0, s42, 0x2000
	s_nop 0
	global_load_lds_dwordx4 v[212:213], off
	v_lshl_add_u64 v[212:213], s[36:37], 0, v[146:147]
	s_mov_b32 m0, s51
	s_nop 0
	global_load_lds_dwordx4 v[212:213], off
	s_mov_b32 m0, s52
	s_nop 0
	global_load_lds_dwordx4 v[214:215], off
	s_waitcnt vmcnt(8)
	s_waitcnt lgkmcnt(0)
	s_barrier
	s_setprio 3
	s_waitcnt lgkmcnt(0)
	v_mfma_f32_16x16x32_bf16 v[62:65], v[130:133], v[180:183], v[62:65]
	v_mfma_f32_16x16x32_bf16 v[58:61], v[138:141], v[180:183], v[58:61]
	v_mfma_f32_16x16x32_bf16 v[46:49], v[130:133], v[188:191], v[46:49]
	v_mfma_f32_16x16x32_bf16 v[42:45], v[138:141], v[188:191], v[42:45]
	v_mfma_f32_16x16x32_bf16 v[30:33], v[130:133], v[196:199], v[30:33]
	v_mfma_f32_16x16x32_bf16 v[26:29], v[138:141], v[196:199], v[26:29]
	v_mfma_f32_16x16x32_bf16 v[14:17], v[130:133], v[204:207], v[14:17]
	v_mfma_f32_16x16x32_bf16 v[10:13], v[138:141], v[204:207], v[10:13]
	v_mfma_f32_16x16x32_bf16 v[62:65], v[134:137], v[184:187], v[62:65]
	v_mfma_f32_16x16x32_bf16 v[58:61], v[142:145], v[184:187], v[58:61]
	v_mfma_f32_16x16x32_bf16 v[46:49], v[134:137], v[192:195], v[46:49]
	v_mfma_f32_16x16x32_bf16 v[42:45], v[142:145], v[192:195], v[42:45]
	v_mfma_f32_16x16x32_bf16 v[30:33], v[134:137], v[200:203], v[30:33]
	v_mfma_f32_16x16x32_bf16 v[26:29], v[142:145], v[200:203], v[26:29]
	v_mfma_f32_16x16x32_bf16 v[14:17], v[134:137], v[208:211], v[14:17]
	v_mfma_f32_16x16x32_bf16 v[10:13], v[142:145], v[208:211], v[10:13]
	s_setprio 0
	s_setprio 3
	v_mfma_f32_16x16x32_bf16 v[54:57], v[164:167], v[180:183], v[54:57]
	v_mfma_f32_16x16x32_bf16 v[50:53], v[172:175], v[180:183], v[50:53]
	v_mfma_f32_16x16x32_bf16 v[38:41], v[164:167], v[188:191], v[38:41]
	v_mfma_f32_16x16x32_bf16 v[34:37], v[172:175], v[188:191], v[34:37]
	v_mfma_f32_16x16x32_bf16 v[22:25], v[164:167], v[196:199], v[22:25]
	v_mfma_f32_16x16x32_bf16 v[18:21], v[172:175], v[196:199], v[18:21]
	v_mfma_f32_16x16x32_bf16 v[6:9], v[164:167], v[204:207], v[6:9]
	v_mfma_f32_16x16x32_bf16 v[2:5], v[172:175], v[204:207], v[2:5]
	v_mfma_f32_16x16x32_bf16 v[54:57], v[168:171], v[184:187], v[54:57]
	v_mfma_f32_16x16x32_bf16 v[50:53], v[176:179], v[184:187], v[50:53]
	v_mfma_f32_16x16x32_bf16 v[38:41], v[168:171], v[192:195], v[38:41]
	v_mfma_f32_16x16x32_bf16 v[34:37], v[176:179], v[192:195], v[34:37]
	v_mfma_f32_16x16x32_bf16 v[22:25], v[168:171], v[200:203], v[22:25]
	v_mfma_f32_16x16x32_bf16 v[18:21], v[176:179], v[200:203], v[18:21]
	v_mfma_f32_16x16x32_bf16 v[6:9], v[168:171], v[208:211], v[6:9]
	v_mfma_f32_16x16x32_bf16 v[2:5], v[176:179], v[208:211], v[2:5]
	s_setprio 0
	s_barrier
; #define PG8_STAGE(bufoff, gbase, voff) do { _Pragma("unroll") for (int _i = 0; _i < 2; ++_i) \
;         __builtin_amdgcn_global_load_lds((const unsigned*)((const char*)(gbase) + (voff)[_i]), (PG8_LAS unsigned*)(lds + (bufoff) + ldsw + _i * 8192), 16, 0, 0); } while (0)
; #define PG8_LDA(dst, b, h) do { _Pragma("unroll") for (int m = 0; m < 4; ++m) _Pragma("unroll") for (int k = 0; k < 2; ++k) dst[m][k] = *(const PG8_LAS bf16x8*)(lds + PG8_SA(b, h) + aoff + m * 2048 + k * 1024); } while (0)
; #define PG8_LDB(dst, b, h) do { _Pragma("unroll") for (int n = 0; n < 2; ++n) _Pragma("unroll") for (int k = 0; k < 2; ++k) dst[n][k] = *(const PG8_LAS bf16x8*)(lds + PG8_SB(b, h) + boff + n * 2048 + k * 1024); } while (0)
; #define PG8_MMA(ai, bj, At, Bt) do { __builtin_amdgcn_s_setprio(1); _Pragma("unroll") for (int m = 0; m < 4; ++m) _Pragma("unroll") for (int n = 0; n < 2; ++n) _Pragma("unroll") for (int k = 0; k < 2; ++k) \
;         acc[ai][bj][m][n] = __builtin_amdgcn_mfma_f32_16x16x32_bf16(Bt[n][k], At[m][k], acc[ai][bj][m][n], 0, 0, 0); __builtin_amdgcn_s_setprio(0); } while (0)
; #define PG8_WAIT_V(n) asm volatile("s_waitcnt vmcnt(" #n ")" ::: "memory")
; #define PG8_WAIT_L(n) asm volatile("s_waitcnt lgkmcnt(" #n ")" ::: "memory")
; #define PG8_BAR __builtin_amdgcn_s_barrier()
; #define PG8_SCHED __builtin_amdgcn_sched_barrier(0)
; template <class Epi, class Sched, bool ALIGN_EPI = false, bool SP2 = false>
; __device__ __forceinline__ void gemm_phase(PG8_LAS unsigned char* lds, const Gemm g, const Sched& S, const Epi& E) {
;     ...
;             PG8_LDB(B0, 1, 0); PG8_LDB(B1, 1, 1); PG8_SCHED; PG8_LDA(At, 1, 0); PG8_STAGE(PG8_SA(0, 1), a2 + hstep, voffA);
;             PG8_WAIT_V(8); PG8_WAIT_L(0); PG8_BAR; PG8_MMA(0, 0, At, B0); PG8_MMA(0, 1, At, B1); PG8_BAR; PG8_SCHED;
.Lpz2_mid:
	s_add_i32 s42, 0, 0x18000
	s_add_i32 s43, 0, 0x1c000
	v_add_u32_e32 v142, s42, v222
	v_add_u32_e32 v154, s43, v222
	ds_read_b128 v[130:133], v142
	ds_read_b128 v[134:137], v142 offset:1024
	ds_read_b128 v[138:141], v142 offset:2048
	ds_read_b128 v[142:145], v142 offset:3072
	ds_read_b128 v[164:167], v154
	ds_read_b128 v[168:171], v154 offset:1024
	ds_read_b128 v[172:175], v154 offset:2048
	ds_read_b128 v[176:179], v154 offset:3072
	s_add_u32 s4, s36, 0xb0000
	s_addc_u32 s5, s37, 0
	s_mov_b32 m0, s53
	v_lshl_add_u64 v[216:217], s[4:5], 0, v[146:147]
	ds_read_b128 v[180:183], v225 offset:32768
	ds_read_b128 v[184:187], v225 offset:33792
	ds_read_b128 v[188:191], v225 offset:34816
	ds_read_b128 v[192:195], v225 offset:35840
	ds_read_b128 v[196:199], v225 offset:36864
	ds_read_b128 v[200:203], v225 offset:37888
	ds_read_b128 v[204:207], v225 offset:38912
	ds_read_b128 v[208:211], v225 offset:39936
	global_load_lds_dwordx4 v[216:217], off
	v_lshl_add_u64 v[216:217], s[4:5], 0, v[150:151]
	s_mov_b32 m0, s54
	s_nop 0
	global_load_lds_dwordx4 v[216:217], off
	s_waitcnt vmcnt(8)
	s_waitcnt lgkmcnt(0)
	s_barrier
	s_setprio 3
	s_waitcnt lgkmcnt(0)
	v_mfma_f32_16x16x32_bf16 v[126:129], v[130:133], v[180:183], v[126:129]
	v_mfma_f32_16x16x32_bf16 v[122:125], v[138:141], v[180:183], v[122:125]
	v_mfma_f32_16x16x32_bf16 v[110:113], v[130:133], v[188:191], v[110:113]
	v_mfma_f32_16x16x32_bf16 v[106:109], v[138:141], v[188:191], v[106:109]
	v_mfma_f32_16x16x32_bf16 v[94:97], v[130:133], v[196:199], v[94:97]
	v_mfma_f32_16x16x32_bf16 v[90:93], v[138:141], v[196:199], v[90:93]
	v_mfma_f32_16x16x32_bf16 v[78:81], v[130:133], v[204:207], v[78:81]
	v_mfma_f32_16x16x32_bf16 v[74:77], v[138:141], v[204:207], v[74:77]
	v_mfma_f32_16x16x32_bf16 v[126:129], v[134:137], v[184:187], v[126:129]
	v_mfma_f32_16x16x32_bf16 v[122:125], v[142:145], v[184:187], v[122:125]
	v_mfma_f32_16x16x32_bf16 v[110:113], v[134:137], v[192:195], v[110:113]
	v_mfma_f32_16x16x32_bf16 v[106:109], v[142:145], v[192:195], v[106:109]
	v_mfma_f32_16x16x32_bf16 v[94:97], v[134:137], v[200:203], v[94:97]
	v_mfma_f32_16x16x32_bf16 v[90:93], v[142:145], v[200:203], v[90:93]
	v_mfma_f32_16x16x32_bf16 v[78:81], v[134:137], v[208:211], v[78:81]
	v_mfma_f32_16x16x32_bf16 v[74:77], v[142:145], v[208:211], v[74:77]
	s_setprio 0
	s_setprio 3
	v_mfma_f32_16x16x32_bf16 v[118:121], v[164:167], v[180:183], v[118:121]
	v_mfma_f32_16x16x32_bf16 v[114:117], v[172:175], v[180:183], v[114:117]
	v_mfma_f32_16x16x32_bf16 v[102:105], v[164:167], v[188:191], v[102:105]
	v_mfma_f32_16x16x32_bf16 v[98:101], v[172:175], v[188:191], v[98:101]
	v_mfma_f32_16x16x32_bf16 v[86:89], v[164:167], v[196:199], v[86:89]
	v_mfma_f32_16x16x32_bf16 v[82:85], v[172:175], v[196:199], v[82:85]
	v_mfma_f32_16x16x32_bf16 v[70:73], v[164:167], v[204:207], v[70:73]
	v_mfma_f32_16x16x32_bf16 v[66:69], v[172:175], v[204:207], v[66:69]
	v_mfma_f32_16x16x32_bf16 v[118:121], v[168:171], v[184:187], v[118:121]
	v_mfma_f32_16x16x32_bf16 v[114:117], v[176:179], v[184:187], v[114:117]
	v_mfma_f32_16x16x32_bf16 v[102:105], v[168:171], v[192:195], v[102:105]
	v_mfma_f32_16x16x32_bf16 v[98:101], v[176:179], v[192:195], v[98:101]
	v_mfma_f32_16x16x32_bf16 v[86:89], v[168:171], v[200:203], v[86:89]
	v_mfma_f32_16x16x32_bf16 v[82:85], v[176:179], v[200:203], v[82:85]
	v_mfma_f32_16x16x32_bf16 v[70:73], v[168:171], v[208:211], v[70:73]
	v_mfma_f32_16x16x32_bf16 v[66:69], v[176:179], v[208:211], v[66:69]
	s_setprio 0
	s_barrier
; #define PG8_STAGE(bufoff, gbase, voff) do { _Pragma("unroll") for (int _i = 0; _i < 2; ++_i) \
;         __builtin_amdgcn_global_load_lds((const unsigned*)((const char*)(gbase) + (voff)[_i]), (PG8_LAS unsigned*)(lds + (bufoff) + ldsw + _i * 8192), 16, 0, 0); } while (0)
; #define PG8_LDA(dst, b, h) do { _Pragma("unroll") for (int m = 0; m < 4; ++m) _Pragma("unroll") for (int k = 0; k < 2; ++k) dst[m][k] = *(const PG8_LAS bf16x8*)(lds + PG8_SA(b, h) + aoff + m * 2048 + k * 1024); } while (0)
; #define PG8_MMA(ai, bj, At, Bt) do { __builtin_amdgcn_s_setprio(1); _Pragma("unroll") for (int m = 0; m < 4; ++m) _Pragma("unroll") for (int n = 0; n < 2; ++n) _Pragma("unroll") for (int k = 0; k < 2; ++k) \
;         acc[ai][bj][m][n] = __builtin_amdgcn_mfma_f32_16x16x32_bf16(Bt[n][k], At[m][k], acc[ai][bj][m][n], 0, 0, 0); __builtin_amdgcn_s_setprio(0); } while (0)
; #define PG8_WAIT_V(n) asm volatile("s_waitcnt vmcnt(" #n ")" ::: "memory")
; #define PG8_WAIT_L(n) asm volatile("s_waitcnt lgkmcnt(" #n ")" ::: "memory")
; #define PG8_BAR __builtin_amdgcn_s_barrier()
; #define PG8_SCHED __builtin_amdgcn_sched_barrier(0)
; template <class Epi, class Sched, bool ALIGN_EPI = false, bool SP2 = false>
; __device__ __forceinline__ void gemm_phase(PG8_LAS unsigned char* lds, const Gemm g, const Sched& S, const Epi& E) {
;     ...
;         for (int t = 0; t < nt; t += 2) {
;     ...
;             PG8_LDA(At, 1, 1); PG8_STAGE(PG8_SB(1, 0), b3, voffB); PG8_STAGE(PG8_SB(1, 1), b3 + hstep, voffB); PG8_STAGE(PG8_SA(1, 0), a3, voffA);
;             PG8_WAIT_V(8); PG8_WAIT_L(0); PG8_BAR; PG8_MMA(1, 0, At, B0); PG8_MMA(1, 1, At, B1); PG8_BAR; PG8_SCHED;
	s_add_i32 s4, s42, s50
	v_lshl_add_u64 v[160:161], v[160:161], 0, s[22:23]
	s_mov_b32 m0, s4
	ds_read_b128 v[180:183], v225 offset:49152
	ds_read_b128 v[184:187], v225 offset:50176
	ds_read_b128 v[188:191], v225 offset:51200
	ds_read_b128 v[192:195], v225 offset:52224
	ds_read_b128 v[196:199], v225 offset:53248
	ds_read_b128 v[200:203], v225 offset:54272
	ds_read_b128 v[204:207], v225 offset:55296
	ds_read_b128 v[208:211], v225 offset:56320
	global_load_lds_dwordx4 v[160:161], off
	s_add_i32 m0, s4, 0x2000
	s_add_u32 s4, s6, 0xb0080
	v_lshl_add_u64 v[160:161], v[162:163], 0, s[22:23]
	s_addc_u32 s5, s7, 0
	s_add_i32 s6, s43, s50
	global_load_lds_dwordx4 v[160:161], off
	v_lshl_add_u64 v[160:161], s[4:5], 0, v[148:149]
	s_mov_b32 m0, s6
	s_nop 0
	global_load_lds_dwordx4 v[160:161], off
	v_lshl_add_u64 v[160:161], s[4:5], 0, v[152:153]
	s_add_i32 m0, s6, 0x2000
	s_nop 0
	global_load_lds_dwordx4 v[160:161], off
	v_lshl_add_u64 v[160:161], v[212:213], 0, s[24:25]
	s_mov_b32 m0, s63
	s_nop 0
	global_load_lds_dwordx4 v[160:161], off
	v_lshl_add_u64 v[160:161], v[214:215], 0, s[24:25]
	s_mov_b32 m0, s64
	s_nop 0
	global_load_lds_dwordx4 v[160:161], off
	s_waitcnt vmcnt(8)
	s_waitcnt lgkmcnt(0)
	s_barrier
	s_setprio 3
	s_waitcnt lgkmcnt(0)
	v_mfma_f32_16x16x32_bf16 v[62:65], v[130:133], v[180:183], v[62:65]
	v_mfma_f32_16x16x32_bf16 v[58:61], v[138:141], v[180:183], v[58:61]
	v_mfma_f32_16x16x32_bf16 v[46:49], v[130:133], v[188:191], v[46:49]
	v_mfma_f32_16x16x32_bf16 v[42:45], v[138:141], v[188:191], v[42:45]
	v_mfma_f32_16x16x32_bf16 v[30:33], v[130:133], v[196:199], v[30:33]
	v_mfma_f32_16x16x32_bf16 v[26:29], v[138:141], v[196:199], v[26:29]
	v_mfma_f32_16x16x32_bf16 v[14:17], v[130:133], v[204:207], v[14:17]
	v_mfma_f32_16x16x32_bf16 v[10:13], v[138:141], v[204:207], v[10:13]
	v_mfma_f32_16x16x32_bf16 v[62:65], v[134:137], v[184:187], v[62:65]
	v_mfma_f32_16x16x32_bf16 v[58:61], v[142:145], v[184:187], v[58:61]
	v_mfma_f32_16x16x32_bf16 v[46:49], v[134:137], v[192:195], v[46:49]
	v_mfma_f32_16x16x32_bf16 v[42:45], v[142:145], v[192:195], v[42:45]
	v_mfma_f32_16x16x32_bf16 v[30:33], v[134:137], v[200:203], v[30:33]
	v_mfma_f32_16x16x32_bf16 v[26:29], v[142:145], v[200:203], v[26:29]
	v_mfma_f32_16x16x32_bf16 v[14:17], v[134:137], v[208:211], v[14:17]
	v_mfma_f32_16x16x32_bf16 v[10:13], v[142:145], v[208:211], v[10:13]
	s_setprio 0
	s_setprio 3
	v_mfma_f32_16x16x32_bf16 v[54:57], v[164:167], v[180:183], v[54:57]
	v_mfma_f32_16x16x32_bf16 v[50:53], v[172:175], v[180:183], v[50:53]
	v_mfma_f32_16x16x32_bf16 v[38:41], v[164:167], v[188:191], v[38:41]
	v_mfma_f32_16x16x32_bf16 v[34:37], v[172:175], v[188:191], v[34:37]
	v_mfma_f32_16x16x32_bf16 v[22:25], v[164:167], v[196:199], v[22:25]
	v_mfma_f32_16x16x32_bf16 v[18:21], v[172:175], v[196:199], v[18:21]
	v_mfma_f32_16x16x32_bf16 v[6:9], v[164:167], v[204:207], v[6:9]
	v_mfma_f32_16x16x32_bf16 v[2:5], v[172:175], v[204:207], v[2:5]
	v_mfma_f32_16x16x32_bf16 v[54:57], v[168:171], v[184:187], v[54:57]
	v_mfma_f32_16x16x32_bf16 v[50:53], v[176:179], v[184:187], v[50:53]
	v_mfma_f32_16x16x32_bf16 v[38:41], v[168:171], v[192:195], v[38:41]
	v_mfma_f32_16x16x32_bf16 v[34:37], v[176:179], v[192:195], v[34:37]
	v_mfma_f32_16x16x32_bf16 v[22:25], v[168:171], v[200:203], v[22:25]
	v_mfma_f32_16x16x32_bf16 v[18:21], v[176:179], v[200:203], v[18:21]
	v_mfma_f32_16x16x32_bf16 v[6:9], v[168:171], v[208:211], v[6:9]
	v_mfma_f32_16x16x32_bf16 v[2:5], v[176:179], v[208:211], v[2:5]
	s_setprio 0
	s_barrier
	s_add_i32 s41, s41, 2
	s_add_u32 s39, s39, 0x100
	s_addc_u32 s40, s40, 0
	s_cmp_gt_u32 s41, 41
	s_mov_b64 s[4:5], s[0:1]
	s_cbranch_scc0 .LBB0_289
	s_and_b64 vcc, exec, s[26:27]
	s_cbranch_vccz .LBB0_292
	s_barrier

;     __host__ __device__ bool next(int i, Unit& u) const { if (!b.next(i >> 1, u)) return false; u.sel = i & 1; return true; }
; #define PG8_STAGE(bufoff, gbase, voff) do { _Pragma("unroll") for (int _i = 0; _i < 2; ++_i) \
;         __builtin_amdgcn_global_load_lds((const unsigned*)((const char*)(gbase) + (voff)[_i]), (PG8_LAS unsigned*)(lds + (bufoff) + ldsw + _i * 8192), 16, 0, 0); } while (0)
; #define PG8_LDA(dst, b, h) do { _Pragma("unroll") for (int m = 0; m < 4; ++m) _Pragma("unroll") for (int k = 0; k < 2; ++k) dst[m][k] = *(const PG8_LAS bf16x8*)(lds + PG8_SA(b, h) + aoff + m * 2048 + k * 1024); } while (0)
; #define PG8_WAIT_V(n) asm volatile("s_waitcnt vmcnt(" #n ")" ::: "memory")
;     __host__ __device__ bool next(int i, Unit& u) const {
;         const long L = (long)i * G + c; if (L >= nwg) return false;
;         int wgid = (int)L; { const int q = nwg / NXCD, r = nwg % NXCD, xcd = wgid % NXCD, off = wgid / NXCD; wgid = (xcd < r ? xcd * (q + 1) : r * (q + 1) + (xcd - r) * q) + off; }
;         const int nig = WGM * nN, gid = wgid / nig, fm = gid * WGM, gsz = (nM - fm) < WGM ? (nM - fm) : WGM;
;         u.pm = fm + ((wgid % nig) % gsz); u.pn = (wgid % nig) / gsz; u.sel = 0; return true;
; template <class Epi, class Sched, bool ALIGN_EPI = false, bool SP2 = false>
; __device__ __forceinline__ void gemm_phase(PG8_LAS unsigned char* lds, const Gemm g, const Sched& S, const Epi& E) {
;     ...
;         const bool has_next = S.next(ui + 1, nxt);
;         const char* nA = has_next ? PG8_ABASE(nxt) : cA; const char* nB = has_next ? PG8_BBASE(nxt) : cB;
;         for (int t = 0; t < nt; t += 2) {
;             const bool last = (t == nt - 2);
;             const char* a1 = cA + (size_t)(t + 1) * kstepA;
;             const char* a2 = last ? nA : cA + (size_t)(t + 2) * kstepA; const char* b2 = last ? nB : cB + (size_t)(t + 2) * kstep;
;             const char* a3 = a2 + kstepA; const char* b3 = b2 + kstep;
;             if (last && has_next) S.a_ready(nxt);
;             if constexpr (SP2) {
;             PG8_LDB(B0, 0, 0); PG8_LDB(B1, 0, 1); PG8_SCHED; PG8_LDA(At, 0, 0); PG8_STAGE(PG8_SA(1, 1), a1 + hstep, voffA);
;             PG8_WAIT_V(8); PG8_WAIT_L(0); PG8_BAR; PG8_MMA(0, 0, At, B0); PG8_MMA(0, 1, At, B1); PG8_BAR; PG8_SCHED;
;             if constexpr (Epi::PREFETCH) { if (t == tpf) E.prefetch(cur, wid, lane); }
.LBB0_435:
	s_ashr_i32 s5, s4, 31
	s_lshl_b32 s8, s6, 8
	s_lshl_b64 s[28:29], s[4:5], 14
	s_ashr_i32 s5, s4, 5
	s_ashr_i32 s9, s8, 31
	s_add_u32 s52, s14, s28
	s_mul_hi_i32 s54, s5, 0x6800
	s_mulk_i32 s5, 0x6800
	s_addc_u32 s53, s88, s29
	s_add_u32 s5, s77, s5
	s_addc_u32 s55, s78, s54
	s_lshl_b64 s[28:29], s[8:9], 2
	s_add_u32 s54, s5, s28
	s_addc_u32 s55, s55, s29
	s_add_u32 s5, s56, 0x100
	v_lshl_add_u64 v[196:197], s[10:11], 0, v[188:189]
	v_lshl_add_u64 v[198:199], s[10:11], 0, v[190:191]
	s_addc_u32 s9, s57, 0
	s_mov_b32 s28, 0
	s_mov_b64 s[56:57], 0
	ds_read_b128 v[162:165], v208
	ds_read_b128 v[166:169], v208 offset:1024
	ds_read_b128 v[170:173], v208 offset:2048
	ds_read_b128 v[174:177], v208 offset:3072
	ds_read_b128 v[146:149], v209
	ds_read_b128 v[150:153], v209 offset:1024
	ds_read_b128 v[154:157], v209 offset:2048
	ds_read_b128 v[158:161], v209 offset:3072
	v_lshl_add_u64 v[42:43], v[196:197], 0, s[56:57]
	s_add_i32 m0, s69, 0xc000
	ds_read_b128 v[212:215], v210
	ds_read_b128 v[216:219], v210 offset:1024
	ds_read_b128 v[222:225], v210 offset:2048
	ds_read_b128 v[226:229], v210 offset:3072
	ds_read_b128 v[230:233], v210 offset:4096
	ds_read_b128 v[234:237], v210 offset:5120
	ds_read_b128 v[238:241], v210 offset:6144
	ds_read_b128 v[242:245], v210 offset:7168
	global_load_lds_dwordx4 v[42:43], off
	v_lshl_add_u64 v[42:43], v[198:199], 0, s[56:57]
	s_add_i32 m0, s69, 0xe000
	s_nop 0
	global_load_lds_dwordx4 v[42:43], off
	s_add_i32 s15, s15, 1
	s_mul_i32 s2, s15, s86
	s_mul_hi_u32 s3, s15, s33
	s_add_i32 s3, s3, s2
	s_mul_i32 s2, s15, s33
	v_readlane_b32 s98, v254, 12
	s_add_u32 s100, s2, s98
	s_addc_u32 s101, s3, s87
	v_cmp_lt_i64_e64 s[2:3], s[100:101], v[192:193]
	s_ashr_i32 s98, s100, 31
	s_lshr_b32 s98, s98, 29
	s_add_i32 s98, s100, s98
	s_ashr_i32 s7, s98, 3
	s_and_b32 s98, s98, -8
	s_sub_i32 s98, s100, s98
	s_cmp_lt_i32 s98, 0
	s_movk_i32 s100, 0x1a1
	s_cselect_b32 s100, s100, 0x1a0
	s_mul_i32 s98, s98, s100
	s_add_i32 s98, s98, s7
	s_mul_hi_i32 s7, s98, 0x4ec4ec4f
	s_lshr_b32 s100, s7, 31
	s_ashr_i32 s7, s7, 4
	s_add_i32 s7, s7, s100
	s_lshl_b32 s100, s7, 1
	s_mul_i32 s7, s7, 52
	s_sub_i32 s98, s98, s7
	s_lshr_b32 s44, s98, 1
	s_and_b32 s98, s98, 1
	s_add_i32 s46, s100, s98
	s_ashr_i32 s47, s46, 31
	s_lshl_b64 s[100:101], s[46:47], 19
	s_add_u32 s48, s64, s100
	s_addc_u32 s49, s65, s101
	s_and_b64 s[100:101], s[2:3], exec
	s_cselect_b32 s7, s49, s65
	s_cselect_b32 s31, s48, s64
	s_ashr_i32 s45, s44, 31
	s_lshl_b64 s[100:101], s[44:45], 19
	s_add_u32 s50, s66, s100
	s_addc_u32 s51, s67, s101
	s_and_b64 s[100:101], s[2:3], exec
	s_cselect_b32 s45, s51, s67
	s_cselect_b32 s47, s50, s66
	s_waitcnt vmcnt(8)
	s_waitcnt lgkmcnt(0)
	s_barrier
	s_setprio 3
	s_waitcnt lgkmcnt(0)
	v_mfma_f32_16x16x32_bf16 v[42:45], v[162:165], v[212:215], 0
	v_mfma_f32_16x16x32_bf16 v[46:49], v[170:173], v[212:215], 0
	v_mfma_f32_16x16x32_bf16 v[50:53], v[162:165], v[222:225], 0
	v_mfma_f32_16x16x32_bf16 v[54:57], v[170:173], v[222:225], 0
	v_mfma_f32_16x16x32_bf16 v[110:113], v[162:165], v[230:233], 0
	v_mfma_f32_16x16x32_bf16 v[106:109], v[170:173], v[230:233], 0
	v_mfma_f32_16x16x32_bf16 v[94:97], v[162:165], v[238:241], 0
	v_mfma_f32_16x16x32_bf16 v[90:93], v[170:173], v[238:241], 0
	v_mfma_f32_16x16x32_bf16 v[42:45], v[166:169], v[216:219], v[42:45]
	v_mfma_f32_16x16x32_bf16 v[46:49], v[174:177], v[216:219], v[46:49]
	v_mfma_f32_16x16x32_bf16 v[50:53], v[166:169], v[226:229], v[50:53]
	v_mfma_f32_16x16x32_bf16 v[54:57], v[174:177], v[226:229], v[54:57]
	v_mfma_f32_16x16x32_bf16 v[110:113], v[166:169], v[234:237], v[110:113]
	v_mfma_f32_16x16x32_bf16 v[106:109], v[174:177], v[234:237], v[106:109]
	v_mfma_f32_16x16x32_bf16 v[94:97], v[166:169], v[242:245], v[94:97]
	v_mfma_f32_16x16x32_bf16 v[90:93], v[174:177], v[242:245], v[90:93]
	s_setprio 0
	s_setprio 3
	v_mfma_f32_16x16x32_bf16 v[122:125], v[146:149], v[212:215], 0
	v_mfma_f32_16x16x32_bf16 v[134:137], v[150:153], v[216:219], v[122:125]
	v_mfma_f32_16x16x32_bf16 v[122:125], v[154:157], v[212:215], 0
	v_mfma_f32_16x16x32_bf16 v[118:121], v[146:149], v[222:225], 0
	v_mfma_f32_16x16x32_bf16 v[114:117], v[154:157], v[222:225], 0
	v_mfma_f32_16x16x32_bf16 v[102:105], v[146:149], v[230:233], 0
	v_mfma_f32_16x16x32_bf16 v[98:101], v[154:157], v[230:233], 0
	v_mfma_f32_16x16x32_bf16 v[86:89], v[146:149], v[238:241], 0
	v_mfma_f32_16x16x32_bf16 v[82:85], v[154:157], v[238:241], 0
	v_mfma_f32_16x16x32_bf16 v[130:133], v[158:161], v[216:219], v[122:125]
	v_mfma_f32_16x16x32_bf16 v[118:121], v[150:153], v[226:229], v[118:121]
	v_mfma_f32_16x16x32_bf16 v[114:117], v[158:161], v[226:229], v[114:117]
	v_mfma_f32_16x16x32_bf16 v[102:105], v[150:153], v[234:237], v[102:105]
	v_mfma_f32_16x16x32_bf16 v[98:101], v[158:161], v[234:237], v[98:101]
	v_mfma_f32_16x16x32_bf16 v[86:89], v[150:153], v[242:245], v[86:89]
	v_mfma_f32_16x16x32_bf16 v[82:85], v[158:161], v[242:245], v[82:85]
	s_setprio 0
	s_barrier
	s_cmp_lg_u32 s63, s28
	s_cbranch_scc1 .Lpz3_a
	v_mov_b32_e32 v186, v207
	s_add_i32 m0, s62, 0x20000
	v_lshl_add_u64 v[122:123], s[52:53], 0, v[186:187]
	s_mov_b64 s[58:59], 0x400
	global_load_lds_dwordx4 v186, s[52:53]
	v_lshl_add_u64 v[122:123], v[122:123], 0, s[58:59]
	s_add_i32 m0, s62, 0x20400
	s_andn2_b64 vcc, exec, s[40:41]
	global_load_lds_dwordx4 v[122:123], off
	s_cbranch_vccnz .Lpz3_a
	v_lshl_add_u64 v[122:123], s[54:55], 0, v[186:187]
	s_mov_b32 m0, s30
	s_nop 0
	global_load_lds_dwordx4 v[122:123], off
	s_branch .Lpz3_a
; #define PG8_STAGE(bufoff, gbase, voff) do { _Pragma("unroll") for (int _i = 0; _i < 2; ++_i) \
;         __builtin_amdgcn_global_load_lds((const unsigned*)((const char*)(gbase) + (voff)[_i]), (PG8_LAS unsigned*)(lds + (bufoff) + ldsw + _i * 8192), 16, 0, 0); } while (0)
; #define PG8_LDA(dst, b, h) do { _Pragma("unroll") for (int m = 0; m < 4; ++m) _Pragma("unroll") for (int k = 0; k < 2; ++k) dst[m][k] = *(const PG8_LAS bf16x8*)(lds + PG8_SA(b, h) + aoff + m * 2048 + k * 1024); } while (0)
; #define PG8_LDB(dst, b, h) do { _Pragma("unroll") for (int n = 0; n < 2; ++n) _Pragma("unroll") for (int k = 0; k < 2; ++k) dst[n][k] = *(const PG8_LAS bf16x8*)(lds + PG8_SB(b, h) + boff + n * 2048 + k * 1024); } while (0)
; #define PG8_MMA(ai, bj, At, Bt) do { __builtin_amdgcn_s_setprio(1); _Pragma("unroll") for (int m = 0; m < 4; ++m) _Pragma("unroll") for (int n = 0; n < 2; ++n) _Pragma("unroll") for (int k = 0; k < 2; ++k) \
;         acc[ai][bj][m][n] = __builtin_amdgcn_mfma_f32_16x16x32_bf16(Bt[n][k], At[m][k], acc[ai][bj][m][n], 0, 0, 0); __builtin_amdgcn_s_setprio(0); } while (0)
; #define PG8_WAIT_V(n) asm volatile("s_waitcnt vmcnt(" #n ")" ::: "memory")
; #define PG8_BAR __builtin_amdgcn_s_barrier()
; template <class Epi, class Sched, bool ALIGN_EPI = false, bool SP2 = false>
; __device__ __forceinline__ void gemm_phase(PG8_LAS unsigned char* lds, const Gemm g, const Sched& S, const Epi& E) {
;     ...
;             const char* a1 = cA + (size_t)(t + 1) * kstepA;
;             const char* a2 = last ? nA : cA + (size_t)(t + 2) * kstepA; const char* b2 = last ? nB : cB + (size_t)(t + 2) * kstep;
;             const char* a3 = a2 + kstepA; const char* b3 = b2 + kstep;
;             if (last && has_next) S.a_ready(nxt);
;             if constexpr (SP2) {
;             PG8_LDB(B0, 0, 0); PG8_LDB(B1, 0, 1); PG8_SCHED; PG8_LDA(At, 0, 0); PG8_STAGE(PG8_SA(1, 1), a1 + hstep, voffA);
;             PG8_WAIT_V(8); PG8_WAIT_L(0); PG8_BAR; PG8_MMA(0, 0, At, B0); PG8_MMA(0, 1, At, B1); PG8_BAR; PG8_SCHED;
;             if constexpr (Epi::PREFETCH) { if (t == tpf) E.prefetch(cur, wid, lane); }
;             PG8_LDA(At, 0, 1); PG8_STAGE(PG8_SB(0, 0), b2, voffB); PG8_STAGE(PG8_SB(0, 1), b2 + hstep, voffB); PG8_STAGE(PG8_SA(0, 0), a2, voffA);
;             PG8_WAIT_V(8); PG8_WAIT_L(0); PG8_BAR; PG8_MMA(1, 0, At, B0); PG8_MMA(1, 1, At, B1); PG8_BAR; PG8_SCHED;
.Lpz3_a:
	s_add_u32 s29, s10, s56
	s_addc_u32 s58, s11, s57
	s_add_u32 s29, s29, 0x100
	s_addc_u32 s58, s58, 0
	s_add_u32 vcc_lo, s5, s56
	s_addc_u32 s59, s9, s57
	s_cmpk_eq_i32 s56, 0x700
	s_cselect_b32 s61, s7, s58
	s_cselect_b32 s59, s45, s59
	s_cselect_b32 s58, s47, vcc_lo
	s_mov_b32 m0, s70
	s_cselect_b32 s60, s31, s29
	v_lshl_add_u64 v[204:205], s[58:59], 0, v[180:181]
	s_add_u32 vcc_lo, s58, 0x40000
	ds_read_b128 v[122:125], v210 offset:16384
	ds_read_b128 v[126:129], v210 offset:17408
	ds_read_b128 v[138:141], v210 offset:18432
	ds_read_b128 v[142:145], v210 offset:19456
	ds_read_b128 v[212:215], v210 offset:20480
	ds_read_b128 v[216:219], v210 offset:21504
	ds_read_b128 v[222:225], v210 offset:22528
	ds_read_b128 v[226:229], v210 offset:23552
	global_load_lds_dwordx4 v[204:205], off
	v_lshl_add_u64 v[246:247], s[58:59], 0, v[184:185]
	s_mov_b32 m0, s71
	s_addc_u32 vcc_hi, s59, 0
	global_load_lds_dwordx4 v[246:247], off
	v_lshl_add_u64 v[230:231], vcc, 0, v[180:181]
	s_mov_b32 m0, s72
	v_lshl_add_u64 v[248:249], s[60:61], 0, v[178:179]
	global_load_lds_dwordx4 v[230:231], off
	v_lshl_add_u64 v[230:231], vcc, 0, v[184:185]
	s_mov_b32 m0, s73
	v_lshl_add_u64 v[250:251], s[60:61], 0, v[182:183]
	global_load_lds_dwordx4 v[230:231], off
	s_mov_b32 m0, s69
	s_nop 0
	global_load_lds_dwordx4 v[248:249], off
	s_mov_b32 m0, s74
	s_nop 0
	global_load_lds_dwordx4 v[250:251], off
	s_waitcnt vmcnt(8)
	s_waitcnt lgkmcnt(0)
	s_barrier
	s_setprio 3
	s_waitcnt lgkmcnt(0)
	v_mfma_f32_16x16x32_bf16 v[78:81], v[162:165], v[122:125], 0
	v_mfma_f32_16x16x32_bf16 v[74:77], v[170:173], v[122:125], 0
	v_mfma_f32_16x16x32_bf16 v[62:65], v[162:165], v[138:141], 0
	v_mfma_f32_16x16x32_bf16 v[58:61], v[170:173], v[138:141], 0
	v_mfma_f32_16x16x32_bf16 v[30:33], v[162:165], v[212:215], 0
	v_mfma_f32_16x16x32_bf16 v[26:29], v[170:173], v[212:215], 0
	v_mfma_f32_16x16x32_bf16 v[14:17], v[162:165], v[222:225], 0
	v_mfma_f32_16x16x32_bf16 v[10:13], v[170:173], v[222:225], 0
	v_mfma_f32_16x16x32_bf16 v[78:81], v[166:169], v[126:129], v[78:81]
	v_mfma_f32_16x16x32_bf16 v[74:77], v[174:177], v[126:129], v[74:77]
	v_mfma_f32_16x16x32_bf16 v[62:65], v[166:169], v[142:145], v[62:65]
	v_mfma_f32_16x16x32_bf16 v[58:61], v[174:177], v[142:145], v[58:61]
	v_mfma_f32_16x16x32_bf16 v[30:33], v[166:169], v[216:219], v[30:33]
	v_mfma_f32_16x16x32_bf16 v[26:29], v[174:177], v[216:219], v[26:29]
	v_mfma_f32_16x16x32_bf16 v[14:17], v[166:169], v[226:229], v[14:17]
	v_mfma_f32_16x16x32_bf16 v[10:13], v[174:177], v[226:229], v[10:13]
	s_setprio 0
	s_setprio 3
	v_mfma_f32_16x16x32_bf16 v[70:73], v[146:149], v[122:125], 0
	v_mfma_f32_16x16x32_bf16 v[66:69], v[154:157], v[122:125], 0
	v_mfma_f32_16x16x32_bf16 v[38:41], v[146:149], v[138:141], 0
	v_mfma_f32_16x16x32_bf16 v[34:37], v[154:157], v[138:141], 0
	v_mfma_f32_16x16x32_bf16 v[22:25], v[146:149], v[212:215], 0
	v_mfma_f32_16x16x32_bf16 v[18:21], v[154:157], v[212:215], 0
	v_mfma_f32_16x16x32_bf16 v[6:9], v[146:149], v[222:225], 0
	v_mfma_f32_16x16x32_bf16 v[2:5], v[154:157], v[222:225], 0
	v_mfma_f32_16x16x32_bf16 v[70:73], v[150:153], v[126:129], v[70:73]
	v_mfma_f32_16x16x32_bf16 v[66:69], v[158:161], v[126:129], v[66:69]
	v_mfma_f32_16x16x32_bf16 v[38:41], v[150:153], v[142:145], v[38:41]
	v_mfma_f32_16x16x32_bf16 v[34:37], v[158:161], v[142:145], v[34:37]
	v_mfma_f32_16x16x32_bf16 v[22:25], v[150:153], v[216:219], v[22:25]
	v_mfma_f32_16x16x32_bf16 v[18:21], v[158:161], v[216:219], v[18:21]
	v_mfma_f32_16x16x32_bf16 v[6:9], v[150:153], v[226:229], v[6:9]
	v_mfma_f32_16x16x32_bf16 v[2:5], v[158:161], v[226:229], v[2:5]
	s_setprio 0
	s_barrier
	s_branch .Lpz3_mid
.LBB0_438:
	s_add_u32 s29, s10, s56
	s_addc_u32 s58, s11, s57
	s_add_u32 s29, s29, 0x100
	s_addc_u32 s58, s58, 0
	s_add_u32 vcc_lo, s5, s56
	s_addc_u32 s59, s9, s57
	s_cmpk_eq_i32 s56, 0x700
	s_cselect_b32 s61, s7, s58
	s_cselect_b32 s59, s45, s59
	s_cselect_b32 s58, s47, vcc_lo
	s_mov_b32 m0, s70
	s_cselect_b32 s60, s31, s29
	v_lshl_add_u64 v[204:205], s[58:59], 0, v[180:181]
	s_add_u32 vcc_lo, s58, 0x40000
	ds_read_b128 v[122:125], v210 offset:16384
	ds_read_b128 v[126:129], v210 offset:17408
	ds_read_b128 v[138:141], v210 offset:18432
	ds_read_b128 v[142:145], v210 offset:19456
	ds_read_b128 v[212:215], v210 offset:20480
	ds_read_b128 v[216:219], v210 offset:21504
	ds_read_b128 v[222:225], v210 offset:22528
	ds_read_b128 v[226:229], v210 offset:23552
	global_load_lds_dwordx4 v[204:205], off
	v_lshl_add_u64 v[246:247], s[58:59], 0, v[184:185]
	s_mov_b32 m0, s71
	s_addc_u32 vcc_hi, s59, 0
	global_load_lds_dwordx4 v[246:247], off
	v_lshl_add_u64 v[230:231], vcc, 0, v[180:181]
	s_mov_b32 m0, s72
	v_lshl_add_u64 v[248:249], s[60:61], 0, v[178:179]
	global_load_lds_dwordx4 v[230:231], off
	v_lshl_add_u64 v[230:231], vcc, 0, v[184:185]
	s_mov_b32 m0, s73
	v_lshl_add_u64 v[250:251], s[60:61], 0, v[182:183]
	global_load_lds_dwordx4 v[230:231], off
	s_mov_b32 m0, s69
	s_nop 0
	global_load_lds_dwordx4 v[248:249], off
	s_mov_b32 m0, s74
	s_nop 0
	global_load_lds_dwordx4 v[250:251], off
	s_waitcnt vmcnt(8)
	s_waitcnt lgkmcnt(0)
	s_barrier
; #define PG8_STAGE(bufoff, gbase, voff) do { _Pragma("unroll") for (int _i = 0; _i < 2; ++_i) \
;         __builtin_amdgcn_global_load_lds((const unsigned*)((const char*)(gbase) + (voff)[_i]), (PG8_LAS unsigned*)(lds + (bufoff) + ldsw + _i * 8192), 16, 0, 0); } while (0)
; #define PG8_LDA(dst, b, h) do { _Pragma("unroll") for (int m = 0; m < 4; ++m) _Pragma("unroll") for (int k = 0; k < 2; ++k) dst[m][k] = *(const PG8_LAS bf16x8*)(lds + PG8_SA(b, h) + aoff + m * 2048 + k * 1024); } while (0)
; #define PG8_LDB(dst, b, h) do { _Pragma("unroll") for (int n = 0; n < 2; ++n) _Pragma("unroll") for (int k = 0; k < 2; ++k) dst[n][k] = *(const PG8_LAS bf16x8*)(lds + PG8_SB(b, h) + boff + n * 2048 + k * 1024); } while (0)
; #define PG8_MMA(ai, bj, At, Bt) do { __builtin_amdgcn_s_setprio(1); _Pragma("unroll") for (int m = 0; m < 4; ++m) _Pragma("unroll") for (int n = 0; n < 2; ++n) _Pragma("unroll") for (int k = 0; k < 2; ++k) \
;         acc[ai][bj][m][n] = __builtin_amdgcn_mfma_f32_16x16x32_bf16(Bt[n][k], At[m][k], acc[ai][bj][m][n], 0, 0, 0); __builtin_amdgcn_s_setprio(0); } while (0)
; #define PG8_WAIT_V(n) asm volatile("s_waitcnt vmcnt(" #n ")" ::: "memory")
; #define PG8_WAIT_L(n) asm volatile("s_waitcnt lgkmcnt(" #n ")" ::: "memory")
; #define PG8_BAR __builtin_amdgcn_s_barrier()
; #define PG8_SCHED __builtin_amdgcn_sched_barrier(0)
; template <class Epi, class Sched, bool ALIGN_EPI = false, bool SP2 = false>
; __device__ __forceinline__ void gemm_phase(PG8_LAS unsigned char* lds, const Gemm g, const Sched& S, const Epi& E) {
;     ...
;             PG8_WAIT_V(8); PG8_WAIT_L(0); PG8_BAR; PG8_MMA(1, 0, At, B0); PG8_MMA(1, 1, At, B1); PG8_BAR; PG8_SCHED;
;             PG8_LDB(B0, 1, 0); PG8_LDB(B1, 1, 1); PG8_SCHED; PG8_LDA(At, 1, 0); PG8_STAGE(PG8_SA(0, 1), a2 + hstep, voffA);
;             PG8_WAIT_V(8); PG8_WAIT_L(0); PG8_BAR; PG8_MMA(0, 0, At, B0); PG8_MMA(0, 1, At, B1); PG8_BAR; PG8_SCHED;
	s_setprio 3
	s_waitcnt lgkmcnt(0)
	v_mfma_f32_16x16x32_bf16 v[78:81], v[162:165], v[122:125], v[78:81]
	v_mfma_f32_16x16x32_bf16 v[74:77], v[170:173], v[122:125], v[74:77]
	v_mfma_f32_16x16x32_bf16 v[62:65], v[162:165], v[138:141], v[62:65]
	v_mfma_f32_16x16x32_bf16 v[58:61], v[170:173], v[138:141], v[58:61]
	v_mfma_f32_16x16x32_bf16 v[30:33], v[162:165], v[212:215], v[30:33]
	v_mfma_f32_16x16x32_bf16 v[26:29], v[170:173], v[212:215], v[26:29]
	v_mfma_f32_16x16x32_bf16 v[14:17], v[162:165], v[222:225], v[14:17]
	v_mfma_f32_16x16x32_bf16 v[10:13], v[170:173], v[222:225], v[10:13]
	v_mfma_f32_16x16x32_bf16 v[78:81], v[166:169], v[126:129], v[78:81]
	v_mfma_f32_16x16x32_bf16 v[74:77], v[174:177], v[126:129], v[74:77]
	v_mfma_f32_16x16x32_bf16 v[62:65], v[166:169], v[142:145], v[62:65]
	v_mfma_f32_16x16x32_bf16 v[58:61], v[174:177], v[142:145], v[58:61]
	v_mfma_f32_16x16x32_bf16 v[30:33], v[166:169], v[216:219], v[30:33]
	v_mfma_f32_16x16x32_bf16 v[26:29], v[174:177], v[216:219], v[26:29]
	v_mfma_f32_16x16x32_bf16 v[14:17], v[166:169], v[226:229], v[14:17]
	v_mfma_f32_16x16x32_bf16 v[10:13], v[174:177], v[226:229], v[10:13]
	s_setprio 0
	s_setprio 3
	v_mfma_f32_16x16x32_bf16 v[70:73], v[146:149], v[122:125], v[70:73]
	v_mfma_f32_16x16x32_bf16 v[66:69], v[154:157], v[122:125], v[66:69]
	v_mfma_f32_16x16x32_bf16 v[38:41], v[146:149], v[138:141], v[38:41]
	v_mfma_f32_16x16x32_bf16 v[34:37], v[154:157], v[138:141], v[34:37]
	v_mfma_f32_16x16x32_bf16 v[22:25], v[146:149], v[212:215], v[22:25]
	v_mfma_f32_16x16x32_bf16 v[18:21], v[154:157], v[212:215], v[18:21]
	v_mfma_f32_16x16x32_bf16 v[6:9], v[146:149], v[222:225], v[6:9]
	v_mfma_f32_16x16x32_bf16 v[2:5], v[154:157], v[222:225], v[2:5]
	v_mfma_f32_16x16x32_bf16 v[70:73], v[150:153], v[126:129], v[70:73]
	v_mfma_f32_16x16x32_bf16 v[66:69], v[158:161], v[126:129], v[66:69]
	v_mfma_f32_16x16x32_bf16 v[38:41], v[150:153], v[142:145], v[38:41]
	v_mfma_f32_16x16x32_bf16 v[34:37], v[158:161], v[142:145], v[34:37]
	v_mfma_f32_16x16x32_bf16 v[22:25], v[150:153], v[216:219], v[22:25]
	v_mfma_f32_16x16x32_bf16 v[18:21], v[158:161], v[216:219], v[18:21]
	v_mfma_f32_16x16x32_bf16 v[6:9], v[150:153], v[226:229], v[6:9]
	v_mfma_f32_16x16x32_bf16 v[2:5], v[158:161], v[226:229], v[2:5]
	s_setprio 0
	s_barrier
.Lpz3_mid:
	s_add_i32 s29, 0, 0x18000
	v_add_u32_e32 v122, s29, v203
	s_add_i32 vcc_lo, 0, 0x1c000
	ds_read_b128 v[146:149], v122
	ds_read_b128 v[150:153], v122 offset:1024
	ds_read_b128 v[154:157], v122 offset:2048
	ds_read_b128 v[158:161], v122 offset:3072
	v_add_u32_e32 v122, vcc_lo, v203
	ds_read_b128 v[162:165], v122
	ds_read_b128 v[166:169], v122 offset:1024
	ds_read_b128 v[170:173], v122 offset:2048
	ds_read_b128 v[174:177], v122 offset:3072
	s_add_u32 s60, s60, 0x40000
	s_addc_u32 s61, s61, 0
	s_mov_b32 m0, s75
	v_lshl_add_u64 v[122:123], s[60:61], 0, v[178:179]
	ds_read_b128 v[212:215], v210 offset:32768
	ds_read_b128 v[216:219], v210 offset:33792
	ds_read_b128 v[222:225], v210 offset:34816
	ds_read_b128 v[226:229], v210 offset:35840
	ds_read_b128 v[230:233], v210 offset:36864
	ds_read_b128 v[234:237], v210 offset:37888
	ds_read_b128 v[238:241], v210 offset:38912
	ds_read_b128 v[242:245], v210 offset:39936
	global_load_lds_dwordx4 v[122:123], off
	v_lshl_add_u64 v[122:123], s[60:61], 0, v[182:183]
	s_mov_b32 m0, s76
	s_nop 0
	global_load_lds_dwordx4 v[122:123], off
	s_waitcnt vmcnt(8)
	s_waitcnt lgkmcnt(0)
	s_barrier
	s_setprio 3
	s_waitcnt lgkmcnt(0)
	v_mfma_f32_16x16x32_bf16 v[42:45], v[146:149], v[212:215], v[42:45]
	v_mfma_f32_16x16x32_bf16 v[142:145], v[150:153], v[216:219], v[42:45]
	v_mfma_f32_16x16x32_bf16 v[42:45], v[154:157], v[212:215], v[46:49]
	v_mfma_f32_16x16x32_bf16 v[138:141], v[158:161], v[216:219], v[42:45]
	v_mfma_f32_16x16x32_bf16 v[42:45], v[146:149], v[222:225], v[50:53]
	v_mfma_f32_16x16x32_bf16 v[126:129], v[150:153], v[226:229], v[42:45]
	v_mfma_f32_16x16x32_bf16 v[42:45], v[154:157], v[222:225], v[54:57]
	v_mfma_f32_16x16x32_bf16 v[122:125], v[158:161], v[226:229], v[42:45]
	v_mfma_f32_16x16x32_bf16 v[42:45], v[146:149], v[230:233], v[110:113]
	v_mfma_f32_16x16x32_bf16 v[110:113], v[150:153], v[234:237], v[42:45]
	v_mfma_f32_16x16x32_bf16 v[42:45], v[154:157], v[230:233], v[106:109]
	v_mfma_f32_16x16x32_bf16 v[106:109], v[158:161], v[234:237], v[42:45]
	v_mfma_f32_16x16x32_bf16 v[42:45], v[146:149], v[238:241], v[94:97]
	v_mfma_f32_16x16x32_bf16 v[94:97], v[150:153], v[242:245], v[42:45]
	v_mfma_f32_16x16x32_bf16 v[42:45], v[154:157], v[238:241], v[90:93]
	v_mfma_f32_16x16x32_bf16 v[90:93], v[158:161], v[242:245], v[42:45]
	s_setprio 0
	s_setprio 3
	v_mfma_f32_16x16x32_bf16 v[42:45], v[162:165], v[212:215], v[134:137]
	v_mfma_f32_16x16x32_bf16 v[134:137], v[166:169], v[216:219], v[42:45]
	v_mfma_f32_16x16x32_bf16 v[42:45], v[170:173], v[212:215], v[130:133]
	v_mfma_f32_16x16x32_bf16 v[130:133], v[174:177], v[216:219], v[42:45]
	v_mfma_f32_16x16x32_bf16 v[42:45], v[162:165], v[222:225], v[118:121]
	v_mfma_f32_16x16x32_bf16 v[118:121], v[166:169], v[226:229], v[42:45]
	v_mfma_f32_16x16x32_bf16 v[42:45], v[170:173], v[222:225], v[114:117]
	v_mfma_f32_16x16x32_bf16 v[114:117], v[174:177], v[226:229], v[42:45]
	v_mfma_f32_16x16x32_bf16 v[42:45], v[162:165], v[230:233], v[102:105]
	v_mfma_f32_16x16x32_bf16 v[102:105], v[166:169], v[234:237], v[42:45]
	v_mfma_f32_16x16x32_bf16 v[42:45], v[170:173], v[230:233], v[98:101]
	v_mfma_f32_16x16x32_bf16 v[98:101], v[174:177], v[234:237], v[42:45]
	v_mfma_f32_16x16x32_bf16 v[42:45], v[162:165], v[238:241], v[86:89]
	v_mfma_f32_16x16x32_bf16 v[86:89], v[166:169], v[242:245], v[42:45]
	v_mfma_f32_16x16x32_bf16 v[42:45], v[170:173], v[238:241], v[82:85]
	v_mfma_f32_16x16x32_bf16 v[82:85], v[174:177], v[242:245], v[42:45]
	s_setprio 0
	s_barrier
; #define PG8_STAGE(bufoff, gbase, voff) do { _Pragma("unroll") for (int _i = 0; _i < 2; ++_i) \
;         __builtin_amdgcn_global_load_lds((const unsigned*)((const char*)(gbase) + (voff)[_i]), (PG8_LAS unsigned*)(lds + (bufoff) + ldsw + _i * 8192), 16, 0, 0); } while (0)
; #define PG8_LDA(dst, b, h) do { _Pragma("unroll") for (int m = 0; m < 4; ++m) _Pragma("unroll") for (int k = 0; k < 2; ++k) dst[m][k] = *(const PG8_LAS bf16x8*)(lds + PG8_SA(b, h) + aoff + m * 2048 + k * 1024); } while (0)
; #define PG8_MMA(ai, bj, At, Bt) do { __builtin_amdgcn_s_setprio(1); _Pragma("unroll") for (int m = 0; m < 4; ++m) _Pragma("unroll") for (int n = 0; n < 2; ++n) _Pragma("unroll") for (int k = 0; k < 2; ++k) \
;         acc[ai][bj][m][n] = __builtin_amdgcn_mfma_f32_16x16x32_bf16(Bt[n][k], At[m][k], acc[ai][bj][m][n], 0, 0, 0); __builtin_amdgcn_s_setprio(0); } while (0)
; #define PG8_WAIT_V(n) asm volatile("s_waitcnt vmcnt(" #n ")" ::: "memory")
; #define PG8_WAIT_L(n) asm volatile("s_waitcnt lgkmcnt(" #n ")" ::: "memory")
; #define PG8_BAR __builtin_amdgcn_s_barrier()
; #define PG8_SCHED __builtin_amdgcn_sched_barrier(0)
; template <class Epi, class Sched, bool ALIGN_EPI = false, bool SP2 = false>
; __device__ __forceinline__ void gemm_phase(PG8_LAS unsigned char* lds, const Gemm g, const Sched& S, const Epi& E) {
;     ...
;             PG8_LDA(At, 1, 1); PG8_STAGE(PG8_SB(1, 0), b3, voffB); PG8_STAGE(PG8_SB(1, 1), b3 + hstep, voffB); PG8_STAGE(PG8_SA(1, 0), a3, voffA);
;             PG8_WAIT_V(8); PG8_WAIT_L(0); PG8_BAR; PG8_MMA(1, 0, At, B0); PG8_MMA(1, 1, At, B1); PG8_BAR; PG8_SCHED;
	s_add_i32 s29, s29, s68
	v_lshl_add_u64 v[204:205], v[204:205], 0, s[38:39]
	s_mov_b32 m0, s29
	s_nop 1
	ds_read_b128 v[42:45], v210 offset:49152
	ds_read_b128 v[46:49], v210 offset:50176
	ds_read_b128 v[50:53], v210 offset:51200
	ds_read_b128 v[54:57], v210 offset:52224
	ds_read_b128 v[212:215], v210 offset:53248
	ds_read_b128 v[216:219], v210 offset:54272
	ds_read_b128 v[222:225], v210 offset:55296
	ds_read_b128 v[226:229], v210 offset:56320
	global_load_lds_dwordx4 v[204:205], off
	s_add_i32 m0, s29, 0x2000
	s_add_u32 s58, s58, 0x40080
	v_lshl_add_u64 v[204:205], v[246:247], 0, s[38:39]
	s_addc_u32 s59, s59, 0
	s_add_i32 s29, vcc_lo, s68
	global_load_lds_dwordx4 v[204:205], off
	v_lshl_add_u64 v[204:205], s[58:59], 0, v[180:181]
	s_mov_b32 m0, s29
	s_nop 0
	global_load_lds_dwordx4 v[204:205], off
	v_lshl_add_u64 v[204:205], s[58:59], 0, v[184:185]
	s_add_i32 m0, s29, 0x2000
	s_nop 0
	global_load_lds_dwordx4 v[204:205], off
	v_lshl_add_u64 v[204:205], v[248:249], 0, s[38:39]
	s_mov_b32 m0, s81
	s_nop 0
	global_load_lds_dwordx4 v[204:205], off
	v_lshl_add_u64 v[204:205], v[250:251], 0, s[38:39]
	s_mov_b32 m0, s82
	s_nop 0
	global_load_lds_dwordx4 v[204:205], off
	s_waitcnt vmcnt(8)
	s_waitcnt lgkmcnt(0)
	s_barrier
	s_setprio 3
	s_waitcnt lgkmcnt(0)
	v_mfma_f32_16x16x32_bf16 v[78:81], v[146:149], v[42:45], v[78:81]
	v_mfma_f32_16x16x32_bf16 v[74:77], v[154:157], v[42:45], v[74:77]
	v_mfma_f32_16x16x32_bf16 v[62:65], v[146:149], v[50:53], v[62:65]
	v_mfma_f32_16x16x32_bf16 v[58:61], v[154:157], v[50:53], v[58:61]
	v_mfma_f32_16x16x32_bf16 v[30:33], v[146:149], v[212:215], v[30:33]
	v_mfma_f32_16x16x32_bf16 v[26:29], v[154:157], v[212:215], v[26:29]
	v_mfma_f32_16x16x32_bf16 v[14:17], v[146:149], v[222:225], v[14:17]
	v_mfma_f32_16x16x32_bf16 v[10:13], v[154:157], v[222:225], v[10:13]
	v_mfma_f32_16x16x32_bf16 v[78:81], v[150:153], v[46:49], v[78:81]
	v_mfma_f32_16x16x32_bf16 v[74:77], v[158:161], v[46:49], v[74:77]
	v_mfma_f32_16x16x32_bf16 v[62:65], v[150:153], v[54:57], v[62:65]
	v_mfma_f32_16x16x32_bf16 v[58:61], v[158:161], v[54:57], v[58:61]
	v_mfma_f32_16x16x32_bf16 v[30:33], v[150:153], v[216:219], v[30:33]
	v_mfma_f32_16x16x32_bf16 v[26:29], v[158:161], v[216:219], v[26:29]
	v_mfma_f32_16x16x32_bf16 v[14:17], v[150:153], v[226:229], v[14:17]
	v_mfma_f32_16x16x32_bf16 v[10:13], v[158:161], v[226:229], v[10:13]
	s_setprio 0
	s_setprio 3
	v_mfma_f32_16x16x32_bf16 v[70:73], v[162:165], v[42:45], v[70:73]
	v_mfma_f32_16x16x32_bf16 v[42:45], v[170:173], v[42:45], v[66:69]
	v_mfma_f32_16x16x32_bf16 v[38:41], v[162:165], v[50:53], v[38:41]
	v_mfma_f32_16x16x32_bf16 v[34:37], v[170:173], v[50:53], v[34:37]
	v_mfma_f32_16x16x32_bf16 v[22:25], v[162:165], v[212:215], v[22:25]
	v_mfma_f32_16x16x32_bf16 v[18:21], v[170:173], v[212:215], v[18:21]
	v_mfma_f32_16x16x32_bf16 v[6:9], v[162:165], v[222:225], v[6:9]
	v_mfma_f32_16x16x32_bf16 v[2:5], v[170:173], v[222:225], v[2:5]
	v_mfma_f32_16x16x32_bf16 v[70:73], v[166:169], v[46:49], v[70:73]
	v_mfma_f32_16x16x32_bf16 v[66:69], v[174:177], v[46:49], v[42:45]
	v_mfma_f32_16x16x32_bf16 v[38:41], v[166:169], v[54:57], v[38:41]
	v_mfma_f32_16x16x32_bf16 v[34:37], v[174:177], v[54:57], v[34:37]
	v_mfma_f32_16x16x32_bf16 v[22:25], v[166:169], v[216:219], v[22:25]
	v_mfma_f32_16x16x32_bf16 v[18:21], v[174:177], v[216:219], v[18:21]
	v_mfma_f32_16x16x32_bf16 v[6:9], v[166:169], v[226:229], v[6:9]
	v_mfma_f32_16x16x32_bf16 v[2:5], v[174:177], v[226:229], v[2:5]
	s_setprio 0
	s_barrier
	s_add_i32 s29, s28, 2
	s_add_u32 s56, s56, 0x100
	s_addc_u32 s57, s57, 0
	s_cmp_gt_u32 s28, 13
	s_mov_b32 s28, s29
	s_cbranch_scc1 .LBB0_442
; #define PG8_STAGE(bufoff, gbase, voff) do { _Pragma("unroll") for (int _i = 0; _i < 2; ++_i) \
;         __builtin_amdgcn_global_load_lds((const unsigned*)((const char*)(gbase) + (voff)[_i]), (PG8_LAS unsigned*)(lds + (bufoff) + ldsw + _i * 8192), 16, 0, 0); } while (0)
; #define PG8_LDA(dst, b, h) do { _Pragma("unroll") for (int m = 0; m < 4; ++m) _Pragma("unroll") for (int k = 0; k < 2; ++k) dst[m][k] = *(const PG8_LAS bf16x8*)(lds + PG8_SA(b, h) + aoff + m * 2048 + k * 1024); } while (0)
; #define PG8_LDB(dst, b, h) do { _Pragma("unroll") for (int n = 0; n < 2; ++n) _Pragma("unroll") for (int k = 0; k < 2; ++k) dst[n][k] = *(const PG8_LAS bf16x8*)(lds + PG8_SB(b, h) + boff + n * 2048 + k * 1024); } while (0)
; #define PG8_MMA(ai, bj, At, Bt) do { __builtin_amdgcn_s_setprio(1); _Pragma("unroll") for (int m = 0; m < 4; ++m) _Pragma("unroll") for (int n = 0; n < 2; ++n) _Pragma("unroll") for (int k = 0; k < 2; ++k) \
;         acc[ai][bj][m][n] = __builtin_amdgcn_mfma_f32_16x16x32_bf16(Bt[n][k], At[m][k], acc[ai][bj][m][n], 0, 0, 0); __builtin_amdgcn_s_setprio(0); } while (0)
; #define PG8_WAIT_V(n) asm volatile("s_waitcnt vmcnt(" #n ")" ::: "memory")
; #define PG8_WAIT_L(n) asm volatile("s_waitcnt lgkmcnt(" #n ")" ::: "memory")
; #define PG8_BAR __builtin_amdgcn_s_barrier()
; #define PG8_SCHED __builtin_amdgcn_sched_barrier(0)
;     __device__ __forceinline__ void prefetch(const Unit& u, int wid, int lane) const { epi_prefetch(scr, ssq, bias + (size_t)(u.pm >> 5) * NGU + u.pn * BM, u, wid, lane); }
;     __device__ __forceinline__ void prefetch(const Unit& u, int wid, int lane) const { epi_prefetch(scr, ssq, bias + (size_t)(u.pm >> 5) * DIN + u.pn * BM, u, wid, lane); }
; template <class Epi, class Sched, bool ALIGN_EPI = false, bool SP2 = false>
; __device__ __forceinline__ void gemm_phase(PG8_LAS unsigned char* lds, const Gemm g, const Sched& S, const Epi& E) {
;     ...
;             PG8_LDB(B0, 0, 0); PG8_LDB(B1, 0, 1); PG8_SCHED; PG8_LDA(At, 0, 0); PG8_STAGE(PG8_SA(1, 1), a1 + hstep, voffA);
;             PG8_WAIT_V(8); PG8_WAIT_L(0); PG8_BAR; PG8_MMA(0, 0, At, B0); PG8_MMA(0, 1, At, B1); PG8_BAR; PG8_SCHED;
;             if constexpr (Epi::PREFETCH) { if (t == tpf) E.prefetch(cur, wid, lane); }
.LBB0_439:
	ds_read_b128 v[162:165], v208
	ds_read_b128 v[166:169], v208 offset:1024
	ds_read_b128 v[170:173], v208 offset:2048
	ds_read_b128 v[174:177], v208 offset:3072
	ds_read_b128 v[146:149], v209
	ds_read_b128 v[150:153], v209 offset:1024
	ds_read_b128 v[154:157], v209 offset:2048
	ds_read_b128 v[158:161], v209 offset:3072
	v_lshl_add_u64 v[42:43], v[196:197], 0, s[56:57]
	s_add_i32 m0, s69, 0xc000
	ds_read_b128 v[212:215], v210
	ds_read_b128 v[216:219], v210 offset:1024
	ds_read_b128 v[222:225], v210 offset:2048
	ds_read_b128 v[226:229], v210 offset:3072
	ds_read_b128 v[230:233], v210 offset:4096
	ds_read_b128 v[234:237], v210 offset:5120
	ds_read_b128 v[238:241], v210 offset:6144
	ds_read_b128 v[242:245], v210 offset:7168
	global_load_lds_dwordx4 v[42:43], off
	v_lshl_add_u64 v[42:43], v[198:199], 0, s[56:57]
	s_add_i32 m0, s69, 0xe000
	s_nop 0
	global_load_lds_dwordx4 v[42:43], off
	s_waitcnt vmcnt(8)
	s_waitcnt lgkmcnt(0)
	s_barrier
	s_setprio 3
	s_waitcnt lgkmcnt(0)
	v_mfma_f32_16x16x32_bf16 v[42:45], v[162:165], v[212:215], v[142:145]
	v_mfma_f32_16x16x32_bf16 v[46:49], v[170:173], v[212:215], v[138:141]
	v_mfma_f32_16x16x32_bf16 v[50:53], v[162:165], v[222:225], v[126:129]
	v_mfma_f32_16x16x32_bf16 v[54:57], v[170:173], v[222:225], v[122:125]
	v_mfma_f32_16x16x32_bf16 v[110:113], v[162:165], v[230:233], v[110:113]
	v_mfma_f32_16x16x32_bf16 v[106:109], v[170:173], v[230:233], v[106:109]
	v_mfma_f32_16x16x32_bf16 v[94:97], v[162:165], v[238:241], v[94:97]
	v_mfma_f32_16x16x32_bf16 v[90:93], v[170:173], v[238:241], v[90:93]
	v_mfma_f32_16x16x32_bf16 v[42:45], v[166:169], v[216:219], v[42:45]
	v_mfma_f32_16x16x32_bf16 v[46:49], v[174:177], v[216:219], v[46:49]
	v_mfma_f32_16x16x32_bf16 v[50:53], v[166:169], v[226:229], v[50:53]
	v_mfma_f32_16x16x32_bf16 v[54:57], v[174:177], v[226:229], v[54:57]
	v_mfma_f32_16x16x32_bf16 v[110:113], v[166:169], v[234:237], v[110:113]
	v_mfma_f32_16x16x32_bf16 v[106:109], v[174:177], v[234:237], v[106:109]
	v_mfma_f32_16x16x32_bf16 v[94:97], v[166:169], v[242:245], v[94:97]
	v_mfma_f32_16x16x32_bf16 v[90:93], v[174:177], v[242:245], v[90:93]
	s_setprio 0
	s_setprio 3
	v_mfma_f32_16x16x32_bf16 v[122:125], v[146:149], v[212:215], v[134:137]
	v_mfma_f32_16x16x32_bf16 v[134:137], v[150:153], v[216:219], v[122:125]
	v_mfma_f32_16x16x32_bf16 v[122:125], v[154:157], v[212:215], v[130:133]
	v_mfma_f32_16x16x32_bf16 v[118:121], v[146:149], v[222:225], v[118:121]
	v_mfma_f32_16x16x32_bf16 v[114:117], v[154:157], v[222:225], v[114:117]
	v_mfma_f32_16x16x32_bf16 v[102:105], v[146:149], v[230:233], v[102:105]
	v_mfma_f32_16x16x32_bf16 v[98:101], v[154:157], v[230:233], v[98:101]
	v_mfma_f32_16x16x32_bf16 v[86:89], v[146:149], v[238:241], v[86:89]
	v_mfma_f32_16x16x32_bf16 v[82:85], v[154:157], v[238:241], v[82:85]
	v_mfma_f32_16x16x32_bf16 v[130:133], v[158:161], v[216:219], v[122:125]
	v_mfma_f32_16x16x32_bf16 v[118:121], v[150:153], v[226:229], v[118:121]
	v_mfma_f32_16x16x32_bf16 v[114:117], v[158:161], v[226:229], v[114:117]
	v_mfma_f32_16x16x32_bf16 v[102:105], v[150:153], v[234:237], v[102:105]
	v_mfma_f32_16x16x32_bf16 v[98:101], v[158:161], v[234:237], v[98:101]
	v_mfma_f32_16x16x32_bf16 v[86:89], v[150:153], v[242:245], v[86:89]
	v_mfma_f32_16x16x32_bf16 v[82:85], v[158:161], v[242:245], v[82:85]
	s_setprio 0
	s_barrier
	s_cmp_lg_u32 s63, s28
	s_cbranch_scc1 .LBB0_438
	v_mov_b32_e32 v186, v207
	s_add_i32 m0, s62, 0x20000
	v_lshl_add_u64 v[122:123], s[52:53], 0, v[186:187]
	s_mov_b64 s[58:59], 0x400
	global_load_lds_dwordx4 v186, s[52:53]
	v_lshl_add_u64 v[122:123], v[122:123], 0, s[58:59]
	s_add_i32 m0, s62, 0x20400
	s_andn2_b64 vcc, exec, s[40:41]
	global_load_lds_dwordx4 v[122:123], off
	s_cbranch_vccnz .LBB0_438
	v_lshl_add_u64 v[122:123], s[54:55], 0, v[186:187]
	s_mov_b32 m0, s30
	s_nop 0
	global_load_lds_dwordx4 v[122:123], off
	s_branch .LBB0_438

; #define PG8_STAGE(bufoff, gbase, voff) do { _Pragma("unroll") for (int _i = 0; _i < 2; ++_i) \
;         __builtin_amdgcn_global_load_lds((const unsigned*)((const char*)(gbase) + (voff)[_i]), (PG8_LAS unsigned*)(lds + (bufoff) + ldsw + _i * 8192), 16, 0, 0); } while (0)
; #define PG8_LDA(dst, b, h) do { _Pragma("unroll") for (int m = 0; m < 4; ++m) _Pragma("unroll") for (int k = 0; k < 2; ++k) dst[m][k] = *(const PG8_LAS bf16x8*)(lds + PG8_SA(b, h) + aoff + m * 2048 + k * 1024); } while (0)
; #define PG8_LDB(dst, b, h) do { _Pragma("unroll") for (int n = 0; n < 2; ++n) _Pragma("unroll") for (int k = 0; k < 2; ++k) dst[n][k] = *(const PG8_LAS bf16x8*)(lds + PG8_SB(b, h) + boff + n * 2048 + k * 1024); } while (0)
; #define PG8_MMA(ai, bj, At, Bt) do { __builtin_amdgcn_s_setprio(1); _Pragma("unroll") for (int m = 0; m < 4; ++m) _Pragma("unroll") for (int n = 0; n < 2; ++n) _Pragma("unroll") for (int k = 0; k < 2; ++k) \
;         acc[ai][bj][m][n] = __builtin_amdgcn_mfma_f32_16x16x32_bf16(Bt[n][k], At[m][k], acc[ai][bj][m][n], 0, 0, 0); __builtin_amdgcn_s_setprio(0); } while (0)
; #define PG8_WAIT_V(n) asm volatile("s_waitcnt vmcnt(" #n ")" ::: "memory")
; #define PG8_WAIT_L(n) asm volatile("s_waitcnt lgkmcnt(" #n ")" ::: "memory")
; #define PG8_BAR __builtin_amdgcn_s_barrier()
; #define PG8_SCHED __builtin_amdgcn_sched_barrier(0)
; template <class Epi, class Sched, bool ALIGN_EPI = false, bool SP2 = false>
; __device__ __forceinline__ void gemm_phase(PG8_LAS unsigned char* lds, const Gemm g, const Sched& S, const Epi& E) {
;     ...
;             const char* a2 = last ? nA : cA + (size_t)(t + 2) * kstepA; const char* b2 = last ? nB : cB + (size_t)(t + 2) * kstep;
;             const char* a3 = a2 + kstepA; const char* b3 = b2 + kstep;
;             if (last && has_next) S.a_ready(nxt);
;             if constexpr (SP2) {
;             PG8_LDB(B0, 0, 0); PG8_LDB(B1, 0, 1); PG8_SCHED; PG8_LDA(At, 0, 0); PG8_STAGE(PG8_SA(1, 1), a1 + hstep, voffA);
;             PG8_WAIT_V(8); PG8_WAIT_L(0); PG8_BAR; PG8_MMA(0, 0, At, B0); PG8_MMA(0, 1, At, B1); PG8_BAR; PG8_SCHED;
;             if constexpr (Epi::PREFETCH) { if (t == tpf) E.prefetch(cur, wid, lane); }
;             PG8_LDA(At, 0, 1); PG8_STAGE(PG8_SB(0, 0), b2, voffB); PG8_STAGE(PG8_SB(0, 1), b2 + hstep, voffB); PG8_STAGE(PG8_SA(0, 0), a2, voffA);
.LBB0_723:
	v_add_u32_e32 v2, s67, v177
	ds_read_b128 v[134:137], v2
	ds_read_b128 v[138:141], v2 offset:1024
	ds_read_b128 v[142:145], v2 offset:2048
	ds_read_b128 v[146:149], v2 offset:3072
	v_add_u32_e32 v2, s68, v177
	ds_read_b128 v[150:153], v2
	ds_read_b128 v[170:173], v2 offset:1024
	ds_read_b128 v[180:183], v2 offset:2048
	ds_read_b128 v[184:187], v2 offset:3072
	s_add_u32 s28, s0, 0xfffc0080
	s_addc_u32 s29, s1, -1
	s_cmp_eq_u32 s43, 12
	s_cselect_b32 s37, s23, s29
	s_cselect_b32 s36, s39, s28
	s_cselect_b32 s29, s21, s42
	s_cselect_b32 s28, s40, s41
	v_lshl_add_u64 v[4:5], s[0:1], 0, v[162:163]
	s_add_i32 m0, s31, 0xc000
	ds_read_b128 v[188:191], v178
	ds_read_b128 v[192:195], v178 offset:1024
	ds_read_b128 v[196:199], v178 offset:2048
	ds_read_b128 v[200:203], v178 offset:3072
	ds_read_b128 v[204:207], v178 offset:4096
	ds_read_b128 v[208:211], v178 offset:5120
	ds_read_b128 v[212:215], v178 offset:6144
	ds_read_b128 v[216:219], v178 offset:7168
	global_load_lds_dwordx4 v[4:5], off
	v_lshl_add_u64 v[4:5], s[0:1], 0, v[164:165]
	s_add_i32 m0, s31, 0xe000
	s_nop 0
	global_load_lds_dwordx4 v[4:5], off
	s_waitcnt vmcnt(8)
	s_waitcnt lgkmcnt(0)
	s_barrier
	s_setprio 3
	s_waitcnt lgkmcnt(0)
	v_mfma_f32_16x16x32_bf16 v[130:133], v[134:137], v[188:191], v[130:133]
	v_mfma_f32_16x16x32_bf16 v[126:129], v[142:145], v[188:191], v[126:129]
	v_mfma_f32_16x16x32_bf16 v[122:125], v[134:137], v[196:199], v[122:125]
	v_mfma_f32_16x16x32_bf16 v[118:121], v[142:145], v[196:199], v[118:121]
	v_mfma_f32_16x16x32_bf16 v[114:117], v[134:137], v[204:207], v[114:117]
	v_mfma_f32_16x16x32_bf16 v[110:113], v[142:145], v[204:207], v[110:113]
	v_mfma_f32_16x16x32_bf16 v[106:109], v[134:137], v[212:215], v[106:109]
	v_mfma_f32_16x16x32_bf16 v[102:105], v[142:145], v[212:215], v[102:105]
	v_mfma_f32_16x16x32_bf16 v[130:133], v[138:141], v[192:195], v[130:133]
	v_mfma_f32_16x16x32_bf16 v[126:129], v[146:149], v[192:195], v[126:129]
	v_mfma_f32_16x16x32_bf16 v[122:125], v[138:141], v[200:203], v[122:125]
	v_mfma_f32_16x16x32_bf16 v[118:121], v[146:149], v[200:203], v[118:121]
	v_mfma_f32_16x16x32_bf16 v[114:117], v[138:141], v[208:211], v[114:117]
	v_mfma_f32_16x16x32_bf16 v[110:113], v[146:149], v[208:211], v[110:113]
	v_mfma_f32_16x16x32_bf16 v[106:109], v[138:141], v[216:219], v[106:109]
	v_mfma_f32_16x16x32_bf16 v[102:105], v[146:149], v[216:219], v[102:105]
	s_setprio 0
	s_setprio 3
	v_mfma_f32_16x16x32_bf16 v[98:101], v[150:153], v[188:191], v[98:101]
	v_mfma_f32_16x16x32_bf16 v[94:97], v[180:183], v[188:191], v[94:97]
	v_mfma_f32_16x16x32_bf16 v[90:93], v[150:153], v[196:199], v[90:93]
	v_mfma_f32_16x16x32_bf16 v[86:89], v[180:183], v[196:199], v[86:89]
	v_mfma_f32_16x16x32_bf16 v[82:85], v[150:153], v[204:207], v[82:85]
	v_mfma_f32_16x16x32_bf16 v[78:81], v[180:183], v[204:207], v[78:81]
	v_mfma_f32_16x16x32_bf16 v[74:77], v[150:153], v[212:215], v[74:77]
	v_mfma_f32_16x16x32_bf16 v[70:73], v[180:183], v[212:215], v[70:73]
	v_mfma_f32_16x16x32_bf16 v[98:101], v[170:173], v[192:195], v[98:101]
	v_mfma_f32_16x16x32_bf16 v[94:97], v[184:187], v[192:195], v[94:97]
	v_mfma_f32_16x16x32_bf16 v[90:93], v[170:173], v[200:203], v[90:93]
	v_mfma_f32_16x16x32_bf16 v[86:89], v[184:187], v[200:203], v[86:89]
	v_mfma_f32_16x16x32_bf16 v[82:85], v[170:173], v[208:211], v[82:85]
	v_mfma_f32_16x16x32_bf16 v[78:81], v[184:187], v[208:211], v[78:81]
	v_mfma_f32_16x16x32_bf16 v[74:77], v[170:173], v[216:219], v[74:77]
	v_mfma_f32_16x16x32_bf16 v[70:73], v[184:187], v[216:219], v[70:73]
	s_setprio 0
	s_barrier
	s_add_i32 s71, s67, s48
	v_lshl_add_u64 v[174:175], s[28:29], 0, v[156:157]
	s_mov_b32 m0, s71
	ds_read_b128 v[188:191], v178 offset:16384
	ds_read_b128 v[192:195], v178 offset:17408
	ds_read_b128 v[196:199], v178 offset:18432
	ds_read_b128 v[200:203], v178 offset:19456
	ds_read_b128 v[204:207], v178 offset:20480
	ds_read_b128 v[208:211], v178 offset:21504
	ds_read_b128 v[212:215], v178 offset:22528
	ds_read_b128 v[216:219], v178 offset:23552
	global_load_lds_dwordx4 v[174:175], off
	s_add_i32 m0, s71, 0x2000
	s_add_u32 s72, s28, 0x40000
	v_lshl_add_u64 v[222:223], s[28:29], 0, v[160:161]
	s_addc_u32 s73, s29, 0
	s_add_i32 s71, s68, s48
	global_load_lds_dwordx4 v[222:223], off
	v_lshl_add_u64 v[4:5], s[72:73], 0, v[156:157]
	s_mov_b32 m0, s71
	v_lshl_add_u64 v[224:225], s[36:37], 0, v[154:155]
	global_load_lds_dwordx4 v[4:5], off
	v_lshl_add_u64 v[4:5], s[72:73], 0, v[160:161]
	s_add_i32 m0, s71, 0x2000
	v_lshl_add_u64 v[226:227], s[36:37], 0, v[158:159]
	global_load_lds_dwordx4 v[4:5], off
	s_mov_b32 m0, s31
	s_nop 0
	global_load_lds_dwordx4 v[224:225], off
	s_mov_b32 m0, s35
	s_nop 0
	global_load_lds_dwordx4 v[226:227], off
	s_waitcnt vmcnt(8)
	s_waitcnt lgkmcnt(0)
	s_barrier
; #define PG8_STAGE(bufoff, gbase, voff) do { _Pragma("unroll") for (int _i = 0; _i < 2; ++_i) \
;         __builtin_amdgcn_global_load_lds((const unsigned*)((const char*)(gbase) + (voff)[_i]), (PG8_LAS unsigned*)(lds + (bufoff) + ldsw + _i * 8192), 16, 0, 0); } while (0)
; #define PG8_LDA(dst, b, h) do { _Pragma("unroll") for (int m = 0; m < 4; ++m) _Pragma("unroll") for (int k = 0; k < 2; ++k) dst[m][k] = *(const PG8_LAS bf16x8*)(lds + PG8_SA(b, h) + aoff + m * 2048 + k * 1024); } while (0)
; #define PG8_LDB(dst, b, h) do { _Pragma("unroll") for (int n = 0; n < 2; ++n) _Pragma("unroll") for (int k = 0; k < 2; ++k) dst[n][k] = *(const PG8_LAS bf16x8*)(lds + PG8_SB(b, h) + boff + n * 2048 + k * 1024); } while (0)
; #define PG8_MMA(ai, bj, At, Bt) do { __builtin_amdgcn_s_setprio(1); _Pragma("unroll") for (int m = 0; m < 4; ++m) _Pragma("unroll") for (int n = 0; n < 2; ++n) _Pragma("unroll") for (int k = 0; k < 2; ++k) \
;         acc[ai][bj][m][n] = __builtin_amdgcn_mfma_f32_16x16x32_bf16(Bt[n][k], At[m][k], acc[ai][bj][m][n], 0, 0, 0); __builtin_amdgcn_s_setprio(0); } while (0)
; #define PG8_WAIT_V(n) asm volatile("s_waitcnt vmcnt(" #n ")" ::: "memory")
; #define PG8_WAIT_L(n) asm volatile("s_waitcnt lgkmcnt(" #n ")" ::: "memory")
; #define PG8_BAR __builtin_amdgcn_s_barrier()
; #define PG8_SCHED __builtin_amdgcn_sched_barrier(0)
; template <class Epi, class Sched, bool ALIGN_EPI = false, bool SP2 = false>
; __device__ __forceinline__ void gemm_phase(PG8_LAS unsigned char* lds, const Gemm g, const Sched& S, const Epi& E) {
;     ...
;             PG8_LDA(At, 0, 1); PG8_STAGE(PG8_SB(0, 0), b2, voffB); PG8_STAGE(PG8_SB(0, 1), b2 + hstep, voffB); PG8_STAGE(PG8_SA(0, 0), a2, voffA);
;             PG8_WAIT_V(8); PG8_WAIT_L(0); PG8_BAR; PG8_MMA(1, 0, At, B0); PG8_MMA(1, 1, At, B1); PG8_BAR; PG8_SCHED;
;             PG8_LDB(B0, 1, 0); PG8_LDB(B1, 1, 1); PG8_SCHED; PG8_LDA(At, 1, 0); PG8_STAGE(PG8_SA(0, 1), a2 + hstep, voffA);
;             PG8_WAIT_V(8); PG8_WAIT_L(0); PG8_BAR; PG8_MMA(0, 0, At, B0); PG8_MMA(0, 1, At, B1); PG8_BAR; PG8_SCHED;
	s_setprio 3
	s_waitcnt lgkmcnt(0)
	v_mfma_f32_16x16x32_bf16 v[66:69], v[134:137], v[188:191], v[66:69]
	v_mfma_f32_16x16x32_bf16 v[62:65], v[142:145], v[188:191], v[62:65]
	v_mfma_f32_16x16x32_bf16 v[58:61], v[134:137], v[196:199], v[58:61]
	v_mfma_f32_16x16x32_bf16 v[54:57], v[142:145], v[196:199], v[54:57]
	v_mfma_f32_16x16x32_bf16 v[50:53], v[134:137], v[204:207], v[50:53]
	v_mfma_f32_16x16x32_bf16 v[46:49], v[142:145], v[204:207], v[46:49]
	v_mfma_f32_16x16x32_bf16 v[42:45], v[134:137], v[212:215], v[42:45]
	v_mfma_f32_16x16x32_bf16 v[38:41], v[142:145], v[212:215], v[38:41]
	v_mfma_f32_16x16x32_bf16 v[66:69], v[138:141], v[192:195], v[66:69]
	v_mfma_f32_16x16x32_bf16 v[62:65], v[146:149], v[192:195], v[62:65]
	v_mfma_f32_16x16x32_bf16 v[58:61], v[138:141], v[200:203], v[58:61]
	v_mfma_f32_16x16x32_bf16 v[54:57], v[146:149], v[200:203], v[54:57]
	v_mfma_f32_16x16x32_bf16 v[50:53], v[138:141], v[208:211], v[50:53]
	v_mfma_f32_16x16x32_bf16 v[46:49], v[146:149], v[208:211], v[46:49]
	v_mfma_f32_16x16x32_bf16 v[42:45], v[138:141], v[216:219], v[42:45]
	v_mfma_f32_16x16x32_bf16 v[38:41], v[146:149], v[216:219], v[38:41]
	s_setprio 0
	s_setprio 3
	v_mfma_f32_16x16x32_bf16 v[34:37], v[150:153], v[188:191], v[34:37]
	v_mfma_f32_16x16x32_bf16 v[30:33], v[180:183], v[188:191], v[30:33]
	v_mfma_f32_16x16x32_bf16 v[26:29], v[150:153], v[196:199], v[26:29]
	v_mfma_f32_16x16x32_bf16 v[22:25], v[180:183], v[196:199], v[22:25]
	v_mfma_f32_16x16x32_bf16 v[18:21], v[150:153], v[204:207], v[18:21]
	v_mfma_f32_16x16x32_bf16 v[14:17], v[180:183], v[204:207], v[14:17]
	v_mfma_f32_16x16x32_bf16 v[10:13], v[150:153], v[212:215], v[10:13]
	v_mfma_f32_16x16x32_bf16 v[4:7], v[180:183], v[212:215], v[6:9]
	v_mfma_f32_16x16x32_bf16 v[34:37], v[170:173], v[192:195], v[34:37]
	v_mfma_f32_16x16x32_bf16 v[30:33], v[184:187], v[192:195], v[30:33]
	v_mfma_f32_16x16x32_bf16 v[26:29], v[170:173], v[200:203], v[26:29]
	v_mfma_f32_16x16x32_bf16 v[22:25], v[184:187], v[200:203], v[22:25]
	v_mfma_f32_16x16x32_bf16 v[18:21], v[170:173], v[208:211], v[18:21]
	v_mfma_f32_16x16x32_bf16 v[14:17], v[184:187], v[208:211], v[14:17]
	v_mfma_f32_16x16x32_bf16 v[10:13], v[170:173], v[216:219], v[10:13]
	v_mfma_f32_16x16x32_bf16 v[4:7], v[184:187], v[216:219], v[4:7]
	s_setprio 0
	s_barrier
	s_add_i32 s71, 0, 0x18000
	v_add_u32_e32 v2, s71, v177
	s_add_i32 s72, 0, 0x1c000
	ds_read_b128 v[134:137], v2
	ds_read_b128 v[138:141], v2 offset:1024
	ds_read_b128 v[142:145], v2 offset:2048
	ds_read_b128 v[146:149], v2 offset:3072
	v_add_u32_e32 v2, s72, v177
	ds_read_b128 v[150:153], v2
	ds_read_b128 v[170:173], v2 offset:1024
	ds_read_b128 v[180:183], v2 offset:2048
	ds_read_b128 v[184:187], v2 offset:3072
	s_add_u32 s36, s36, 0x40000
	s_addc_u32 s37, s37, 0
	s_mov_b32 m0, s49
	v_lshl_add_u64 v[8:9], s[36:37], 0, v[154:155]
	ds_read_b128 v[188:191], v178 offset:32768
	ds_read_b128 v[192:195], v178 offset:33792
	ds_read_b128 v[196:199], v178 offset:34816
	ds_read_b128 v[200:203], v178 offset:35840
	ds_read_b128 v[204:207], v178 offset:36864
	ds_read_b128 v[208:211], v178 offset:37888
	ds_read_b128 v[212:215], v178 offset:38912
	ds_read_b128 v[216:219], v178 offset:39936
	global_load_lds_dwordx4 v[8:9], off
	v_lshl_add_u64 v[8:9], s[36:37], 0, v[158:159]
	s_mov_b32 m0, s50
	s_nop 0
	global_load_lds_dwordx4 v[8:9], off
	s_waitcnt vmcnt(8)
	s_waitcnt lgkmcnt(0)
	s_barrier
	s_setprio 3
	s_waitcnt lgkmcnt(0)
	v_mfma_f32_16x16x32_bf16 v[130:133], v[134:137], v[188:191], v[130:133]
	v_mfma_f32_16x16x32_bf16 v[126:129], v[142:145], v[188:191], v[126:129]
	v_mfma_f32_16x16x32_bf16 v[122:125], v[134:137], v[196:199], v[122:125]
	v_mfma_f32_16x16x32_bf16 v[118:121], v[142:145], v[196:199], v[118:121]
	v_mfma_f32_16x16x32_bf16 v[114:117], v[134:137], v[204:207], v[114:117]
	v_mfma_f32_16x16x32_bf16 v[110:113], v[142:145], v[204:207], v[110:113]
	v_mfma_f32_16x16x32_bf16 v[106:109], v[134:137], v[212:215], v[106:109]
	v_mfma_f32_16x16x32_bf16 v[102:105], v[142:145], v[212:215], v[102:105]
	v_mfma_f32_16x16x32_bf16 v[130:133], v[138:141], v[192:195], v[130:133]
	v_mfma_f32_16x16x32_bf16 v[126:129], v[146:149], v[192:195], v[126:129]
	v_mfma_f32_16x16x32_bf16 v[122:125], v[138:141], v[200:203], v[122:125]
	v_mfma_f32_16x16x32_bf16 v[118:121], v[146:149], v[200:203], v[118:121]
	v_mfma_f32_16x16x32_bf16 v[114:117], v[138:141], v[208:211], v[114:117]
	v_mfma_f32_16x16x32_bf16 v[110:113], v[146:149], v[208:211], v[110:113]
	v_mfma_f32_16x16x32_bf16 v[106:109], v[138:141], v[216:219], v[106:109]
	v_mfma_f32_16x16x32_bf16 v[102:105], v[146:149], v[216:219], v[102:105]
	s_setprio 0
	s_setprio 3
	v_mfma_f32_16x16x32_bf16 v[98:101], v[150:153], v[188:191], v[98:101]
	v_mfma_f32_16x16x32_bf16 v[94:97], v[180:183], v[188:191], v[94:97]
	v_mfma_f32_16x16x32_bf16 v[90:93], v[150:153], v[196:199], v[90:93]
	v_mfma_f32_16x16x32_bf16 v[86:89], v[180:183], v[196:199], v[86:89]
	v_mfma_f32_16x16x32_bf16 v[82:85], v[150:153], v[204:207], v[82:85]
	v_mfma_f32_16x16x32_bf16 v[78:81], v[180:183], v[204:207], v[78:81]
	v_mfma_f32_16x16x32_bf16 v[74:77], v[150:153], v[212:215], v[74:77]
	v_mfma_f32_16x16x32_bf16 v[70:73], v[180:183], v[212:215], v[70:73]
	v_mfma_f32_16x16x32_bf16 v[98:101], v[170:173], v[192:195], v[98:101]
	v_mfma_f32_16x16x32_bf16 v[94:97], v[184:187], v[192:195], v[94:97]
	v_mfma_f32_16x16x32_bf16 v[90:93], v[170:173], v[200:203], v[90:93]
	v_mfma_f32_16x16x32_bf16 v[86:89], v[184:187], v[200:203], v[86:89]
	v_mfma_f32_16x16x32_bf16 v[82:85], v[170:173], v[208:211], v[82:85]
	v_mfma_f32_16x16x32_bf16 v[78:81], v[184:187], v[208:211], v[78:81]
	v_mfma_f32_16x16x32_bf16 v[74:77], v[170:173], v[216:219], v[74:77]
	v_mfma_f32_16x16x32_bf16 v[70:73], v[184:187], v[216:219], v[70:73]
	s_setprio 0
	s_barrier
; #define PG8_STAGE(bufoff, gbase, voff) do { _Pragma("unroll") for (int _i = 0; _i < 2; ++_i) \
;         __builtin_amdgcn_global_load_lds((const unsigned*)((const char*)(gbase) + (voff)[_i]), (PG8_LAS unsigned*)(lds + (bufoff) + ldsw + _i * 8192), 16, 0, 0); } while (0)
; #define PG8_LDA(dst, b, h) do { _Pragma("unroll") for (int m = 0; m < 4; ++m) _Pragma("unroll") for (int k = 0; k < 2; ++k) dst[m][k] = *(const PG8_LAS bf16x8*)(lds + PG8_SA(b, h) + aoff + m * 2048 + k * 1024); } while (0)
; #define PG8_MMA(ai, bj, At, Bt) do { __builtin_amdgcn_s_setprio(1); _Pragma("unroll") for (int m = 0; m < 4; ++m) _Pragma("unroll") for (int n = 0; n < 2; ++n) _Pragma("unroll") for (int k = 0; k < 2; ++k) \
;         acc[ai][bj][m][n] = __builtin_amdgcn_mfma_f32_16x16x32_bf16(Bt[n][k], At[m][k], acc[ai][bj][m][n], 0, 0, 0); __builtin_amdgcn_s_setprio(0); } while (0)
; #define PG8_WAIT_V(n) asm volatile("s_waitcnt vmcnt(" #n ")" ::: "memory")
; #define PG8_WAIT_L(n) asm volatile("s_waitcnt lgkmcnt(" #n ")" ::: "memory")
; #define PG8_BAR __builtin_amdgcn_s_barrier()
; #define PG8_SCHED __builtin_amdgcn_sched_barrier(0)
; template <class Epi, class Sched, bool ALIGN_EPI = false, bool SP2 = false>
; __device__ __forceinline__ void gemm_phase(PG8_LAS unsigned char* lds, const Gemm g, const Sched& S, const Epi& E) {
;     ...
;             PG8_LDA(At, 1, 1); PG8_STAGE(PG8_SB(1, 0), b3, voffB); PG8_STAGE(PG8_SB(1, 1), b3 + hstep, voffB); PG8_STAGE(PG8_SA(1, 0), a3, voffA);
;             PG8_WAIT_V(8); PG8_WAIT_L(0); PG8_BAR; PG8_MMA(1, 0, At, B0); PG8_MMA(1, 1, At, B1); PG8_BAR; PG8_SCHED;
;     ...
;         if constexpr (ALIGN_EPI) { if (wr == 0) PG8_BAR; }
	s_add_i32 s36, s71, s48
	v_lshl_add_u64 v[8:9], v[174:175], 0, s[14:15]
	s_mov_b32 m0, s36
	ds_read_b128 v[188:191], v178 offset:49152
	ds_read_b128 v[192:195], v178 offset:50176
	ds_read_b128 v[196:199], v178 offset:51200
	ds_read_b128 v[200:203], v178 offset:52224
	ds_read_b128 v[204:207], v178 offset:53248
	ds_read_b128 v[208:211], v178 offset:54272
	ds_read_b128 v[212:215], v178 offset:55296
	ds_read_b128 v[216:219], v178 offset:56320
	global_load_lds_dwordx4 v[8:9], off
	s_add_i32 m0, s36, 0x2000
	s_add_u32 s28, s28, 0x40080
	v_lshl_add_u64 v[8:9], v[222:223], 0, s[14:15]
	s_addc_u32 s29, s29, 0
	s_add_i32 s36, s72, s48
	global_load_lds_dwordx4 v[8:9], off
	v_lshl_add_u64 v[8:9], s[28:29], 0, v[156:157]
	s_mov_b32 m0, s36
	s_nop 0
	global_load_lds_dwordx4 v[8:9], off
	v_lshl_add_u64 v[8:9], s[28:29], 0, v[160:161]
	s_add_i32 m0, s36, 0x2000
	s_nop 0
	global_load_lds_dwordx4 v[8:9], off
	v_lshl_add_u64 v[8:9], v[224:225], 0, s[14:15]
	s_mov_b32 m0, s58
	s_nop 0
	global_load_lds_dwordx4 v[8:9], off
	v_lshl_add_u64 v[8:9], v[226:227], 0, s[14:15]
	s_mov_b32 m0, s59
	s_nop 0
	global_load_lds_dwordx4 v[8:9], off
	s_waitcnt vmcnt(8)
	s_waitcnt lgkmcnt(0)
	s_barrier
	s_setprio 3
	s_waitcnt lgkmcnt(0)
	v_mfma_f32_16x16x32_bf16 v[66:69], v[134:137], v[188:191], v[66:69]
	v_mfma_f32_16x16x32_bf16 v[62:65], v[142:145], v[188:191], v[62:65]
	v_mfma_f32_16x16x32_bf16 v[58:61], v[134:137], v[196:199], v[58:61]
	v_mfma_f32_16x16x32_bf16 v[54:57], v[142:145], v[196:199], v[54:57]
	v_mfma_f32_16x16x32_bf16 v[50:53], v[134:137], v[204:207], v[50:53]
	v_mfma_f32_16x16x32_bf16 v[46:49], v[142:145], v[204:207], v[46:49]
	v_mfma_f32_16x16x32_bf16 v[42:45], v[134:137], v[212:215], v[42:45]
	v_mfma_f32_16x16x32_bf16 v[38:41], v[142:145], v[212:215], v[38:41]
	v_mfma_f32_16x16x32_bf16 v[66:69], v[138:141], v[192:195], v[66:69]
	v_mfma_f32_16x16x32_bf16 v[62:65], v[146:149], v[192:195], v[62:65]
	v_mfma_f32_16x16x32_bf16 v[58:61], v[138:141], v[200:203], v[58:61]
	v_mfma_f32_16x16x32_bf16 v[54:57], v[146:149], v[200:203], v[54:57]
	v_mfma_f32_16x16x32_bf16 v[50:53], v[138:141], v[208:211], v[50:53]
	v_mfma_f32_16x16x32_bf16 v[46:49], v[146:149], v[208:211], v[46:49]
	v_mfma_f32_16x16x32_bf16 v[42:45], v[138:141], v[216:219], v[42:45]
	v_mfma_f32_16x16x32_bf16 v[38:41], v[146:149], v[216:219], v[38:41]
	s_setprio 0
	s_setprio 3
	v_mfma_f32_16x16x32_bf16 v[34:37], v[150:153], v[188:191], v[34:37]
	v_mfma_f32_16x16x32_bf16 v[30:33], v[180:183], v[188:191], v[30:33]
	v_mfma_f32_16x16x32_bf16 v[26:29], v[150:153], v[196:199], v[26:29]
	v_mfma_f32_16x16x32_bf16 v[22:25], v[180:183], v[196:199], v[22:25]
	v_mfma_f32_16x16x32_bf16 v[18:21], v[150:153], v[204:207], v[18:21]
	v_mfma_f32_16x16x32_bf16 v[14:17], v[180:183], v[204:207], v[14:17]
	v_mfma_f32_16x16x32_bf16 v[8:11], v[150:153], v[212:215], v[10:13]
	v_mfma_f32_16x16x32_bf16 v[4:7], v[180:183], v[212:215], v[4:7]
	v_mfma_f32_16x16x32_bf16 v[34:37], v[170:173], v[192:195], v[34:37]
	v_mfma_f32_16x16x32_bf16 v[30:33], v[184:187], v[192:195], v[30:33]
	v_mfma_f32_16x16x32_bf16 v[26:29], v[170:173], v[200:203], v[26:29]
	v_mfma_f32_16x16x32_bf16 v[22:25], v[184:187], v[200:203], v[22:25]
	v_mfma_f32_16x16x32_bf16 v[18:21], v[170:173], v[208:211], v[18:21]
	v_mfma_f32_16x16x32_bf16 v[14:17], v[184:187], v[208:211], v[14:17]
	v_mfma_f32_16x16x32_bf16 v[10:13], v[170:173], v[216:219], v[8:11]
	v_mfma_f32_16x16x32_bf16 v[6:9], v[184:187], v[216:219], v[4:7]
	s_setprio 0
	s_barrier
	s_add_i32 s43, s43, 2
	s_add_u32 s0, s0, 0x100
	s_addc_u32 s1, s1, 0
	s_add_u32 s41, s41, 0x100
	s_addc_u32 s42, s42, 0
	s_cmp_gt_u32 s43, 13
	s_cbranch_scc0 .LBB0_723
	s_and_b64 vcc, exec, s[16:17]
	s_cbranch_vccz .LBB0_726
	s_barrier

;     __host__ __device__ bool next(int i, Unit& u) const { if (!b.next(i >> 1, u)) return false; u.sel = i & 1; return true; }
; #define PG8_STAGE(bufoff, gbase, voff) do { _Pragma("unroll") for (int _i = 0; _i < 2; ++_i) \
;         __builtin_amdgcn_global_load_lds((const unsigned*)((const char*)(gbase) + (voff)[_i]), (PG8_LAS unsigned*)(lds + (bufoff) + ldsw + _i * 8192), 16, 0, 0); } while (0)
; #define PG8_LDA(dst, b, h) do { _Pragma("unroll") for (int m = 0; m < 4; ++m) _Pragma("unroll") for (int k = 0; k < 2; ++k) dst[m][k] = *(const PG8_LAS bf16x8*)(lds + PG8_SA(b, h) + aoff + m * 2048 + k * 1024); } while (0)
; #define PG8_LDB(dst, b, h) do { _Pragma("unroll") for (int n = 0; n < 2; ++n) _Pragma("unroll") for (int k = 0; k < 2; ++k) dst[n][k] = *(const PG8_LAS bf16x8*)(lds + PG8_SB(b, h) + boff + n * 2048 + k * 1024); } while (0)
; #define PG8_WAIT_V(n) asm volatile("s_waitcnt vmcnt(" #n ")" ::: "memory")
; #define PG8_WAIT_L(n) asm volatile("s_waitcnt lgkmcnt(" #n ")" ::: "memory")
; #define PG8_BAR __builtin_amdgcn_s_barrier()
; #define PG8_SCHED __builtin_amdgcn_sched_barrier(0)
; template <class Epi, class Sched, bool ALIGN_EPI = false, bool SP2 = false>
; __device__ __forceinline__ void gemm_phase(PG8_LAS unsigned char* lds, const Gemm g, const Sched& S, const Epi& E) {
;     ...
;         const bool has_next = S.next(ui + 1, nxt);
;         const char* nA = has_next ? PG8_ABASE(nxt) : cA; const char* nB = has_next ? PG8_BBASE(nxt) : cB;
;         for (int t = 0; t < nt; t += 2) {
;             const bool last = (t == nt - 2);
;             const char* a1 = cA + (size_t)(t + 1) * kstepA;
;             const char* a2 = last ? nA : cA + (size_t)(t + 2) * kstepA; const char* b2 = last ? nB : cB + (size_t)(t + 2) * kstep;
;             const char* a3 = a2 + kstepA; const char* b3 = b2 + kstep;
;             if (last && has_next) S.a_ready(nxt);
;             if constexpr (SP2) {
;             PG8_LDB(B0, 0, 0); PG8_LDB(B1, 0, 1); PG8_SCHED; PG8_LDA(At, 0, 0); PG8_STAGE(PG8_SA(1, 1), a1 + hstep, voffA);
;             PG8_WAIT_V(8); PG8_WAIT_L(0); PG8_BAR; PG8_MMA(0, 0, At, B0); PG8_MMA(0, 1, At, B1); PG8_BAR; PG8_SCHED;
;             if constexpr (Epi::PREFETCH) { if (t == tpf) E.prefetch(cur, wid, lane); }
;             PG8_LDA(At, 0, 1); PG8_STAGE(PG8_SB(0, 0), b2, voffB); PG8_STAGE(PG8_SB(0, 1), b2 + hstep, voffB); PG8_STAGE(PG8_SA(0, 0), a2, voffA);
.LBB0_837:
	s_ashr_i32 s29, s28, 31
	s_lshl_b64 s[30:31], s[28:29], 19
	s_add_u32 s30, s46, s30
	s_addc_u32 s31, s47, s31
	s_and_b64 s[34:35], s[2:3], exec
	s_cselect_b32 s1, s31, s5
	s_cselect_b32 s29, s30, s4
	s_ashr_i32 s27, s26, 31
	s_lshl_b64 s[34:35], s[26:27], 19
	s_add_u32 s34, s48, s34
	s_addc_u32 s35, s49, s35
	s_and_b64 s[36:37], s[2:3], exec
	s_cselect_b32 s27, s35, s7
	s_cselect_b32 s38, s34, s6
	s_add_u32 s4, s4, 0x40080
	s_addc_u32 s5, s5, 0
	s_add_u32 s39, s6, 0x100
	s_addc_u32 s40, s7, 0
	s_mov_b32 s41, -2
	s_waitcnt lgkmcnt(0)
	ds_read_b128 v[50:53], v214
	ds_read_b128 v[54:57], v214 offset:1024
	ds_read_b128 v[66:69], v214 offset:2048
	ds_read_b128 v[70:73], v214 offset:3072
	ds_read_b128 v[146:149], v215
	ds_read_b128 v[150:153], v215 offset:1024
	ds_read_b128 v[172:175], v215 offset:2048
	ds_read_b128 v[176:179], v215 offset:3072
	s_add_u32 s6, s4, 0xfffc0080
	s_addc_u32 s7, s5, -1
	s_cmp_eq_u32 s41, 12
	s_cselect_b32 s37, s1, s7
	s_cselect_b32 s36, s29, s6
	s_cselect_b32 s7, s27, s40
	s_cselect_b32 s6, s38, s39
	v_lshl_add_u64 v[218:219], s[4:5], 0, v[164:165]
	s_add_i32 m0, s51, 0xc000
	ds_read_b128 v[180:183], v216
	ds_read_b128 v[184:187], v216 offset:1024
	ds_read_b128 v[188:191], v216 offset:2048
	ds_read_b128 v[192:195], v216 offset:3072
	ds_read_b128 v[196:199], v216 offset:4096
	ds_read_b128 v[200:203], v216 offset:5120
	ds_read_b128 v[204:207], v216 offset:6144
	ds_read_b128 v[208:211], v216 offset:7168
	global_load_lds_dwordx4 v[218:219], off
	v_lshl_add_u64 v[218:219], s[4:5], 0, v[166:167]
	s_add_i32 m0, s51, 0xe000
	s_nop 0
	global_load_lds_dwordx4 v[218:219], off
	s_waitcnt vmcnt(8)
	s_waitcnt lgkmcnt(0)
	s_barrier
	s_setprio 3
	s_waitcnt lgkmcnt(0)
	v_mfma_f32_16x16x32_bf16 v[142:145], v[50:53], v[180:183], 0
	v_mfma_f32_16x16x32_bf16 v[138:141], v[66:69], v[180:183], 0
	v_mfma_f32_16x16x32_bf16 v[126:129], v[50:53], v[188:191], 0
	v_mfma_f32_16x16x32_bf16 v[122:125], v[66:69], v[188:191], 0
	v_mfma_f32_16x16x32_bf16 v[110:113], v[50:53], v[196:199], 0
	v_mfma_f32_16x16x32_bf16 v[106:109], v[66:69], v[196:199], 0
	v_mfma_f32_16x16x32_bf16 v[94:97], v[50:53], v[204:207], 0
	v_mfma_f32_16x16x32_bf16 v[90:93], v[66:69], v[204:207], 0
	v_mfma_f32_16x16x32_bf16 v[142:145], v[54:57], v[184:187], v[142:145]
	v_mfma_f32_16x16x32_bf16 v[138:141], v[70:73], v[184:187], v[138:141]
	v_mfma_f32_16x16x32_bf16 v[126:129], v[54:57], v[192:195], v[126:129]
	v_mfma_f32_16x16x32_bf16 v[122:125], v[70:73], v[192:195], v[122:125]
	v_mfma_f32_16x16x32_bf16 v[110:113], v[54:57], v[200:203], v[110:113]
	v_mfma_f32_16x16x32_bf16 v[106:109], v[70:73], v[200:203], v[106:109]
	v_mfma_f32_16x16x32_bf16 v[94:97], v[54:57], v[208:211], v[94:97]
	v_mfma_f32_16x16x32_bf16 v[90:93], v[70:73], v[208:211], v[90:93]
	s_setprio 0
	s_setprio 3
	v_mfma_f32_16x16x32_bf16 v[134:137], v[146:149], v[180:183], 0
	v_mfma_f32_16x16x32_bf16 v[130:133], v[172:175], v[180:183], 0
	v_mfma_f32_16x16x32_bf16 v[118:121], v[146:149], v[188:191], 0
	v_mfma_f32_16x16x32_bf16 v[114:117], v[172:175], v[188:191], 0
	v_mfma_f32_16x16x32_bf16 v[102:105], v[146:149], v[196:199], 0
	v_mfma_f32_16x16x32_bf16 v[98:101], v[172:175], v[196:199], 0
	v_mfma_f32_16x16x32_bf16 v[86:89], v[146:149], v[204:207], 0
	v_mfma_f32_16x16x32_bf16 v[82:85], v[172:175], v[204:207], 0
	v_mfma_f32_16x16x32_bf16 v[134:137], v[150:153], v[184:187], v[134:137]
	v_mfma_f32_16x16x32_bf16 v[130:133], v[176:179], v[184:187], v[130:133]
	v_mfma_f32_16x16x32_bf16 v[118:121], v[150:153], v[192:195], v[118:121]
	v_mfma_f32_16x16x32_bf16 v[114:117], v[176:179], v[192:195], v[114:117]
	v_mfma_f32_16x16x32_bf16 v[102:105], v[150:153], v[200:203], v[102:105]
	v_mfma_f32_16x16x32_bf16 v[98:101], v[176:179], v[200:203], v[98:101]
	v_mfma_f32_16x16x32_bf16 v[86:89], v[150:153], v[208:211], v[86:89]
	v_mfma_f32_16x16x32_bf16 v[82:85], v[176:179], v[208:211], v[82:85]
	s_setprio 0
	s_barrier
	s_add_i32 s42, s68, s50
	v_lshl_add_u64 v[218:219], s[6:7], 0, v[156:157]
	s_mov_b32 m0, s42
	ds_read_b128 v[180:183], v216 offset:16384
	ds_read_b128 v[184:187], v216 offset:17408
	ds_read_b128 v[188:191], v216 offset:18432
	ds_read_b128 v[192:195], v216 offset:19456
	ds_read_b128 v[196:199], v216 offset:20480
	ds_read_b128 v[200:203], v216 offset:21504
	ds_read_b128 v[204:207], v216 offset:22528
	ds_read_b128 v[208:211], v216 offset:23552
	global_load_lds_dwordx4 v[218:219], off
	s_add_i32 m0, s42, 0x2000
	s_add_u32 s42, s6, 0x40000
	v_lshl_add_u64 v[222:223], s[6:7], 0, v[160:161]
	s_addc_u32 s43, s7, 0
	s_add_i32 s44, s69, s50
	global_load_lds_dwordx4 v[222:223], off
	v_lshl_add_u64 v[224:225], s[42:43], 0, v[156:157]
	s_mov_b32 m0, s44
	v_lshl_add_u64 v[226:227], s[36:37], 0, v[158:159]
	global_load_lds_dwordx4 v[224:225], off
	v_lshl_add_u64 v[224:225], s[42:43], 0, v[160:161]
	s_add_i32 m0, s44, 0x2000
	s_nop 0
	global_load_lds_dwordx4 v[224:225], off
	v_lshl_add_u64 v[224:225], s[36:37], 0, v[154:155]
	s_mov_b32 m0, s51
	s_nop 0
	global_load_lds_dwordx4 v[224:225], off
	s_mov_b32 m0, s52
	s_nop 0
	global_load_lds_dwordx4 v[226:227], off
	s_waitcnt vmcnt(8)
	s_waitcnt lgkmcnt(0)
	s_barrier
; #define PG8_STAGE(bufoff, gbase, voff) do { _Pragma("unroll") for (int _i = 0; _i < 2; ++_i) \
;         __builtin_amdgcn_global_load_lds((const unsigned*)((const char*)(gbase) + (voff)[_i]), (PG8_LAS unsigned*)(lds + (bufoff) + ldsw + _i * 8192), 16, 0, 0); } while (0)
; #define PG8_LDA(dst, b, h) do { _Pragma("unroll") for (int m = 0; m < 4; ++m) _Pragma("unroll") for (int k = 0; k < 2; ++k) dst[m][k] = *(const PG8_LAS bf16x8*)(lds + PG8_SA(b, h) + aoff + m * 2048 + k * 1024); } while (0)
; #define PG8_LDB(dst, b, h) do { _Pragma("unroll") for (int n = 0; n < 2; ++n) _Pragma("unroll") for (int k = 0; k < 2; ++k) dst[n][k] = *(const PG8_LAS bf16x8*)(lds + PG8_SB(b, h) + boff + n * 2048 + k * 1024); } while (0)
; #define PG8_MMA(ai, bj, At, Bt) do { __builtin_amdgcn_s_setprio(1); _Pragma("unroll") for (int m = 0; m < 4; ++m) _Pragma("unroll") for (int n = 0; n < 2; ++n) _Pragma("unroll") for (int k = 0; k < 2; ++k) \
;         acc[ai][bj][m][n] = __builtin_amdgcn_mfma_f32_16x16x32_bf16(Bt[n][k], At[m][k], acc[ai][bj][m][n], 0, 0, 0); __builtin_amdgcn_s_setprio(0); } while (0)
; #define PG8_WAIT_V(n) asm volatile("s_waitcnt vmcnt(" #n ")" ::: "memory")
; #define PG8_WAIT_L(n) asm volatile("s_waitcnt lgkmcnt(" #n ")" ::: "memory")
; #define PG8_BAR __builtin_amdgcn_s_barrier()
; #define PG8_SCHED __builtin_amdgcn_sched_barrier(0)
;     __device__ __forceinline__ void prefetch(const Unit& u, int wid, int lane) const { epi_prefetch(scr, ssq, bias + (size_t)(u.pm >> 5) * NGU + u.pn * BM, u, wid, lane); }
; template <class Epi, class Sched, bool ALIGN_EPI = false, bool SP2 = false>
; __device__ __forceinline__ void gemm_phase(PG8_LAS unsigned char* lds, const Gemm g, const Sched& S, const Epi& E) {
;     ...
;             PG8_LDB(B0, 0, 0); PG8_LDB(B1, 0, 1); PG8_SCHED; PG8_LDA(At, 0, 0); PG8_STAGE(PG8_SA(1, 1), a1 + hstep, voffA);
;             PG8_WAIT_V(8); PG8_WAIT_L(0); PG8_BAR; PG8_MMA(0, 0, At, B0); PG8_MMA(0, 1, At, B1); PG8_BAR; PG8_SCHED;
;             if constexpr (Epi::PREFETCH) { if (t == tpf) E.prefetch(cur, wid, lane); }
;             PG8_LDA(At, 0, 1); PG8_STAGE(PG8_SB(0, 0), b2, voffB); PG8_STAGE(PG8_SB(0, 1), b2 + hstep, voffB); PG8_STAGE(PG8_SA(0, 0), a2, voffA);
;             PG8_WAIT_V(8); PG8_WAIT_L(0); PG8_BAR; PG8_MMA(1, 0, At, B0); PG8_MMA(1, 1, At, B1); PG8_BAR; PG8_SCHED;
	s_setprio 3
	s_waitcnt lgkmcnt(0)
	v_mfma_f32_16x16x32_bf16 v[78:81], v[50:53], v[180:183], 0
	v_mfma_f32_16x16x32_bf16 v[74:77], v[66:69], v[180:183], 0
	v_mfma_f32_16x16x32_bf16 v[46:49], v[50:53], v[188:191], 0
	v_mfma_f32_16x16x32_bf16 v[42:45], v[66:69], v[188:191], 0
	v_mfma_f32_16x16x32_bf16 v[30:33], v[50:53], v[196:199], 0
	v_mfma_f32_16x16x32_bf16 v[26:29], v[66:69], v[196:199], 0
	v_mfma_f32_16x16x32_bf16 v[14:17], v[50:53], v[204:207], 0
	v_mfma_f32_16x16x32_bf16 v[10:13], v[66:69], v[204:207], 0
	v_mfma_f32_16x16x32_bf16 v[78:81], v[54:57], v[184:187], v[78:81]
	v_mfma_f32_16x16x32_bf16 v[74:77], v[70:73], v[184:187], v[74:77]
	v_mfma_f32_16x16x32_bf16 v[46:49], v[54:57], v[192:195], v[46:49]
	v_mfma_f32_16x16x32_bf16 v[42:45], v[70:73], v[192:195], v[42:45]
	v_mfma_f32_16x16x32_bf16 v[30:33], v[54:57], v[200:203], v[30:33]
	v_mfma_f32_16x16x32_bf16 v[26:29], v[70:73], v[200:203], v[26:29]
	v_mfma_f32_16x16x32_bf16 v[14:17], v[54:57], v[208:211], v[14:17]
	v_mfma_f32_16x16x32_bf16 v[10:13], v[70:73], v[208:211], v[10:13]
	s_setprio 0
	s_setprio 3
	v_mfma_f32_16x16x32_bf16 v[38:41], v[146:149], v[188:191], 0
	v_mfma_f32_16x16x32_bf16 v[34:37], v[172:175], v[188:191], 0
	v_mfma_f32_16x16x32_bf16 v[22:25], v[146:149], v[196:199], 0
	v_mfma_f32_16x16x32_bf16 v[18:21], v[172:175], v[196:199], 0
	v_mfma_f32_16x16x32_bf16 v[6:9], v[146:149], v[204:207], 0
	v_mfma_f32_16x16x32_bf16 v[2:5], v[172:175], v[204:207], 0
	v_mfma_f32_16x16x32_bf16 v[50:53], v[146:149], v[180:183], 0
	v_mfma_f32_16x16x32_bf16 v[54:57], v[172:175], v[180:183], 0
	v_mfma_f32_16x16x32_bf16 v[38:41], v[150:153], v[192:195], v[38:41]
	v_mfma_f32_16x16x32_bf16 v[34:37], v[176:179], v[192:195], v[34:37]
	v_mfma_f32_16x16x32_bf16 v[22:25], v[150:153], v[200:203], v[22:25]
	v_mfma_f32_16x16x32_bf16 v[18:21], v[176:179], v[200:203], v[18:21]
	v_mfma_f32_16x16x32_bf16 v[6:9], v[150:153], v[208:211], v[6:9]
	v_mfma_f32_16x16x32_bf16 v[2:5], v[176:179], v[208:211], v[2:5]
	v_mfma_f32_16x16x32_bf16 v[50:53], v[150:153], v[184:187], v[50:53]
	v_mfma_f32_16x16x32_bf16 v[54:57], v[176:179], v[184:187], v[54:57]
	s_setprio 0
	s_barrier
	s_branch .Lpz4_mid
.LBB0_838:
	ds_read_b128 v[50:53], v214
	ds_read_b128 v[54:57], v214 offset:1024
	ds_read_b128 v[66:69], v214 offset:2048
	ds_read_b128 v[70:73], v214 offset:3072
	ds_read_b128 v[146:149], v215
	ds_read_b128 v[150:153], v215 offset:1024
	ds_read_b128 v[172:175], v215 offset:2048
	ds_read_b128 v[176:179], v215 offset:3072
	s_add_u32 s6, s4, 0xfffc0080
	s_addc_u32 s7, s5, -1
	s_cmp_eq_u32 s41, 12
	s_cselect_b32 s37, s1, s7
	s_cselect_b32 s36, s29, s6
	s_cselect_b32 s7, s27, s40
	s_cselect_b32 s6, s38, s39
	v_lshl_add_u64 v[218:219], s[4:5], 0, v[164:165]
	s_add_i32 m0, s51, 0xc000
	ds_read_b128 v[180:183], v216
	ds_read_b128 v[184:187], v216 offset:1024
	ds_read_b128 v[188:191], v216 offset:2048
	ds_read_b128 v[192:195], v216 offset:3072
	ds_read_b128 v[196:199], v216 offset:4096
	ds_read_b128 v[200:203], v216 offset:5120
	ds_read_b128 v[204:207], v216 offset:6144
	ds_read_b128 v[208:211], v216 offset:7168
	global_load_lds_dwordx4 v[218:219], off
	v_lshl_add_u64 v[218:219], s[4:5], 0, v[166:167]
	s_add_i32 m0, s51, 0xe000
	s_nop 0
	global_load_lds_dwordx4 v[218:219], off
	s_waitcnt vmcnt(8)
	s_waitcnt lgkmcnt(0)
	s_barrier
	s_setprio 3
	s_waitcnt lgkmcnt(0)
	v_mfma_f32_16x16x32_bf16 v[142:145], v[50:53], v[180:183], v[142:145]
	v_mfma_f32_16x16x32_bf16 v[138:141], v[66:69], v[180:183], v[138:141]
	v_mfma_f32_16x16x32_bf16 v[126:129], v[50:53], v[188:191], v[126:129]
	v_mfma_f32_16x16x32_bf16 v[122:125], v[66:69], v[188:191], v[122:125]
	v_mfma_f32_16x16x32_bf16 v[110:113], v[50:53], v[196:199], v[110:113]
	v_mfma_f32_16x16x32_bf16 v[106:109], v[66:69], v[196:199], v[106:109]
	v_mfma_f32_16x16x32_bf16 v[94:97], v[50:53], v[204:207], v[94:97]
	v_mfma_f32_16x16x32_bf16 v[90:93], v[66:69], v[204:207], v[90:93]
	v_mfma_f32_16x16x32_bf16 v[142:145], v[54:57], v[184:187], v[142:145]
	v_mfma_f32_16x16x32_bf16 v[138:141], v[70:73], v[184:187], v[138:141]
	v_mfma_f32_16x16x32_bf16 v[126:129], v[54:57], v[192:195], v[126:129]
	v_mfma_f32_16x16x32_bf16 v[122:125], v[70:73], v[192:195], v[122:125]
	v_mfma_f32_16x16x32_bf16 v[110:113], v[54:57], v[200:203], v[110:113]
	v_mfma_f32_16x16x32_bf16 v[106:109], v[70:73], v[200:203], v[106:109]
	v_mfma_f32_16x16x32_bf16 v[94:97], v[54:57], v[208:211], v[94:97]
	v_mfma_f32_16x16x32_bf16 v[90:93], v[70:73], v[208:211], v[90:93]
	s_setprio 0
	s_setprio 3
	v_mfma_f32_16x16x32_bf16 v[134:137], v[146:149], v[180:183], v[134:137]
	v_mfma_f32_16x16x32_bf16 v[130:133], v[172:175], v[180:183], v[130:133]
	v_mfma_f32_16x16x32_bf16 v[118:121], v[146:149], v[188:191], v[118:121]
	v_mfma_f32_16x16x32_bf16 v[114:117], v[172:175], v[188:191], v[114:117]
	v_mfma_f32_16x16x32_bf16 v[102:105], v[146:149], v[196:199], v[102:105]
	v_mfma_f32_16x16x32_bf16 v[98:101], v[172:175], v[196:199], v[98:101]
	v_mfma_f32_16x16x32_bf16 v[86:89], v[146:149], v[204:207], v[86:89]
	v_mfma_f32_16x16x32_bf16 v[82:85], v[172:175], v[204:207], v[82:85]
	v_mfma_f32_16x16x32_bf16 v[134:137], v[150:153], v[184:187], v[134:137]
	v_mfma_f32_16x16x32_bf16 v[130:133], v[176:179], v[184:187], v[130:133]
	v_mfma_f32_16x16x32_bf16 v[118:121], v[150:153], v[192:195], v[118:121]
	v_mfma_f32_16x16x32_bf16 v[114:117], v[176:179], v[192:195], v[114:117]
	v_mfma_f32_16x16x32_bf16 v[102:105], v[150:153], v[200:203], v[102:105]
	v_mfma_f32_16x16x32_bf16 v[98:101], v[176:179], v[200:203], v[98:101]
	v_mfma_f32_16x16x32_bf16 v[86:89], v[150:153], v[208:211], v[86:89]
	v_mfma_f32_16x16x32_bf16 v[82:85], v[176:179], v[208:211], v[82:85]
	s_setprio 0
	s_barrier
; #define PG8_STAGE(bufoff, gbase, voff) do { _Pragma("unroll") for (int _i = 0; _i < 2; ++_i) \
;         __builtin_amdgcn_global_load_lds((const unsigned*)((const char*)(gbase) + (voff)[_i]), (PG8_LAS unsigned*)(lds + (bufoff) + ldsw + _i * 8192), 16, 0, 0); } while (0)
; #define PG8_LDA(dst, b, h) do { _Pragma("unroll") for (int m = 0; m < 4; ++m) _Pragma("unroll") for (int k = 0; k < 2; ++k) dst[m][k] = *(const PG8_LAS bf16x8*)(lds + PG8_SA(b, h) + aoff + m * 2048 + k * 1024); } while (0)
; #define PG8_LDB(dst, b, h) do { _Pragma("unroll") for (int n = 0; n < 2; ++n) _Pragma("unroll") for (int k = 0; k < 2; ++k) dst[n][k] = *(const PG8_LAS bf16x8*)(lds + PG8_SB(b, h) + boff + n * 2048 + k * 1024); } while (0)
; #define PG8_MMA(ai, bj, At, Bt) do { __builtin_amdgcn_s_setprio(1); _Pragma("unroll") for (int m = 0; m < 4; ++m) _Pragma("unroll") for (int n = 0; n < 2; ++n) _Pragma("unroll") for (int k = 0; k < 2; ++k) \
;         acc[ai][bj][m][n] = __builtin_amdgcn_mfma_f32_16x16x32_bf16(Bt[n][k], At[m][k], acc[ai][bj][m][n], 0, 0, 0); __builtin_amdgcn_s_setprio(0); } while (0)
; #define PG8_WAIT_V(n) asm volatile("s_waitcnt vmcnt(" #n ")" ::: "memory")
; #define PG8_WAIT_L(n) asm volatile("s_waitcnt lgkmcnt(" #n ")" ::: "memory")
; #define PG8_BAR __builtin_amdgcn_s_barrier()
; #define PG8_SCHED __builtin_amdgcn_sched_barrier(0)
; template <class Epi, class Sched, bool ALIGN_EPI = false, bool SP2 = false>
; __device__ __forceinline__ void gemm_phase(PG8_LAS unsigned char* lds, const Gemm g, const Sched& S, const Epi& E) {
;     ...
;             PG8_LDA(At, 0, 1); PG8_STAGE(PG8_SB(0, 0), b2, voffB); PG8_STAGE(PG8_SB(0, 1), b2 + hstep, voffB); PG8_STAGE(PG8_SA(0, 0), a2, voffA);
;             PG8_WAIT_V(8); PG8_WAIT_L(0); PG8_BAR; PG8_MMA(1, 0, At, B0); PG8_MMA(1, 1, At, B1); PG8_BAR; PG8_SCHED;
;             PG8_LDB(B0, 1, 0); PG8_LDB(B1, 1, 1); PG8_SCHED; PG8_LDA(At, 1, 0); PG8_STAGE(PG8_SA(0, 1), a2 + hstep, voffA);
	s_add_i32 s42, s68, s50
	v_lshl_add_u64 v[218:219], s[6:7], 0, v[156:157]
	s_mov_b32 m0, s42
	ds_read_b128 v[180:183], v216 offset:16384
	ds_read_b128 v[184:187], v216 offset:17408
	ds_read_b128 v[188:191], v216 offset:18432
	ds_read_b128 v[192:195], v216 offset:19456
	ds_read_b128 v[196:199], v216 offset:20480
	ds_read_b128 v[200:203], v216 offset:21504
	ds_read_b128 v[204:207], v216 offset:22528
	ds_read_b128 v[208:211], v216 offset:23552
	global_load_lds_dwordx4 v[218:219], off
	s_add_i32 m0, s42, 0x2000
	s_add_u32 s42, s6, 0x40000
	v_lshl_add_u64 v[222:223], s[6:7], 0, v[160:161]
	s_addc_u32 s43, s7, 0
	s_add_i32 s44, s69, s50
	global_load_lds_dwordx4 v[222:223], off
	v_lshl_add_u64 v[224:225], s[42:43], 0, v[156:157]
	s_mov_b32 m0, s44
	v_lshl_add_u64 v[226:227], s[36:37], 0, v[158:159]
	global_load_lds_dwordx4 v[224:225], off
	v_lshl_add_u64 v[224:225], s[42:43], 0, v[160:161]
	s_add_i32 m0, s44, 0x2000
	s_nop 0
	global_load_lds_dwordx4 v[224:225], off
	v_lshl_add_u64 v[224:225], s[36:37], 0, v[154:155]
	s_mov_b32 m0, s51
	s_nop 0
	global_load_lds_dwordx4 v[224:225], off
	s_mov_b32 m0, s52
	s_nop 0
	global_load_lds_dwordx4 v[226:227], off
	s_waitcnt vmcnt(8)
	s_waitcnt lgkmcnt(0)
	s_barrier
	s_setprio 3
	s_waitcnt lgkmcnt(0)
	v_mfma_f32_16x16x32_bf16 v[78:81], v[50:53], v[180:183], v[78:81]
	v_mfma_f32_16x16x32_bf16 v[74:77], v[66:69], v[180:183], v[74:77]
	v_mfma_f32_16x16x32_bf16 v[46:49], v[50:53], v[188:191], v[46:49]
	v_mfma_f32_16x16x32_bf16 v[42:45], v[66:69], v[188:191], v[42:45]
	v_mfma_f32_16x16x32_bf16 v[30:33], v[50:53], v[196:199], v[30:33]
	v_mfma_f32_16x16x32_bf16 v[26:29], v[66:69], v[196:199], v[26:29]
	v_mfma_f32_16x16x32_bf16 v[14:17], v[50:53], v[204:207], v[14:17]
	v_mfma_f32_16x16x32_bf16 v[10:13], v[66:69], v[204:207], v[10:13]
	v_mfma_f32_16x16x32_bf16 v[78:81], v[54:57], v[184:187], v[78:81]
	v_mfma_f32_16x16x32_bf16 v[74:77], v[70:73], v[184:187], v[74:77]
	v_mfma_f32_16x16x32_bf16 v[46:49], v[54:57], v[192:195], v[46:49]
	v_mfma_f32_16x16x32_bf16 v[42:45], v[70:73], v[192:195], v[42:45]
	v_mfma_f32_16x16x32_bf16 v[30:33], v[54:57], v[200:203], v[30:33]
	v_mfma_f32_16x16x32_bf16 v[26:29], v[70:73], v[200:203], v[26:29]
	v_mfma_f32_16x16x32_bf16 v[14:17], v[54:57], v[208:211], v[14:17]
	v_mfma_f32_16x16x32_bf16 v[10:13], v[70:73], v[208:211], v[10:13]
	s_setprio 0
	s_setprio 3
	v_mfma_f32_16x16x32_bf16 v[38:41], v[146:149], v[188:191], v[38:41]
	v_mfma_f32_16x16x32_bf16 v[34:37], v[172:175], v[188:191], v[34:37]
	v_mfma_f32_16x16x32_bf16 v[22:25], v[146:149], v[196:199], v[22:25]
	v_mfma_f32_16x16x32_bf16 v[18:21], v[172:175], v[196:199], v[18:21]
	v_mfma_f32_16x16x32_bf16 v[6:9], v[146:149], v[204:207], v[6:9]
	v_mfma_f32_16x16x32_bf16 v[2:5], v[172:175], v[204:207], v[2:5]
	v_mfma_f32_16x16x32_bf16 v[50:53], v[146:149], v[180:183], v[62:65]
	v_mfma_f32_16x16x32_bf16 v[54:57], v[172:175], v[180:183], v[58:61]
	v_mfma_f32_16x16x32_bf16 v[38:41], v[150:153], v[192:195], v[38:41]
	v_mfma_f32_16x16x32_bf16 v[34:37], v[176:179], v[192:195], v[34:37]
	v_mfma_f32_16x16x32_bf16 v[22:25], v[150:153], v[200:203], v[22:25]
	v_mfma_f32_16x16x32_bf16 v[18:21], v[176:179], v[200:203], v[18:21]
	v_mfma_f32_16x16x32_bf16 v[6:9], v[150:153], v[208:211], v[6:9]
	v_mfma_f32_16x16x32_bf16 v[2:5], v[176:179], v[208:211], v[2:5]
	v_mfma_f32_16x16x32_bf16 v[50:53], v[150:153], v[184:187], v[50:53]
	v_mfma_f32_16x16x32_bf16 v[54:57], v[176:179], v[184:187], v[54:57]
	s_setprio 0
	s_barrier
.Lpz4_mid:
	s_add_i32 s42, 0, 0x18000
	s_add_i32 s43, 0, 0x1c000
	v_add_u32_e32 v70, s42, v213
	v_add_u32_e32 v162, s43, v213
	ds_read_b128 v[58:61], v70
	ds_read_b128 v[62:65], v70 offset:1024
	ds_read_b128 v[66:69], v70 offset:2048
	ds_read_b128 v[70:73], v70 offset:3072
	ds_read_b128 v[146:149], v162
	ds_read_b128 v[150:153], v162 offset:1024
	ds_read_b128 v[172:175], v162 offset:2048
	ds_read_b128 v[176:179], v162 offset:3072
	s_add_u32 s36, s36, 0x40000
	s_addc_u32 s37, s37, 0
	s_mov_b32 m0, s53
	v_lshl_add_u64 v[228:229], s[36:37], 0, v[154:155]
	ds_read_b128 v[180:183], v216 offset:32768
	ds_read_b128 v[184:187], v216 offset:33792
	ds_read_b128 v[188:191], v216 offset:34816
	ds_read_b128 v[192:195], v216 offset:35840
	ds_read_b128 v[196:199], v216 offset:36864
	ds_read_b128 v[200:203], v216 offset:37888
	ds_read_b128 v[204:207], v216 offset:38912
	ds_read_b128 v[208:211], v216 offset:39936
	global_load_lds_dwordx4 v[228:229], off
	v_lshl_add_u64 v[228:229], s[36:37], 0, v[158:159]
	s_mov_b32 m0, s54
	s_nop 0
	global_load_lds_dwordx4 v[228:229], off
	s_waitcnt vmcnt(8)
	s_waitcnt lgkmcnt(0)
	s_barrier
; #define PG8_STAGE(bufoff, gbase, voff) do { _Pragma("unroll") for (int _i = 0; _i < 2; ++_i) \
;         __builtin_amdgcn_global_load_lds((const unsigned*)((const char*)(gbase) + (voff)[_i]), (PG8_LAS unsigned*)(lds + (bufoff) + ldsw + _i * 8192), 16, 0, 0); } while (0)
; #define PG8_LDA(dst, b, h) do { _Pragma("unroll") for (int m = 0; m < 4; ++m) _Pragma("unroll") for (int k = 0; k < 2; ++k) dst[m][k] = *(const PG8_LAS bf16x8*)(lds + PG8_SA(b, h) + aoff + m * 2048 + k * 1024); } while (0)
; #define PG8_MMA(ai, bj, At, Bt) do { __builtin_amdgcn_s_setprio(1); _Pragma("unroll") for (int m = 0; m < 4; ++m) _Pragma("unroll") for (int n = 0; n < 2; ++n) _Pragma("unroll") for (int k = 0; k < 2; ++k) \
;         acc[ai][bj][m][n] = __builtin_amdgcn_mfma_f32_16x16x32_bf16(Bt[n][k], At[m][k], acc[ai][bj][m][n], 0, 0, 0); __builtin_amdgcn_s_setprio(0); } while (0)
; #define PG8_WAIT_V(n) asm volatile("s_waitcnt vmcnt(" #n ")" ::: "memory")
; #define PG8_WAIT_L(n) asm volatile("s_waitcnt lgkmcnt(" #n ")" ::: "memory")
; #define PG8_BAR __builtin_amdgcn_s_barrier()
; #define PG8_SCHED __builtin_amdgcn_sched_barrier(0)
; template <class Epi, class Sched, bool ALIGN_EPI = false, bool SP2 = false>
; __device__ __forceinline__ void gemm_phase(PG8_LAS unsigned char* lds, const Gemm g, const Sched& S, const Epi& E) {
;     ...
;             PG8_WAIT_V(8); PG8_WAIT_L(0); PG8_BAR; PG8_MMA(0, 0, At, B0); PG8_MMA(0, 1, At, B1); PG8_BAR; PG8_SCHED;
;             PG8_LDA(At, 1, 1); PG8_STAGE(PG8_SB(1, 0), b3, voffB); PG8_STAGE(PG8_SB(1, 1), b3 + hstep, voffB); PG8_STAGE(PG8_SA(1, 0), a3, voffA);
;             PG8_WAIT_V(8); PG8_WAIT_L(0); PG8_BAR; PG8_MMA(1, 0, At, B0); PG8_MMA(1, 1, At, B1); PG8_BAR; PG8_SCHED;
;     ...
;         if constexpr (ALIGN_EPI) { if (wr == 0) PG8_BAR; }
	s_setprio 3
	s_waitcnt lgkmcnt(0)
	v_mfma_f32_16x16x32_bf16 v[142:145], v[58:61], v[180:183], v[142:145]
	v_mfma_f32_16x16x32_bf16 v[138:141], v[66:69], v[180:183], v[138:141]
	v_mfma_f32_16x16x32_bf16 v[126:129], v[58:61], v[188:191], v[126:129]
	v_mfma_f32_16x16x32_bf16 v[122:125], v[66:69], v[188:191], v[122:125]
	v_mfma_f32_16x16x32_bf16 v[110:113], v[58:61], v[196:199], v[110:113]
	v_mfma_f32_16x16x32_bf16 v[106:109], v[66:69], v[196:199], v[106:109]
	v_mfma_f32_16x16x32_bf16 v[94:97], v[58:61], v[204:207], v[94:97]
	v_mfma_f32_16x16x32_bf16 v[90:93], v[66:69], v[204:207], v[90:93]
	v_mfma_f32_16x16x32_bf16 v[142:145], v[62:65], v[184:187], v[142:145]
	v_mfma_f32_16x16x32_bf16 v[138:141], v[70:73], v[184:187], v[138:141]
	v_mfma_f32_16x16x32_bf16 v[126:129], v[62:65], v[192:195], v[126:129]
	v_mfma_f32_16x16x32_bf16 v[122:125], v[70:73], v[192:195], v[122:125]
	v_mfma_f32_16x16x32_bf16 v[110:113], v[62:65], v[200:203], v[110:113]
	v_mfma_f32_16x16x32_bf16 v[106:109], v[70:73], v[200:203], v[106:109]
	v_mfma_f32_16x16x32_bf16 v[94:97], v[62:65], v[208:211], v[94:97]
	v_mfma_f32_16x16x32_bf16 v[90:93], v[70:73], v[208:211], v[90:93]
	s_setprio 0
	s_setprio 3
	v_mfma_f32_16x16x32_bf16 v[134:137], v[146:149], v[180:183], v[134:137]
	v_mfma_f32_16x16x32_bf16 v[130:133], v[172:175], v[180:183], v[130:133]
	v_mfma_f32_16x16x32_bf16 v[118:121], v[146:149], v[188:191], v[118:121]
	v_mfma_f32_16x16x32_bf16 v[114:117], v[172:175], v[188:191], v[114:117]
	v_mfma_f32_16x16x32_bf16 v[102:105], v[146:149], v[196:199], v[102:105]
	v_mfma_f32_16x16x32_bf16 v[98:101], v[172:175], v[196:199], v[98:101]
	v_mfma_f32_16x16x32_bf16 v[86:89], v[146:149], v[204:207], v[86:89]
	v_mfma_f32_16x16x32_bf16 v[82:85], v[172:175], v[204:207], v[82:85]
	v_mfma_f32_16x16x32_bf16 v[134:137], v[150:153], v[184:187], v[134:137]
	v_mfma_f32_16x16x32_bf16 v[130:133], v[176:179], v[184:187], v[130:133]
	v_mfma_f32_16x16x32_bf16 v[118:121], v[150:153], v[192:195], v[118:121]
	v_mfma_f32_16x16x32_bf16 v[114:117], v[176:179], v[192:195], v[114:117]
	v_mfma_f32_16x16x32_bf16 v[102:105], v[150:153], v[200:203], v[102:105]
	v_mfma_f32_16x16x32_bf16 v[98:101], v[176:179], v[200:203], v[98:101]
	v_mfma_f32_16x16x32_bf16 v[86:89], v[150:153], v[208:211], v[86:89]
	v_mfma_f32_16x16x32_bf16 v[82:85], v[176:179], v[208:211], v[82:85]
	s_setprio 0
	s_barrier
	s_add_i32 s36, s42, s50
	v_lshl_add_u64 v[218:219], v[218:219], 0, s[20:21]
	s_mov_b32 m0, s36
	ds_read_b128 v[180:183], v216 offset:49152
	ds_read_b128 v[184:187], v216 offset:50176
	ds_read_b128 v[188:191], v216 offset:51200
	ds_read_b128 v[192:195], v216 offset:52224
	ds_read_b128 v[196:199], v216 offset:53248
	ds_read_b128 v[200:203], v216 offset:54272
	ds_read_b128 v[204:207], v216 offset:55296
	ds_read_b128 v[208:211], v216 offset:56320
	global_load_lds_dwordx4 v[218:219], off
	s_add_i32 m0, s36, 0x2000
	s_add_u32 s6, s6, 0x40080
	v_lshl_add_u64 v[218:219], v[222:223], 0, s[20:21]
	s_addc_u32 s7, s7, 0
	s_add_i32 s36, s43, s50
	global_load_lds_dwordx4 v[218:219], off
	v_lshl_add_u64 v[218:219], s[6:7], 0, v[156:157]
	s_mov_b32 m0, s36
	s_nop 0
	global_load_lds_dwordx4 v[218:219], off
	v_lshl_add_u64 v[218:219], s[6:7], 0, v[160:161]
	s_add_i32 m0, s36, 0x2000
	s_nop 0
	global_load_lds_dwordx4 v[218:219], off
	v_lshl_add_u64 v[218:219], v[224:225], 0, s[20:21]
	s_mov_b32 m0, s63
	s_nop 0
	global_load_lds_dwordx4 v[218:219], off
	v_lshl_add_u64 v[218:219], v[226:227], 0, s[20:21]
	s_mov_b32 m0, s64
	s_nop 0
	global_load_lds_dwordx4 v[218:219], off
	s_waitcnt vmcnt(8)
	s_waitcnt lgkmcnt(0)
	s_barrier
	s_setprio 3
	s_waitcnt lgkmcnt(0)
	v_mfma_f32_16x16x32_bf16 v[78:81], v[58:61], v[180:183], v[78:81]
	v_mfma_f32_16x16x32_bf16 v[74:77], v[66:69], v[180:183], v[74:77]
	v_mfma_f32_16x16x32_bf16 v[46:49], v[58:61], v[188:191], v[46:49]
	v_mfma_f32_16x16x32_bf16 v[42:45], v[66:69], v[188:191], v[42:45]
	v_mfma_f32_16x16x32_bf16 v[30:33], v[58:61], v[196:199], v[30:33]
	v_mfma_f32_16x16x32_bf16 v[26:29], v[66:69], v[196:199], v[26:29]
	v_mfma_f32_16x16x32_bf16 v[14:17], v[58:61], v[204:207], v[14:17]
	v_mfma_f32_16x16x32_bf16 v[10:13], v[66:69], v[204:207], v[10:13]
	v_mfma_f32_16x16x32_bf16 v[78:81], v[62:65], v[184:187], v[78:81]
	v_mfma_f32_16x16x32_bf16 v[74:77], v[70:73], v[184:187], v[74:77]
	v_mfma_f32_16x16x32_bf16 v[46:49], v[62:65], v[192:195], v[46:49]
	v_mfma_f32_16x16x32_bf16 v[42:45], v[70:73], v[192:195], v[42:45]
	v_mfma_f32_16x16x32_bf16 v[30:33], v[62:65], v[200:203], v[30:33]
	v_mfma_f32_16x16x32_bf16 v[26:29], v[70:73], v[200:203], v[26:29]
	v_mfma_f32_16x16x32_bf16 v[14:17], v[62:65], v[208:211], v[14:17]
	v_mfma_f32_16x16x32_bf16 v[10:13], v[70:73], v[208:211], v[10:13]
	s_setprio 0
	s_setprio 3
	v_mfma_f32_16x16x32_bf16 v[50:53], v[146:149], v[180:183], v[50:53]
	v_mfma_f32_16x16x32_bf16 v[62:65], v[150:153], v[184:187], v[50:53]
	v_mfma_f32_16x16x32_bf16 v[50:53], v[172:175], v[180:183], v[54:57]
	v_mfma_f32_16x16x32_bf16 v[38:41], v[146:149], v[188:191], v[38:41]
	v_mfma_f32_16x16x32_bf16 v[34:37], v[172:175], v[188:191], v[34:37]
	v_mfma_f32_16x16x32_bf16 v[22:25], v[146:149], v[196:199], v[22:25]
	v_mfma_f32_16x16x32_bf16 v[18:21], v[172:175], v[196:199], v[18:21]
	v_mfma_f32_16x16x32_bf16 v[6:9], v[146:149], v[204:207], v[6:9]
	v_mfma_f32_16x16x32_bf16 v[2:5], v[172:175], v[204:207], v[2:5]
	v_mfma_f32_16x16x32_bf16 v[58:61], v[176:179], v[184:187], v[50:53]
	v_mfma_f32_16x16x32_bf16 v[38:41], v[150:153], v[192:195], v[38:41]
	v_mfma_f32_16x16x32_bf16 v[34:37], v[176:179], v[192:195], v[34:37]
	v_mfma_f32_16x16x32_bf16 v[22:25], v[150:153], v[200:203], v[22:25]
	v_mfma_f32_16x16x32_bf16 v[18:21], v[176:179], v[200:203], v[18:21]
	v_mfma_f32_16x16x32_bf16 v[6:9], v[150:153], v[208:211], v[6:9]
	v_mfma_f32_16x16x32_bf16 v[2:5], v[176:179], v[208:211], v[2:5]
	s_setprio 0
	s_barrier
	s_add_i32 s41, s41, 2
	s_add_u32 s4, s4, 0x100
	s_addc_u32 s5, s5, 0
	s_add_u32 s39, s39, 0x100
	s_addc_u32 s40, s40, 0
	s_cmp_gt_u32 s41, 13
	s_cbranch_scc0 .LBB0_838
	s_and_b64 vcc, exec, s[22:23]
	s_cbranch_vccz .LBB0_841
	s_barrier

;     __host__ __device__ bool next(int i, Unit& u) const { if (!b.next(i >> 1, u)) return false; u.sel = i & 1; return true; }
; #define PG8_STAGE(bufoff, gbase, voff) do { _Pragma("unroll") for (int _i = 0; _i < 2; ++_i) \
;         __builtin_amdgcn_global_load_lds((const unsigned*)((const char*)(gbase) + (voff)[_i]), (PG8_LAS unsigned*)(lds + (bufoff) + ldsw + _i * 8192), 16, 0, 0); } while (0)
; #define PG8_LDA(dst, b, h) do { _Pragma("unroll") for (int m = 0; m < 4; ++m) _Pragma("unroll") for (int k = 0; k < 2; ++k) dst[m][k] = *(const PG8_LAS bf16x8*)(lds + PG8_SA(b, h) + aoff + m * 2048 + k * 1024); } while (0)
; #define PG8_WAIT_V(n) asm volatile("s_waitcnt vmcnt(" #n ")" ::: "memory")
;     __host__ __device__ bool next(int i, Unit& u) const {
;         const long L = (long)i * G + c; if (L >= nwg) return false;
;         int wgid = (int)L; { const int q = nwg / NXCD, r = nwg % NXCD, xcd = wgid % NXCD, off = wgid / NXCD; wgid = (xcd < r ? xcd * (q + 1) : r * (q + 1) + (xcd - r) * q) + off; }
;         const int nig = WGM * nN, gid = wgid / nig, fm = gid * WGM, gsz = (nM - fm) < WGM ? (nM - fm) : WGM;
;         u.pm = fm + ((wgid % nig) % gsz); u.pn = (wgid % nig) / gsz; u.sel = 0; return true;
; template <class Epi, class Sched, bool ALIGN_EPI = false, bool SP2 = false>
; __device__ __forceinline__ void gemm_phase(PG8_LAS unsigned char* lds, const Gemm g, const Sched& S, const Epi& E) {
;     ...
;         const bool has_next = S.next(ui + 1, nxt);
;         const char* nA = has_next ? PG8_ABASE(nxt) : cA; const char* nB = has_next ? PG8_BBASE(nxt) : cB;
;         for (int t = 0; t < nt; t += 2) {
;             const bool last = (t == nt - 2);
;             const char* a1 = cA + (size_t)(t + 1) * kstepA;
;             const char* a2 = last ? nA : cA + (size_t)(t + 2) * kstepA; const char* b2 = last ? nB : cB + (size_t)(t + 2) * kstep;
;             const char* a3 = a2 + kstepA; const char* b3 = b2 + kstep;
;             if (last && has_next) S.a_ready(nxt);
;             if constexpr (SP2) {
;             PG8_LDB(B0, 0, 0); PG8_LDB(B1, 0, 1); PG8_SCHED; PG8_LDA(At, 0, 0); PG8_STAGE(PG8_SA(1, 1), a1 + hstep, voffA);
;             PG8_WAIT_V(8); PG8_WAIT_L(0); PG8_BAR; PG8_MMA(0, 0, At, B0); PG8_MMA(0, 1, At, B1); PG8_BAR; PG8_SCHED;
;             if constexpr (Epi::PREFETCH) { if (t == tpf) E.prefetch(cur, wid, lane); }
.LBB0_982:
	s_ashr_i32 s29, s28, 31
	s_lshl_b32 s34, s34, 8
	s_lshl_b64 s[36:37], s[28:29], 14
	s_ashr_i32 s29, s28, 5
	s_ashr_i32 s35, s34, 31
	s_add_u32 s36, s10, s36
	s_mul_hi_i32 s38, s29, 0x5800
	s_mulk_i32 s29, 0x5800
	s_addc_u32 s37, s69, s37
	s_add_u32 s29, s62, s29
	s_addc_u32 s42, s63, s38
	s_lshl_b64 s[38:39], s[34:35], 2
	s_add_u32 s38, s29, s38
	s_addc_u32 s39, s42, s39
	s_add_u32 s29, s40, 0x100
	v_lshl_add_u64 v[188:189], s[30:31], 0, v[180:181]
	v_lshl_add_u64 v[190:191], s[30:31], 0, v[182:183]
	s_addc_u32 s35, s41, 0
	s_mov_b32 s83, 0
	s_mov_b64 s[40:41], 0
	ds_read_b128 v[154:157], v195
	ds_read_b128 v[158:161], v195 offset:1024
	ds_read_b128 v[162:165], v195 offset:2048
	ds_read_b128 v[166:169], v195 offset:3072
	ds_read_b128 v[138:141], v196
	ds_read_b128 v[142:145], v196 offset:1024
	ds_read_b128 v[146:149], v196 offset:2048
	ds_read_b128 v[150:153], v196 offset:3072
	v_lshl_add_u64 v[98:99], v[188:189], 0, s[40:41]
	s_add_i32 m0, s54, 0xc000
	ds_read_b128 v[200:203], v197
	ds_read_b128 v[204:207], v197 offset:1024
	ds_read_b128 v[208:211], v197 offset:2048
	ds_read_b128 v[212:215], v197 offset:3072
	ds_read_b128 v[216:219], v197 offset:4096
	ds_read_b128 v[220:223], v197 offset:5120
	ds_read_b128 v[224:227], v197 offset:6144
	ds_read_b128 v[228:231], v197 offset:7168
	global_load_lds_dwordx4 v[98:99], off
	v_lshl_add_u64 v[98:99], v[190:191], 0, s[40:41]
	s_add_i32 m0, s54, 0xe000
	s_nop 0
	global_load_lds_dwordx4 v[98:99], off
	s_add_i32 s11, s11, 1
	s_mul_i32 s2, s11, s68
	s_mul_hi_u32 s3, s11, s33
	s_add_i32 s3, s3, s2
	s_mul_i32 s2, s11, s33
	s_add_u32 s24, s2, s87
	s_addc_u32 s25, s3, s52
	v_cmp_lt_i64_e64 s[2:3], s[24:25], v[184:185]
	s_ashr_i32 s20, s24, 31
	s_lshr_b32 s20, s20, 29
	s_add_i32 s20, s24, s20
	s_ashr_i32 s21, s20, 3
	s_and_b32 s20, s20, -8
	s_sub_i32 s20, s24, s20
	s_cmp_lt_i32 s20, 0
	s_cselect_b32 s22, s53, 0x160
	s_mul_i32 s20, s20, s22
	s_add_i32 s20, s20, s21
	s_mul_hi_i32 s21, s20, 0x2e8ba2e9
	s_lshr_b32 s22, s21, 31
	s_ashr_i32 s21, s21, 3
	s_add_i32 s21, s21, s22
	s_lshl_b32 s22, s21, 1
	s_mul_i32 s21, s21, 44
	s_sub_i32 s21, s20, s21
	s_lshr_b32 s20, s21, 1
	s_and_b32 s21, s21, 1
	s_add_i32 s22, s22, s21
	s_ashr_i32 s23, s22, 31
	s_lshl_b64 s[24:25], s[22:23], 19
	s_add_u32 s24, s47, s24
	s_addc_u32 s25, s48, s25
	s_and_b64 s[26:27], s[2:3], exec
	s_cselect_b32 s23, s25, s48
	s_cselect_b32 s81, s24, s47
	s_ashr_i32 s21, s20, 31
	s_lshl_b64 s[26:27], s[20:21], 19
	s_add_u32 s26, s49, s26
	s_addc_u32 s27, s50, s27
	s_and_b64 s[98:99], s[2:3], exec
	s_cselect_b32 s21, s27, s50
	s_cselect_b32 s82, s26, s49
	s_waitcnt vmcnt(8)
	s_waitcnt lgkmcnt(0)
	s_barrier
	s_setprio 3
	s_waitcnt lgkmcnt(0)
	v_mfma_f32_16x16x32_bf16 v[98:101], v[154:157], v[200:203], 0
	v_mfma_f32_16x16x32_bf16 v[106:109], v[162:165], v[200:203], 0
	v_mfma_f32_16x16x32_bf16 v[118:121], v[154:157], v[208:211], 0
	v_mfma_f32_16x16x32_bf16 v[114:117], v[162:165], v[208:211], 0
	v_mfma_f32_16x16x32_bf16 v[94:97], v[154:157], v[216:219], 0
	v_mfma_f32_16x16x32_bf16 v[90:93], v[162:165], v[216:219], 0
	v_mfma_f32_16x16x32_bf16 v[78:81], v[154:157], v[224:227], 0
	v_mfma_f32_16x16x32_bf16 v[74:77], v[162:165], v[224:227], 0
	v_mfma_f32_16x16x32_bf16 v[98:101], v[158:161], v[204:207], v[98:101]
	v_mfma_f32_16x16x32_bf16 v[106:109], v[166:169], v[204:207], v[106:109]
	v_mfma_f32_16x16x32_bf16 v[118:121], v[158:161], v[212:215], v[118:121]
	v_mfma_f32_16x16x32_bf16 v[114:117], v[166:169], v[212:215], v[114:117]
	v_mfma_f32_16x16x32_bf16 v[94:97], v[158:161], v[220:223], v[94:97]
	v_mfma_f32_16x16x32_bf16 v[90:93], v[166:169], v[220:223], v[90:93]
	v_mfma_f32_16x16x32_bf16 v[78:81], v[158:161], v[228:231], v[78:81]
	v_mfma_f32_16x16x32_bf16 v[74:77], v[166:169], v[228:231], v[74:77]
	s_setprio 0
	s_setprio 3
	v_mfma_f32_16x16x32_bf16 v[126:129], v[138:141], v[200:203], 0
	v_mfma_f32_16x16x32_bf16 v[122:125], v[146:149], v[200:203], 0
	v_mfma_f32_16x16x32_bf16 v[110:113], v[138:141], v[208:211], 0
	v_mfma_f32_16x16x32_bf16 v[102:105], v[146:149], v[208:211], 0
	v_mfma_f32_16x16x32_bf16 v[86:89], v[138:141], v[216:219], 0
	v_mfma_f32_16x16x32_bf16 v[82:85], v[146:149], v[216:219], 0
	v_mfma_f32_16x16x32_bf16 v[70:73], v[138:141], v[224:227], 0
	v_mfma_f32_16x16x32_bf16 v[66:69], v[146:149], v[224:227], 0
	v_mfma_f32_16x16x32_bf16 v[126:129], v[142:145], v[204:207], v[126:129]
	v_mfma_f32_16x16x32_bf16 v[122:125], v[150:153], v[204:207], v[122:125]
	v_mfma_f32_16x16x32_bf16 v[110:113], v[142:145], v[212:215], v[110:113]
	v_mfma_f32_16x16x32_bf16 v[102:105], v[150:153], v[212:215], v[102:105]
	v_mfma_f32_16x16x32_bf16 v[86:89], v[142:145], v[220:223], v[86:89]
	v_mfma_f32_16x16x32_bf16 v[82:85], v[150:153], v[220:223], v[82:85]
	v_mfma_f32_16x16x32_bf16 v[70:73], v[142:145], v[228:231], v[70:73]
	v_mfma_f32_16x16x32_bf16 v[66:69], v[150:153], v[228:231], v[66:69]
	s_setprio 0
	s_barrier
	s_cmp_lg_u32 s46, s83
	s_cbranch_scc1 .Lpz5_a
	v_mov_b32_e32 v178, v194
	s_add_i32 m0, s79, 0x20000
	v_lshl_add_u64 v[130:131], s[36:37], 0, v[178:179]
	global_load_lds_dwordx4 v178, s[36:37]
	v_lshl_add_u64 v[130:131], v[130:131], 0, s[18:19]
	s_add_i32 m0, s79, 0x20400
	s_andn2_b64 vcc, exec, s[14:15]
	global_load_lds_dwordx4 v[130:131], off
	s_cbranch_vccnz .Lpz5_a
	v_lshl_add_u64 v[130:131], s[38:39], 0, v[178:179]
	s_add_i32 m0, 0, 0x24000
	s_nop 0
	global_load_lds_dwordx4 v[130:131], off
	s_branch .Lpz5_a
; #define PG8_STAGE(bufoff, gbase, voff) do { _Pragma("unroll") for (int _i = 0; _i < 2; ++_i) \
;         __builtin_amdgcn_global_load_lds((const unsigned*)((const char*)(gbase) + (voff)[_i]), (PG8_LAS unsigned*)(lds + (bufoff) + ldsw + _i * 8192), 16, 0, 0); } while (0)
; #define PG8_LDA(dst, b, h) do { _Pragma("unroll") for (int m = 0; m < 4; ++m) _Pragma("unroll") for (int k = 0; k < 2; ++k) dst[m][k] = *(const PG8_LAS bf16x8*)(lds + PG8_SA(b, h) + aoff + m * 2048 + k * 1024); } while (0)
; #define PG8_MMA(ai, bj, At, Bt) do { __builtin_amdgcn_s_setprio(1); _Pragma("unroll") for (int m = 0; m < 4; ++m) _Pragma("unroll") for (int n = 0; n < 2; ++n) _Pragma("unroll") for (int k = 0; k < 2; ++k) \
;         acc[ai][bj][m][n] = __builtin_amdgcn_mfma_f32_16x16x32_bf16(Bt[n][k], At[m][k], acc[ai][bj][m][n], 0, 0, 0); __builtin_amdgcn_s_setprio(0); } while (0)
; #define PG8_WAIT_V(n) asm volatile("s_waitcnt vmcnt(" #n ")" ::: "memory")
; #define PG8_WAIT_L(n) asm volatile("s_waitcnt lgkmcnt(" #n ")" ::: "memory")
; #define PG8_BAR __builtin_amdgcn_s_barrier()
; #define PG8_SCHED __builtin_amdgcn_sched_barrier(0)
; template <class Epi, class Sched, bool ALIGN_EPI = false, bool SP2 = false>
; __device__ __forceinline__ void gemm_phase(PG8_LAS unsigned char* lds, const Gemm g, const Sched& S, const Epi& E) {
;     ...
;             PG8_LDA(At, 0, 1); PG8_STAGE(PG8_SB(0, 0), b2, voffB); PG8_STAGE(PG8_SB(0, 1), b2 + hstep, voffB); PG8_STAGE(PG8_SA(0, 0), a2, voffA);
;             PG8_WAIT_V(8); PG8_WAIT_L(0); PG8_BAR; PG8_MMA(1, 0, At, B0); PG8_MMA(1, 1, At, B1); PG8_BAR; PG8_SCHED;
.Lpz5_a:
	s_add_u32 s42, s30, s40
	s_addc_u32 s43, s31, s41
	s_add_u32 s42, s42, 0x100
	s_addc_u32 s43, s43, 0
	s_add_u32 s84, s29, s40
	s_addc_u32 s85, s35, s41
	s_cmpk_eq_i32 s40, 0x700
	s_cselect_b32 s45, s23, s43
	s_cselect_b32 s44, s81, s42
	s_cselect_b32 s43, s21, s85
	s_cselect_b32 s42, s82, s84
	s_mov_b32 m0, s55
	v_lshl_add_u64 v[232:233], s[42:43], 0, v[174:175]
	s_add_u32 s84, s42, 0x40000
	ds_read_b128 v[130:133], v197 offset:16384
	ds_read_b128 v[134:137], v197 offset:17408
	ds_read_b128 v[200:203], v197 offset:18432
	ds_read_b128 v[204:207], v197 offset:19456
	ds_read_b128 v[208:211], v197 offset:20480
	ds_read_b128 v[212:215], v197 offset:21504
	ds_read_b128 v[216:219], v197 offset:22528
	ds_read_b128 v[220:223], v197 offset:23552
	global_load_lds_dwordx4 v[232:233], off
	v_lshl_add_u64 v[234:235], s[42:43], 0, v[170:171]
	s_mov_b32 m0, s56
	s_addc_u32 s85, s43, 0
	global_load_lds_dwordx4 v[234:235], off
	v_lshl_add_u64 v[224:225], s[84:85], 0, v[174:175]
	s_mov_b32 m0, s57
	v_lshl_add_u64 v[236:237], s[44:45], 0, v[176:177]
	global_load_lds_dwordx4 v[224:225], off
	v_lshl_add_u64 v[224:225], s[84:85], 0, v[170:171]
	s_mov_b32 m0, s58
	v_lshl_add_u64 v[238:239], s[44:45], 0, v[172:173]
	global_load_lds_dwordx4 v[224:225], off
	s_mov_b32 m0, s54
	s_nop 0
	global_load_lds_dwordx4 v[236:237], off
	s_mov_b32 m0, s59
	s_nop 0
	global_load_lds_dwordx4 v[238:239], off
	s_waitcnt vmcnt(8)
	s_waitcnt lgkmcnt(0)
	s_barrier
	s_setprio 3
	s_waitcnt lgkmcnt(0)
	v_mfma_f32_16x16x32_bf16 v[62:65], v[154:157], v[130:133], 0
	v_mfma_f32_16x16x32_bf16 v[58:61], v[162:165], v[130:133], 0
	v_mfma_f32_16x16x32_bf16 v[46:49], v[154:157], v[200:203], 0
	v_mfma_f32_16x16x32_bf16 v[42:45], v[162:165], v[200:203], 0
	v_mfma_f32_16x16x32_bf16 v[30:33], v[154:157], v[208:211], 0
	v_mfma_f32_16x16x32_bf16 v[26:29], v[162:165], v[208:211], 0
	v_mfma_f32_16x16x32_bf16 v[14:17], v[154:157], v[216:219], 0
	v_mfma_f32_16x16x32_bf16 v[10:13], v[162:165], v[216:219], 0
	v_mfma_f32_16x16x32_bf16 v[62:65], v[158:161], v[134:137], v[62:65]
	v_mfma_f32_16x16x32_bf16 v[58:61], v[166:169], v[134:137], v[58:61]
	v_mfma_f32_16x16x32_bf16 v[46:49], v[158:161], v[204:207], v[46:49]
	v_mfma_f32_16x16x32_bf16 v[42:45], v[166:169], v[204:207], v[42:45]
	v_mfma_f32_16x16x32_bf16 v[30:33], v[158:161], v[212:215], v[30:33]
	v_mfma_f32_16x16x32_bf16 v[26:29], v[166:169], v[212:215], v[26:29]
	v_mfma_f32_16x16x32_bf16 v[14:17], v[158:161], v[220:223], v[14:17]
	v_mfma_f32_16x16x32_bf16 v[10:13], v[166:169], v[220:223], v[10:13]
	s_setprio 0
	s_setprio 3
	v_mfma_f32_16x16x32_bf16 v[54:57], v[138:141], v[130:133], 0
	v_mfma_f32_16x16x32_bf16 v[50:53], v[146:149], v[130:133], 0
	v_mfma_f32_16x16x32_bf16 v[38:41], v[138:141], v[200:203], 0
	v_mfma_f32_16x16x32_bf16 v[34:37], v[146:149], v[200:203], 0
	v_mfma_f32_16x16x32_bf16 v[22:25], v[138:141], v[208:211], 0
	v_mfma_f32_16x16x32_bf16 v[18:21], v[146:149], v[208:211], 0
	v_mfma_f32_16x16x32_bf16 v[6:9], v[138:141], v[216:219], 0
	v_mfma_f32_16x16x32_bf16 v[2:5], v[146:149], v[216:219], 0
	v_mfma_f32_16x16x32_bf16 v[54:57], v[142:145], v[134:137], v[54:57]
	v_mfma_f32_16x16x32_bf16 v[50:53], v[150:153], v[134:137], v[50:53]
	v_mfma_f32_16x16x32_bf16 v[38:41], v[142:145], v[204:207], v[38:41]
	v_mfma_f32_16x16x32_bf16 v[34:37], v[150:153], v[204:207], v[34:37]
	v_mfma_f32_16x16x32_bf16 v[22:25], v[142:145], v[212:215], v[22:25]
	v_mfma_f32_16x16x32_bf16 v[18:21], v[150:153], v[212:215], v[18:21]
	v_mfma_f32_16x16x32_bf16 v[6:9], v[142:145], v[220:223], v[6:9]
	v_mfma_f32_16x16x32_bf16 v[2:5], v[150:153], v[220:223], v[2:5]
	s_setprio 0
	s_barrier
	s_branch .Lpz5_mid
.LBB0_985:
	s_add_u32 s42, s30, s40
	s_addc_u32 s43, s31, s41
	s_add_u32 s42, s42, 0x100
	s_addc_u32 s43, s43, 0
	s_add_u32 s84, s29, s40
	s_addc_u32 s85, s35, s41
	s_cmpk_eq_i32 s40, 0x700
	s_cselect_b32 s45, s23, s43
	s_cselect_b32 s44, s81, s42
	s_cselect_b32 s43, s21, s85
	s_cselect_b32 s42, s82, s84
	s_mov_b32 m0, s55
	v_lshl_add_u64 v[232:233], s[42:43], 0, v[174:175]
	s_add_u32 s84, s42, 0x40000
	ds_read_b128 v[130:133], v197 offset:16384
	ds_read_b128 v[134:137], v197 offset:17408
	ds_read_b128 v[200:203], v197 offset:18432
	ds_read_b128 v[204:207], v197 offset:19456
	ds_read_b128 v[208:211], v197 offset:20480
	ds_read_b128 v[212:215], v197 offset:21504
	ds_read_b128 v[216:219], v197 offset:22528
	ds_read_b128 v[220:223], v197 offset:23552
	global_load_lds_dwordx4 v[232:233], off
	v_lshl_add_u64 v[234:235], s[42:43], 0, v[170:171]
	s_mov_b32 m0, s56
	s_addc_u32 s85, s43, 0
	global_load_lds_dwordx4 v[234:235], off
	v_lshl_add_u64 v[224:225], s[84:85], 0, v[174:175]
	s_mov_b32 m0, s57
	v_lshl_add_u64 v[236:237], s[44:45], 0, v[176:177]
	global_load_lds_dwordx4 v[224:225], off
	v_lshl_add_u64 v[224:225], s[84:85], 0, v[170:171]
	s_mov_b32 m0, s58
	v_lshl_add_u64 v[238:239], s[44:45], 0, v[172:173]
	global_load_lds_dwordx4 v[224:225], off
	s_mov_b32 m0, s54
	s_nop 0
	global_load_lds_dwordx4 v[236:237], off
	s_mov_b32 m0, s59
	s_nop 0
	global_load_lds_dwordx4 v[238:239], off
	s_waitcnt vmcnt(8)
	s_waitcnt lgkmcnt(0)
	s_barrier
; #define PG8_STAGE(bufoff, gbase, voff) do { _Pragma("unroll") for (int _i = 0; _i < 2; ++_i) \
;         __builtin_amdgcn_global_load_lds((const unsigned*)((const char*)(gbase) + (voff)[_i]), (PG8_LAS unsigned*)(lds + (bufoff) + ldsw + _i * 8192), 16, 0, 0); } while (0)
; #define PG8_LDA(dst, b, h) do { _Pragma("unroll") for (int m = 0; m < 4; ++m) _Pragma("unroll") for (int k = 0; k < 2; ++k) dst[m][k] = *(const PG8_LAS bf16x8*)(lds + PG8_SA(b, h) + aoff + m * 2048 + k * 1024); } while (0)
; #define PG8_LDB(dst, b, h) do { _Pragma("unroll") for (int n = 0; n < 2; ++n) _Pragma("unroll") for (int k = 0; k < 2; ++k) dst[n][k] = *(const PG8_LAS bf16x8*)(lds + PG8_SB(b, h) + boff + n * 2048 + k * 1024); } while (0)
; #define PG8_MMA(ai, bj, At, Bt) do { __builtin_amdgcn_s_setprio(1); _Pragma("unroll") for (int m = 0; m < 4; ++m) _Pragma("unroll") for (int n = 0; n < 2; ++n) _Pragma("unroll") for (int k = 0; k < 2; ++k) \
;         acc[ai][bj][m][n] = __builtin_amdgcn_mfma_f32_16x16x32_bf16(Bt[n][k], At[m][k], acc[ai][bj][m][n], 0, 0, 0); __builtin_amdgcn_s_setprio(0); } while (0)
; #define PG8_WAIT_V(n) asm volatile("s_waitcnt vmcnt(" #n ")" ::: "memory")
; #define PG8_WAIT_L(n) asm volatile("s_waitcnt lgkmcnt(" #n ")" ::: "memory")
; #define PG8_BAR __builtin_amdgcn_s_barrier()
; #define PG8_SCHED __builtin_amdgcn_sched_barrier(0)
; template <class Epi, class Sched, bool ALIGN_EPI = false, bool SP2 = false>
; __device__ __forceinline__ void gemm_phase(PG8_LAS unsigned char* lds, const Gemm g, const Sched& S, const Epi& E) {
;     ...
;             PG8_WAIT_V(8); PG8_WAIT_L(0); PG8_BAR; PG8_MMA(1, 0, At, B0); PG8_MMA(1, 1, At, B1); PG8_BAR; PG8_SCHED;
;             PG8_LDB(B0, 1, 0); PG8_LDB(B1, 1, 1); PG8_SCHED; PG8_LDA(At, 1, 0); PG8_STAGE(PG8_SA(0, 1), a2 + hstep, voffA);
;             PG8_WAIT_V(8); PG8_WAIT_L(0); PG8_BAR; PG8_MMA(0, 0, At, B0); PG8_MMA(0, 1, At, B1); PG8_BAR; PG8_SCHED;
	s_setprio 3
	s_waitcnt lgkmcnt(0)
	v_mfma_f32_16x16x32_bf16 v[62:65], v[154:157], v[130:133], v[62:65]
	v_mfma_f32_16x16x32_bf16 v[58:61], v[162:165], v[130:133], v[58:61]
	v_mfma_f32_16x16x32_bf16 v[46:49], v[154:157], v[200:203], v[46:49]
	v_mfma_f32_16x16x32_bf16 v[42:45], v[162:165], v[200:203], v[42:45]
	v_mfma_f32_16x16x32_bf16 v[30:33], v[154:157], v[208:211], v[30:33]
	v_mfma_f32_16x16x32_bf16 v[26:29], v[162:165], v[208:211], v[26:29]
	v_mfma_f32_16x16x32_bf16 v[14:17], v[154:157], v[216:219], v[14:17]
	v_mfma_f32_16x16x32_bf16 v[10:13], v[162:165], v[216:219], v[10:13]
	v_mfma_f32_16x16x32_bf16 v[62:65], v[158:161], v[134:137], v[62:65]
	v_mfma_f32_16x16x32_bf16 v[58:61], v[166:169], v[134:137], v[58:61]
	v_mfma_f32_16x16x32_bf16 v[46:49], v[158:161], v[204:207], v[46:49]
	v_mfma_f32_16x16x32_bf16 v[42:45], v[166:169], v[204:207], v[42:45]
	v_mfma_f32_16x16x32_bf16 v[30:33], v[158:161], v[212:215], v[30:33]
	v_mfma_f32_16x16x32_bf16 v[26:29], v[166:169], v[212:215], v[26:29]
	v_mfma_f32_16x16x32_bf16 v[14:17], v[158:161], v[220:223], v[14:17]
	v_mfma_f32_16x16x32_bf16 v[10:13], v[166:169], v[220:223], v[10:13]
	s_setprio 0
	s_setprio 3
	v_mfma_f32_16x16x32_bf16 v[54:57], v[138:141], v[130:133], v[54:57]
	v_mfma_f32_16x16x32_bf16 v[50:53], v[146:149], v[130:133], v[50:53]
	v_mfma_f32_16x16x32_bf16 v[38:41], v[138:141], v[200:203], v[38:41]
	v_mfma_f32_16x16x32_bf16 v[34:37], v[146:149], v[200:203], v[34:37]
	v_mfma_f32_16x16x32_bf16 v[22:25], v[138:141], v[208:211], v[22:25]
	v_mfma_f32_16x16x32_bf16 v[18:21], v[146:149], v[208:211], v[18:21]
	v_mfma_f32_16x16x32_bf16 v[6:9], v[138:141], v[216:219], v[6:9]
	v_mfma_f32_16x16x32_bf16 v[2:5], v[146:149], v[216:219], v[2:5]
	v_mfma_f32_16x16x32_bf16 v[54:57], v[142:145], v[134:137], v[54:57]
	v_mfma_f32_16x16x32_bf16 v[50:53], v[150:153], v[134:137], v[50:53]
	v_mfma_f32_16x16x32_bf16 v[38:41], v[142:145], v[204:207], v[38:41]
	v_mfma_f32_16x16x32_bf16 v[34:37], v[150:153], v[204:207], v[34:37]
	v_mfma_f32_16x16x32_bf16 v[22:25], v[142:145], v[212:215], v[22:25]
	v_mfma_f32_16x16x32_bf16 v[18:21], v[150:153], v[212:215], v[18:21]
	v_mfma_f32_16x16x32_bf16 v[6:9], v[142:145], v[220:223], v[6:9]
	v_mfma_f32_16x16x32_bf16 v[2:5], v[150:153], v[220:223], v[2:5]
	s_setprio 0
	s_barrier
.Lpz5_mid:
	s_add_i32 s84, 0, 0x18000
	v_add_u32_e32 v130, s84, v193
	s_add_i32 s85, 0, 0x1c000
	ds_read_b128 v[138:141], v130
	ds_read_b128 v[142:145], v130 offset:1024
	ds_read_b128 v[146:149], v130 offset:2048
	ds_read_b128 v[150:153], v130 offset:3072
	v_add_u32_e32 v130, s85, v193
	ds_read_b128 v[154:157], v130
	ds_read_b128 v[158:161], v130 offset:1024
	ds_read_b128 v[162:165], v130 offset:2048
	ds_read_b128 v[166:169], v130 offset:3072
	s_add_u32 s44, s44, 0x40000
	s_addc_u32 s45, s45, 0
	s_mov_b32 m0, s60
	v_lshl_add_u64 v[130:131], s[44:45], 0, v[176:177]
	ds_read_b128 v[200:203], v197 offset:32768
	ds_read_b128 v[204:207], v197 offset:33792
	ds_read_b128 v[208:211], v197 offset:34816
	ds_read_b128 v[212:215], v197 offset:35840
	ds_read_b128 v[216:219], v197 offset:36864
	ds_read_b128 v[220:223], v197 offset:37888
	ds_read_b128 v[224:227], v197 offset:38912
	ds_read_b128 v[228:231], v197 offset:39936
	global_load_lds_dwordx4 v[130:131], off
	v_lshl_add_u64 v[130:131], s[44:45], 0, v[172:173]
	s_mov_b32 m0, s61
	s_nop 0
	global_load_lds_dwordx4 v[130:131], off
	s_waitcnt vmcnt(8)
	s_waitcnt lgkmcnt(0)
	s_barrier
	s_setprio 3
	s_waitcnt lgkmcnt(0)
	v_mfma_f32_16x16x32_bf16 v[98:101], v[138:141], v[200:203], v[98:101]
	v_mfma_f32_16x16x32_bf16 v[134:137], v[142:145], v[204:207], v[98:101]
	v_mfma_f32_16x16x32_bf16 v[98:101], v[146:149], v[200:203], v[106:109]
	v_mfma_f32_16x16x32_bf16 v[130:133], v[150:153], v[204:207], v[98:101]
	v_mfma_f32_16x16x32_bf16 v[98:101], v[138:141], v[208:211], v[118:121]
	v_mfma_f32_16x16x32_bf16 v[118:121], v[142:145], v[212:215], v[98:101]
	v_mfma_f32_16x16x32_bf16 v[98:101], v[146:149], v[208:211], v[114:117]
	v_mfma_f32_16x16x32_bf16 v[94:97], v[138:141], v[216:219], v[94:97]
	v_mfma_f32_16x16x32_bf16 v[90:93], v[146:149], v[216:219], v[90:93]
	v_mfma_f32_16x16x32_bf16 v[78:81], v[138:141], v[224:227], v[78:81]
	v_mfma_f32_16x16x32_bf16 v[74:77], v[146:149], v[224:227], v[74:77]
	v_mfma_f32_16x16x32_bf16 v[114:117], v[150:153], v[212:215], v[98:101]
	v_mfma_f32_16x16x32_bf16 v[94:97], v[142:145], v[220:223], v[94:97]
	v_mfma_f32_16x16x32_bf16 v[90:93], v[150:153], v[220:223], v[90:93]
	v_mfma_f32_16x16x32_bf16 v[78:81], v[142:145], v[228:231], v[78:81]
	v_mfma_f32_16x16x32_bf16 v[74:77], v[150:153], v[228:231], v[74:77]
	s_setprio 0
	s_setprio 3
	v_mfma_f32_16x16x32_bf16 v[98:101], v[154:157], v[200:203], v[126:129]
	v_mfma_f32_16x16x32_bf16 v[126:129], v[158:161], v[204:207], v[98:101]
	v_mfma_f32_16x16x32_bf16 v[98:101], v[162:165], v[200:203], v[122:125]
	v_mfma_f32_16x16x32_bf16 v[122:125], v[166:169], v[204:207], v[98:101]
	v_mfma_f32_16x16x32_bf16 v[98:101], v[154:157], v[208:211], v[110:113]
	v_mfma_f32_16x16x32_bf16 v[110:113], v[158:161], v[212:215], v[98:101]
	v_mfma_f32_16x16x32_bf16 v[98:101], v[162:165], v[208:211], v[102:105]
	v_mfma_f32_16x16x32_bf16 v[86:89], v[154:157], v[216:219], v[86:89]
	v_mfma_f32_16x16x32_bf16 v[82:85], v[162:165], v[216:219], v[82:85]
	v_mfma_f32_16x16x32_bf16 v[70:73], v[154:157], v[224:227], v[70:73]
	v_mfma_f32_16x16x32_bf16 v[66:69], v[162:165], v[224:227], v[66:69]
	v_mfma_f32_16x16x32_bf16 v[102:105], v[166:169], v[212:215], v[98:101]
	v_mfma_f32_16x16x32_bf16 v[86:89], v[158:161], v[220:223], v[86:89]
	v_mfma_f32_16x16x32_bf16 v[82:85], v[166:169], v[220:223], v[82:85]
	v_mfma_f32_16x16x32_bf16 v[70:73], v[158:161], v[228:231], v[70:73]
	v_mfma_f32_16x16x32_bf16 v[66:69], v[166:169], v[228:231], v[66:69]
	s_setprio 0
	s_barrier
; #define PG8_STAGE(bufoff, gbase, voff) do { _Pragma("unroll") for (int _i = 0; _i < 2; ++_i) \
;         __builtin_amdgcn_global_load_lds((const unsigned*)((const char*)(gbase) + (voff)[_i]), (PG8_LAS unsigned*)(lds + (bufoff) + ldsw + _i * 8192), 16, 0, 0); } while (0)
; #define PG8_LDA(dst, b, h) do { _Pragma("unroll") for (int m = 0; m < 4; ++m) _Pragma("unroll") for (int k = 0; k < 2; ++k) dst[m][k] = *(const PG8_LAS bf16x8*)(lds + PG8_SA(b, h) + aoff + m * 2048 + k * 1024); } while (0)
; #define PG8_MMA(ai, bj, At, Bt) do { __builtin_amdgcn_s_setprio(1); _Pragma("unroll") for (int m = 0; m < 4; ++m) _Pragma("unroll") for (int n = 0; n < 2; ++n) _Pragma("unroll") for (int k = 0; k < 2; ++k) \
;         acc[ai][bj][m][n] = __builtin_amdgcn_mfma_f32_16x16x32_bf16(Bt[n][k], At[m][k], acc[ai][bj][m][n], 0, 0, 0); __builtin_amdgcn_s_setprio(0); } while (0)
; #define PG8_WAIT_V(n) asm volatile("s_waitcnt vmcnt(" #n ")" ::: "memory")
; #define PG8_WAIT_L(n) asm volatile("s_waitcnt lgkmcnt(" #n ")" ::: "memory")
; #define PG8_BAR __builtin_amdgcn_s_barrier()
; #define PG8_SCHED __builtin_amdgcn_sched_barrier(0)
; template <class Epi, class Sched, bool ALIGN_EPI = false, bool SP2 = false>
; __device__ __forceinline__ void gemm_phase(PG8_LAS unsigned char* lds, const Gemm g, const Sched& S, const Epi& E) {
;     ...
;             PG8_LDA(At, 1, 1); PG8_STAGE(PG8_SB(1, 0), b3, voffB); PG8_STAGE(PG8_SB(1, 1), b3 + hstep, voffB); PG8_STAGE(PG8_SA(1, 0), a3, voffA);
;             PG8_WAIT_V(8); PG8_WAIT_L(0); PG8_BAR; PG8_MMA(1, 0, At, B0); PG8_MMA(1, 1, At, B1); PG8_BAR; PG8_SCHED;
	s_add_i32 s44, s84, s51
	v_lshl_add_u64 v[224:225], v[232:233], 0, s[8:9]
	s_mov_b32 m0, s44
	ds_read_b128 v[98:101], v197 offset:49152
	ds_read_b128 v[106:109], v197 offset:50176
	ds_read_b128 v[200:203], v197 offset:51200
	ds_read_b128 v[204:207], v197 offset:52224
	ds_read_b128 v[208:211], v197 offset:53248
	ds_read_b128 v[212:215], v197 offset:54272
	ds_read_b128 v[216:219], v197 offset:55296
	ds_read_b128 v[220:223], v197 offset:56320
	global_load_lds_dwordx4 v[224:225], off
	s_add_i32 m0, s44, 0x2000
	s_add_u32 s42, s42, 0x40080
	v_lshl_add_u64 v[224:225], v[234:235], 0, s[8:9]
	s_addc_u32 s43, s43, 0
	s_add_i32 s44, s85, s51
	global_load_lds_dwordx4 v[224:225], off
	v_lshl_add_u64 v[224:225], s[42:43], 0, v[174:175]
	s_mov_b32 m0, s44
	s_nop 0
	global_load_lds_dwordx4 v[224:225], off
	v_lshl_add_u64 v[224:225], s[42:43], 0, v[170:171]
	s_add_i32 m0, s44, 0x2000
	s_nop 0
	global_load_lds_dwordx4 v[224:225], off
	v_lshl_add_u64 v[224:225], v[236:237], 0, s[8:9]
	s_mov_b32 m0, s65
	s_nop 0
	global_load_lds_dwordx4 v[224:225], off
	v_lshl_add_u64 v[224:225], v[238:239], 0, s[8:9]
	s_mov_b32 m0, s66
	s_nop 0
	global_load_lds_dwordx4 v[224:225], off
	s_waitcnt vmcnt(8)
	s_waitcnt lgkmcnt(0)
	s_barrier
	s_setprio 3
	s_waitcnt lgkmcnt(0)
	v_mfma_f32_16x16x32_bf16 v[62:65], v[138:141], v[98:101], v[62:65]
	v_mfma_f32_16x16x32_bf16 v[58:61], v[146:149], v[98:101], v[58:61]
	v_mfma_f32_16x16x32_bf16 v[46:49], v[138:141], v[200:203], v[46:49]
	v_mfma_f32_16x16x32_bf16 v[42:45], v[146:149], v[200:203], v[42:45]
	v_mfma_f32_16x16x32_bf16 v[30:33], v[138:141], v[208:211], v[30:33]
	v_mfma_f32_16x16x32_bf16 v[26:29], v[146:149], v[208:211], v[26:29]
	v_mfma_f32_16x16x32_bf16 v[14:17], v[138:141], v[216:219], v[14:17]
	v_mfma_f32_16x16x32_bf16 v[10:13], v[146:149], v[216:219], v[10:13]
	v_mfma_f32_16x16x32_bf16 v[62:65], v[142:145], v[106:109], v[62:65]
	v_mfma_f32_16x16x32_bf16 v[58:61], v[150:153], v[106:109], v[58:61]
	v_mfma_f32_16x16x32_bf16 v[46:49], v[142:145], v[204:207], v[46:49]
	v_mfma_f32_16x16x32_bf16 v[42:45], v[150:153], v[204:207], v[42:45]
	v_mfma_f32_16x16x32_bf16 v[30:33], v[142:145], v[212:215], v[30:33]
	v_mfma_f32_16x16x32_bf16 v[26:29], v[150:153], v[212:215], v[26:29]
	v_mfma_f32_16x16x32_bf16 v[14:17], v[142:145], v[220:223], v[14:17]
	v_mfma_f32_16x16x32_bf16 v[10:13], v[150:153], v[220:223], v[10:13]
	s_setprio 0
	s_setprio 3
	v_mfma_f32_16x16x32_bf16 v[54:57], v[154:157], v[98:101], v[54:57]
	v_mfma_f32_16x16x32_bf16 v[50:53], v[162:165], v[98:101], v[50:53]
	v_mfma_f32_16x16x32_bf16 v[38:41], v[154:157], v[200:203], v[38:41]
	v_mfma_f32_16x16x32_bf16 v[34:37], v[162:165], v[200:203], v[34:37]
	v_mfma_f32_16x16x32_bf16 v[22:25], v[154:157], v[208:211], v[22:25]
	v_mfma_f32_16x16x32_bf16 v[18:21], v[162:165], v[208:211], v[18:21]
	v_mfma_f32_16x16x32_bf16 v[6:9], v[154:157], v[216:219], v[6:9]
	v_mfma_f32_16x16x32_bf16 v[2:5], v[162:165], v[216:219], v[2:5]
	v_mfma_f32_16x16x32_bf16 v[54:57], v[158:161], v[106:109], v[54:57]
	v_mfma_f32_16x16x32_bf16 v[50:53], v[166:169], v[106:109], v[50:53]
	v_mfma_f32_16x16x32_bf16 v[38:41], v[158:161], v[204:207], v[38:41]
	v_mfma_f32_16x16x32_bf16 v[34:37], v[166:169], v[204:207], v[34:37]
	v_mfma_f32_16x16x32_bf16 v[22:25], v[158:161], v[212:215], v[22:25]
	v_mfma_f32_16x16x32_bf16 v[18:21], v[166:169], v[212:215], v[18:21]
	v_mfma_f32_16x16x32_bf16 v[6:9], v[158:161], v[220:223], v[6:9]
	v_mfma_f32_16x16x32_bf16 v[2:5], v[166:169], v[220:223], v[2:5]
	s_setprio 0
	s_barrier
	s_add_i32 s42, s83, 2
	s_add_u32 s40, s40, 0x100
	s_addc_u32 s41, s41, 0
	s_cmp_gt_u32 s83, 13
	s_mov_b32 s83, s42
	s_cbranch_scc1 .LBB0_989
; #define PG8_LAS __attribute__((address_space(3)))
; #define PG8_STAGE(bufoff, gbase, voff) do { _Pragma("unroll") for (int _i = 0; _i < 2; ++_i) \
;         __builtin_amdgcn_global_load_lds((const unsigned*)((const char*)(gbase) + (voff)[_i]), (PG8_LAS unsigned*)(lds + (bufoff) + ldsw + _i * 8192), 16, 0, 0); } while (0)
; #define PG8_LDA(dst, b, h) do { _Pragma("unroll") for (int m = 0; m < 4; ++m) _Pragma("unroll") for (int k = 0; k < 2; ++k) dst[m][k] = *(const PG8_LAS bf16x8*)(lds + PG8_SA(b, h) + aoff + m * 2048 + k * 1024); } while (0)
; #define PG8_LDB(dst, b, h) do { _Pragma("unroll") for (int n = 0; n < 2; ++n) _Pragma("unroll") for (int k = 0; k < 2; ++k) dst[n][k] = *(const PG8_LAS bf16x8*)(lds + PG8_SB(b, h) + boff + n * 2048 + k * 1024); } while (0)
; #define PG8_MMA(ai, bj, At, Bt) do { __builtin_amdgcn_s_setprio(1); _Pragma("unroll") for (int m = 0; m < 4; ++m) _Pragma("unroll") for (int n = 0; n < 2; ++n) _Pragma("unroll") for (int k = 0; k < 2; ++k) \
;         acc[ai][bj][m][n] = __builtin_amdgcn_mfma_f32_16x16x32_bf16(Bt[n][k], At[m][k], acc[ai][bj][m][n], 0, 0, 0); __builtin_amdgcn_s_setprio(0); } while (0)
; #define PG8_WAIT_V(n) asm volatile("s_waitcnt vmcnt(" #n ")" ::: "memory")
; template <class Epi, class Sched, bool ALIGN_EPI = false, bool SP2 = false>
; __device__ __forceinline__ void gemm_phase(PG8_LAS unsigned char* lds, const Gemm g, const Sched& S, const Epi& E) {
;     ...
;             PG8_LDB(B0, 0, 0); PG8_LDB(B1, 0, 1); PG8_SCHED; PG8_LDA(At, 0, 0); PG8_STAGE(PG8_SA(1, 1), a1 + hstep, voffA);
;             PG8_WAIT_V(8); PG8_WAIT_L(0); PG8_BAR; PG8_MMA(0, 0, At, B0); PG8_MMA(0, 1, At, B1); PG8_BAR; PG8_SCHED;
;             if constexpr (Epi::PREFETCH) { if (t == tpf) E.prefetch(cur, wid, lane); }
; __device__ __forceinline__ void epi_prefetch(PG8_LAS unsigned char* scr, const float* ssq, const float* bias_tile, const Unit& u, int wid, int lane) {
;     unsigned lo = (unsigned)lane * 16u; asm volatile("" : "+v"(lo));
;     const char* src = (const char*)(ssq + (size_t)u.pm * BM * 16 + wid * 512);
; #pragma unroll
;     for (int j = 0; j < 2; ++j) __builtin_amdgcn_global_load_lds((const unsigned*)(src + j * 1024 + lo), (PG8_LAS unsigned*)(scr + (wid * 2 + j) * 1024), 16, 0, 0);
;     if (wid == 0) __builtin_amdgcn_global_load_lds((const unsigned*)((const char*)bias_tile + lo), (PG8_LAS unsigned*)(scr + 16384), 16, 0, 0);
; }
.LBB0_986:
	ds_read_b128 v[154:157], v195
	ds_read_b128 v[158:161], v195 offset:1024
	ds_read_b128 v[162:165], v195 offset:2048
	ds_read_b128 v[166:169], v195 offset:3072
	ds_read_b128 v[138:141], v196
	ds_read_b128 v[142:145], v196 offset:1024
	ds_read_b128 v[146:149], v196 offset:2048
	ds_read_b128 v[150:153], v196 offset:3072
	v_lshl_add_u64 v[98:99], v[188:189], 0, s[40:41]
	s_add_i32 m0, s54, 0xc000
	ds_read_b128 v[200:203], v197
	ds_read_b128 v[204:207], v197 offset:1024
	ds_read_b128 v[208:211], v197 offset:2048
	ds_read_b128 v[212:215], v197 offset:3072
	ds_read_b128 v[216:219], v197 offset:4096
	ds_read_b128 v[220:223], v197 offset:5120
	ds_read_b128 v[224:227], v197 offset:6144
	ds_read_b128 v[228:231], v197 offset:7168
	global_load_lds_dwordx4 v[98:99], off
	v_lshl_add_u64 v[98:99], v[190:191], 0, s[40:41]
	s_add_i32 m0, s54, 0xe000
	s_nop 0
	global_load_lds_dwordx4 v[98:99], off
	s_waitcnt vmcnt(8)
	s_waitcnt lgkmcnt(0)
	s_barrier
	s_setprio 3
	s_waitcnt lgkmcnt(0)
	v_mfma_f32_16x16x32_bf16 v[98:101], v[154:157], v[200:203], v[134:137]
	v_mfma_f32_16x16x32_bf16 v[106:109], v[162:165], v[200:203], v[130:133]
	v_mfma_f32_16x16x32_bf16 v[118:121], v[154:157], v[208:211], v[118:121]
	v_mfma_f32_16x16x32_bf16 v[114:117], v[162:165], v[208:211], v[114:117]
	v_mfma_f32_16x16x32_bf16 v[94:97], v[154:157], v[216:219], v[94:97]
	v_mfma_f32_16x16x32_bf16 v[90:93], v[162:165], v[216:219], v[90:93]
	v_mfma_f32_16x16x32_bf16 v[78:81], v[154:157], v[224:227], v[78:81]
	v_mfma_f32_16x16x32_bf16 v[74:77], v[162:165], v[224:227], v[74:77]
	v_mfma_f32_16x16x32_bf16 v[98:101], v[158:161], v[204:207], v[98:101]
	v_mfma_f32_16x16x32_bf16 v[106:109], v[166:169], v[204:207], v[106:109]
	v_mfma_f32_16x16x32_bf16 v[118:121], v[158:161], v[212:215], v[118:121]
	v_mfma_f32_16x16x32_bf16 v[114:117], v[166:169], v[212:215], v[114:117]
	v_mfma_f32_16x16x32_bf16 v[94:97], v[158:161], v[220:223], v[94:97]
	v_mfma_f32_16x16x32_bf16 v[90:93], v[166:169], v[220:223], v[90:93]
	v_mfma_f32_16x16x32_bf16 v[78:81], v[158:161], v[228:231], v[78:81]
	v_mfma_f32_16x16x32_bf16 v[74:77], v[166:169], v[228:231], v[74:77]
	s_setprio 0
	s_setprio 3
	v_mfma_f32_16x16x32_bf16 v[126:129], v[138:141], v[200:203], v[126:129]
	v_mfma_f32_16x16x32_bf16 v[122:125], v[146:149], v[200:203], v[122:125]
	v_mfma_f32_16x16x32_bf16 v[110:113], v[138:141], v[208:211], v[110:113]
	v_mfma_f32_16x16x32_bf16 v[102:105], v[146:149], v[208:211], v[102:105]
	v_mfma_f32_16x16x32_bf16 v[86:89], v[138:141], v[216:219], v[86:89]
	v_mfma_f32_16x16x32_bf16 v[82:85], v[146:149], v[216:219], v[82:85]
	v_mfma_f32_16x16x32_bf16 v[70:73], v[138:141], v[224:227], v[70:73]
	v_mfma_f32_16x16x32_bf16 v[66:69], v[146:149], v[224:227], v[66:69]
	v_mfma_f32_16x16x32_bf16 v[126:129], v[142:145], v[204:207], v[126:129]
	v_mfma_f32_16x16x32_bf16 v[122:125], v[150:153], v[204:207], v[122:125]
	v_mfma_f32_16x16x32_bf16 v[110:113], v[142:145], v[212:215], v[110:113]
	v_mfma_f32_16x16x32_bf16 v[102:105], v[150:153], v[212:215], v[102:105]
	v_mfma_f32_16x16x32_bf16 v[86:89], v[142:145], v[220:223], v[86:89]
	v_mfma_f32_16x16x32_bf16 v[82:85], v[150:153], v[220:223], v[82:85]
	v_mfma_f32_16x16x32_bf16 v[70:73], v[142:145], v[228:231], v[70:73]
	v_mfma_f32_16x16x32_bf16 v[66:69], v[150:153], v[228:231], v[66:69]
	s_setprio 0
	s_barrier
	s_cmp_lg_u32 s46, s83
	s_cbranch_scc1 .LBB0_985
	v_mov_b32_e32 v178, v194
	s_add_i32 m0, s79, 0x20000
	v_lshl_add_u64 v[130:131], s[36:37], 0, v[178:179]
	global_load_lds_dwordx4 v178, s[36:37]
	v_lshl_add_u64 v[130:131], v[130:131], 0, s[18:19]
	s_add_i32 m0, s79, 0x20400
	s_andn2_b64 vcc, exec, s[14:15]
	global_load_lds_dwordx4 v[130:131], off
	s_cbranch_vccnz .LBB0_985
	v_lshl_add_u64 v[130:131], s[38:39], 0, v[178:179]
	s_add_i32 m0, 0, 0x24000
	s_nop 0
	global_load_lds_dwordx4 v[130:131], off
	s_branch .LBB0_985

; #define PG8_STAGE(bufoff, gbase, voff) do { _Pragma("unroll") for (int _i = 0; _i < 2; ++_i) \
;         __builtin_amdgcn_global_load_lds((const unsigned*)((const char*)(gbase) + (voff)[_i]), (PG8_LAS unsigned*)(lds + (bufoff) + ldsw + _i * 8192), 16, 0, 0); } while (0)
; #define PG8_LDA(dst, b, h) do { _Pragma("unroll") for (int m = 0; m < 4; ++m) _Pragma("unroll") for (int k = 0; k < 2; ++k) dst[m][k] = *(const PG8_LAS bf16x8*)(lds + PG8_SA(b, h) + aoff + m * 2048 + k * 1024); } while (0)
; #define PG8_LDB(dst, b, h) do { _Pragma("unroll") for (int n = 0; n < 2; ++n) _Pragma("unroll") for (int k = 0; k < 2; ++k) dst[n][k] = *(const PG8_LAS bf16x8*)(lds + PG8_SB(b, h) + boff + n * 2048 + k * 1024); } while (0)
; #define PG8_MMA(ai, bj, At, Bt) do { __builtin_amdgcn_s_setprio(1); _Pragma("unroll") for (int m = 0; m < 4; ++m) _Pragma("unroll") for (int n = 0; n < 2; ++n) _Pragma("unroll") for (int k = 0; k < 2; ++k) \
;         acc[ai][bj][m][n] = __builtin_amdgcn_mfma_f32_16x16x32_bf16(Bt[n][k], At[m][k], acc[ai][bj][m][n], 0, 0, 0); __builtin_amdgcn_s_setprio(0); } while (0)
; #define PG8_BAR __builtin_amdgcn_s_barrier()
; template <class Epi, class Sched, bool ALIGN_EPI = false, bool SP2 = false>
; __device__ __forceinline__ void gemm_phase(PG8_LAS unsigned char* lds, const Gemm g, const Sched& S, const Epi& E) {
;     ...
;         for (int t = 0; t < nt; t += 2) {
;             const bool last = (t == nt - 2);
;             const char* a1 = cA + (size_t)(t + 1) * kstepA;
;             const char* a2 = last ? nA : cA + (size_t)(t + 2) * kstepA; const char* b2 = last ? nB : cB + (size_t)(t + 2) * kstep;
;             const char* a3 = a2 + kstepA; const char* b3 = b2 + kstep;
;             if (last && has_next) S.a_ready(nxt);
;             if constexpr (SP2) {
;             PG8_LDB(B0, 0, 0); PG8_LDB(B1, 0, 1); PG8_SCHED; PG8_LDA(At, 0, 0); PG8_STAGE(PG8_SA(1, 1), a1 + hstep, voffA);
;             PG8_WAIT_V(8); PG8_WAIT_L(0); PG8_BAR; PG8_MMA(0, 0, At, B0); PG8_MMA(0, 1, At, B1); PG8_BAR; PG8_SCHED;
;             if constexpr (Epi::PREFETCH) { if (t == tpf) E.prefetch(cur, wid, lane); }
;             PG8_LDA(At, 0, 1); PG8_STAGE(PG8_SB(0, 0), b2, voffB); PG8_STAGE(PG8_SB(0, 1), b2 + hstep, voffB); PG8_STAGE(PG8_SA(0, 0), a2, voffA);
;             PG8_WAIT_V(8); PG8_WAIT_L(0); PG8_BAR; PG8_MMA(1, 0, At, B0); PG8_MMA(1, 1, At, B1); PG8_BAR; PG8_SCHED;
.LBB0_1068:
	s_add_u32 s35, s6, 0x100
	s_addc_u32 s36, s7, 0
	s_mov_b32 s37, -2
	s_waitcnt lgkmcnt(0)
	ds_read_b128 v[130:133], v192
	ds_read_b128 v[134:137], v192 offset:1024
	ds_read_b128 v[156:159], v192 offset:2048
	ds_read_b128 v[160:163], v192 offset:3072
	ds_read_b128 v[164:167], v193
	ds_read_b128 v[168:171], v193 offset:1024
	ds_read_b128 v[172:175], v193 offset:2048
	ds_read_b128 v[176:179], v193 offset:3072
	s_add_u32 s0, s4, 0x200
	s_addc_u32 s1, s5, 0
	s_cmp_eq_u32 s37, 40
	s_cselect_b32 s31, s27, s1
	s_cselect_b32 s30, s26, s0
	s_cselect_b32 s7, s29, s36
	s_cselect_b32 s6, s28, s35
	v_lshl_add_u64 v[188:189], s[4:5], 0, v[148:149]
	s_add_i32 m0, s45, 0xc000
	ds_read_b128 v[180:183], v194
	ds_read_b128 v[184:187], v194 offset:1024
	ds_read_b128 v[196:199], v194 offset:2048
	ds_read_b128 v[200:203], v194 offset:3072
	ds_read_b128 v[204:207], v194 offset:4096
	ds_read_b128 v[208:211], v194 offset:5120
	ds_read_b128 v[212:215], v194 offset:6144
	ds_read_b128 v[216:219], v194 offset:7168
	global_load_lds_dwordx4 v[188:189], off
	v_lshl_add_u64 v[188:189], s[4:5], 0, v[150:151]
	s_add_i32 m0, s45, 0xe000
	s_nop 0
	global_load_lds_dwordx4 v[188:189], off
	s_waitcnt vmcnt(8)
	s_waitcnt lgkmcnt(0)
	s_barrier
	s_setprio 3
	s_waitcnt lgkmcnt(0)
	v_mfma_f32_16x16x32_bf16 v[126:129], v[130:133], v[180:183], 0
	v_mfma_f32_16x16x32_bf16 v[122:125], v[156:159], v[180:183], 0
	v_mfma_f32_16x16x32_bf16 v[110:113], v[130:133], v[196:199], 0
	v_mfma_f32_16x16x32_bf16 v[106:109], v[156:159], v[196:199], 0
	v_mfma_f32_16x16x32_bf16 v[94:97], v[130:133], v[204:207], 0
	v_mfma_f32_16x16x32_bf16 v[90:93], v[156:159], v[204:207], 0
	v_mfma_f32_16x16x32_bf16 v[78:81], v[130:133], v[212:215], 0
	v_mfma_f32_16x16x32_bf16 v[74:77], v[156:159], v[212:215], 0
	v_mfma_f32_16x16x32_bf16 v[126:129], v[134:137], v[184:187], v[126:129]
	v_mfma_f32_16x16x32_bf16 v[122:125], v[160:163], v[184:187], v[122:125]
	v_mfma_f32_16x16x32_bf16 v[110:113], v[134:137], v[200:203], v[110:113]
	v_mfma_f32_16x16x32_bf16 v[106:109], v[160:163], v[200:203], v[106:109]
	v_mfma_f32_16x16x32_bf16 v[94:97], v[134:137], v[208:211], v[94:97]
	v_mfma_f32_16x16x32_bf16 v[90:93], v[160:163], v[208:211], v[90:93]
	v_mfma_f32_16x16x32_bf16 v[78:81], v[134:137], v[216:219], v[78:81]
	v_mfma_f32_16x16x32_bf16 v[74:77], v[160:163], v[216:219], v[74:77]
	s_setprio 0
	s_setprio 3
	v_mfma_f32_16x16x32_bf16 v[118:121], v[164:167], v[180:183], 0
	v_mfma_f32_16x16x32_bf16 v[114:117], v[172:175], v[180:183], 0
	v_mfma_f32_16x16x32_bf16 v[102:105], v[164:167], v[196:199], 0
	v_mfma_f32_16x16x32_bf16 v[98:101], v[172:175], v[196:199], 0
	v_mfma_f32_16x16x32_bf16 v[86:89], v[164:167], v[204:207], 0
	v_mfma_f32_16x16x32_bf16 v[82:85], v[172:175], v[204:207], 0
	v_mfma_f32_16x16x32_bf16 v[70:73], v[164:167], v[212:215], 0
	v_mfma_f32_16x16x32_bf16 v[66:69], v[172:175], v[212:215], 0
	v_mfma_f32_16x16x32_bf16 v[118:121], v[168:171], v[184:187], v[118:121]
	v_mfma_f32_16x16x32_bf16 v[114:117], v[176:179], v[184:187], v[114:117]
	v_mfma_f32_16x16x32_bf16 v[102:105], v[168:171], v[200:203], v[102:105]
	v_mfma_f32_16x16x32_bf16 v[98:101], v[176:179], v[200:203], v[98:101]
	v_mfma_f32_16x16x32_bf16 v[86:89], v[168:171], v[208:211], v[86:89]
	v_mfma_f32_16x16x32_bf16 v[82:85], v[176:179], v[208:211], v[82:85]
	v_mfma_f32_16x16x32_bf16 v[70:73], v[168:171], v[216:219], v[70:73]
	v_mfma_f32_16x16x32_bf16 v[66:69], v[176:179], v[216:219], v[66:69]
	s_setprio 0
	s_barrier
	s_add_i32 s4, s61, s44
	v_lshl_add_u64 v[188:189], s[6:7], 0, v[140:141]
	s_mov_b32 m0, s4
	ds_read_b128 v[180:183], v194 offset:16384
	ds_read_b128 v[184:187], v194 offset:17408
	ds_read_b128 v[196:199], v194 offset:18432
	ds_read_b128 v[200:203], v194 offset:19456
	ds_read_b128 v[204:207], v194 offset:20480
	ds_read_b128 v[208:211], v194 offset:21504
	ds_read_b128 v[212:215], v194 offset:22528
	ds_read_b128 v[216:219], v194 offset:23552
	global_load_lds_dwordx4 v[188:189], off
	s_add_i32 m0, s4, 0x2000
	s_add_u32 s4, s6, 0xb0000
	v_lshl_add_u64 v[220:221], s[6:7], 0, v[144:145]
	s_addc_u32 s5, s7, 0
	s_add_i32 s38, s62, s44
	global_load_lds_dwordx4 v[220:221], off
	v_lshl_add_u64 v[222:223], s[4:5], 0, v[140:141]
	s_mov_b32 m0, s38
	v_lshl_add_u64 v[224:225], s[30:31], 0, v[142:143]
	global_load_lds_dwordx4 v[222:223], off
	v_lshl_add_u64 v[222:223], s[4:5], 0, v[144:145]
	s_add_i32 m0, s38, 0x2000
	s_nop 0
	global_load_lds_dwordx4 v[222:223], off
	v_lshl_add_u64 v[222:223], s[30:31], 0, v[138:139]
	s_mov_b32 m0, s45
	s_nop 0
	global_load_lds_dwordx4 v[222:223], off
	s_mov_b32 m0, s46
	s_nop 0
	global_load_lds_dwordx4 v[224:225], off
	s_waitcnt vmcnt(8)
	s_waitcnt lgkmcnt(0)
	s_barrier
	s_setprio 3
	s_waitcnt lgkmcnt(0)
	v_mfma_f32_16x16x32_bf16 v[62:65], v[130:133], v[180:183], 0
	v_mfma_f32_16x16x32_bf16 v[58:61], v[156:159], v[180:183], 0
	v_mfma_f32_16x16x32_bf16 v[46:49], v[130:133], v[196:199], 0
	v_mfma_f32_16x16x32_bf16 v[42:45], v[156:159], v[196:199], 0
	v_mfma_f32_16x16x32_bf16 v[30:33], v[130:133], v[204:207], 0
	v_mfma_f32_16x16x32_bf16 v[26:29], v[156:159], v[204:207], 0
	v_mfma_f32_16x16x32_bf16 v[14:17], v[130:133], v[212:215], 0
	v_mfma_f32_16x16x32_bf16 v[10:13], v[156:159], v[212:215], 0
	v_mfma_f32_16x16x32_bf16 v[62:65], v[134:137], v[184:187], v[62:65]
	v_mfma_f32_16x16x32_bf16 v[58:61], v[160:163], v[184:187], v[58:61]
	v_mfma_f32_16x16x32_bf16 v[46:49], v[134:137], v[200:203], v[46:49]
	v_mfma_f32_16x16x32_bf16 v[42:45], v[160:163], v[200:203], v[42:45]
	v_mfma_f32_16x16x32_bf16 v[30:33], v[134:137], v[208:211], v[30:33]
	v_mfma_f32_16x16x32_bf16 v[26:29], v[160:163], v[208:211], v[26:29]
	v_mfma_f32_16x16x32_bf16 v[14:17], v[134:137], v[216:219], v[14:17]
	v_mfma_f32_16x16x32_bf16 v[10:13], v[160:163], v[216:219], v[10:13]
	s_setprio 0
	s_setprio 3
	v_mfma_f32_16x16x32_bf16 v[54:57], v[164:167], v[180:183], 0
	v_mfma_f32_16x16x32_bf16 v[50:53], v[172:175], v[180:183], 0
	v_mfma_f32_16x16x32_bf16 v[38:41], v[164:167], v[196:199], 0
	v_mfma_f32_16x16x32_bf16 v[34:37], v[172:175], v[196:199], 0
	v_mfma_f32_16x16x32_bf16 v[22:25], v[164:167], v[204:207], 0
	v_mfma_f32_16x16x32_bf16 v[18:21], v[172:175], v[204:207], 0
	v_mfma_f32_16x16x32_bf16 v[6:9], v[164:167], v[212:215], 0
	v_mfma_f32_16x16x32_bf16 v[2:5], v[172:175], v[212:215], 0
	v_mfma_f32_16x16x32_bf16 v[54:57], v[168:171], v[184:187], v[54:57]
	v_mfma_f32_16x16x32_bf16 v[50:53], v[176:179], v[184:187], v[50:53]
	v_mfma_f32_16x16x32_bf16 v[38:41], v[168:171], v[200:203], v[38:41]
	v_mfma_f32_16x16x32_bf16 v[34:37], v[176:179], v[200:203], v[34:37]
	v_mfma_f32_16x16x32_bf16 v[22:25], v[168:171], v[208:211], v[22:25]
	v_mfma_f32_16x16x32_bf16 v[18:21], v[176:179], v[208:211], v[18:21]
	v_mfma_f32_16x16x32_bf16 v[6:9], v[168:171], v[216:219], v[6:9]
	v_mfma_f32_16x16x32_bf16 v[2:5], v[176:179], v[216:219], v[2:5]
	s_setprio 0
	s_barrier
	s_branch .Lpz6_mid
; #define PG8_STAGE(bufoff, gbase, voff) do { _Pragma("unroll") for (int _i = 0; _i < 2; ++_i) \
;         __builtin_amdgcn_global_load_lds((const unsigned*)((const char*)(gbase) + (voff)[_i]), (PG8_LAS unsigned*)(lds + (bufoff) + ldsw + _i * 8192), 16, 0, 0); } while (0)
; #define PG8_LDA(dst, b, h) do { _Pragma("unroll") for (int m = 0; m < 4; ++m) _Pragma("unroll") for (int k = 0; k < 2; ++k) dst[m][k] = *(const PG8_LAS bf16x8*)(lds + PG8_SA(b, h) + aoff + m * 2048 + k * 1024); } while (0)
; #define PG8_LDB(dst, b, h) do { _Pragma("unroll") for (int n = 0; n < 2; ++n) _Pragma("unroll") for (int k = 0; k < 2; ++k) dst[n][k] = *(const PG8_LAS bf16x8*)(lds + PG8_SB(b, h) + boff + n * 2048 + k * 1024); } while (0)
; #define PG8_MMA(ai, bj, At, Bt) do { __builtin_amdgcn_s_setprio(1); _Pragma("unroll") for (int m = 0; m < 4; ++m) _Pragma("unroll") for (int n = 0; n < 2; ++n) _Pragma("unroll") for (int k = 0; k < 2; ++k) \
;         acc[ai][bj][m][n] = __builtin_amdgcn_mfma_f32_16x16x32_bf16(Bt[n][k], At[m][k], acc[ai][bj][m][n], 0, 0, 0); __builtin_amdgcn_s_setprio(0); } while (0)
; #define PG8_WAIT_V(n) asm volatile("s_waitcnt vmcnt(" #n ")" ::: "memory")
; #define PG8_WAIT_L(n) asm volatile("s_waitcnt lgkmcnt(" #n ")" ::: "memory")
; #define PG8_BAR __builtin_amdgcn_s_barrier()
; #define PG8_SCHED __builtin_amdgcn_sched_barrier(0)
;     __device__ __forceinline__ void prefetch(const Unit& u, int wid, int lane) const { epi_prefetch(scr, ssq, bias + (size_t)(u.pm >> 5) * NGU + u.pn * BM, u, wid, lane); }
; template <class Epi, class Sched, bool ALIGN_EPI = false, bool SP2 = false>
; __device__ __forceinline__ void gemm_phase(PG8_LAS unsigned char* lds, const Gemm g, const Sched& S, const Epi& E) {
;     ...
;             PG8_LDB(B0, 0, 0); PG8_LDB(B1, 0, 1); PG8_SCHED; PG8_LDA(At, 0, 0); PG8_STAGE(PG8_SA(1, 1), a1 + hstep, voffA);
;             PG8_WAIT_V(8); PG8_WAIT_L(0); PG8_BAR; PG8_MMA(0, 0, At, B0); PG8_MMA(0, 1, At, B1); PG8_BAR; PG8_SCHED;
;             if constexpr (Epi::PREFETCH) { if (t == tpf) E.prefetch(cur, wid, lane); }
;             PG8_LDA(At, 0, 1); PG8_STAGE(PG8_SB(0, 0), b2, voffB); PG8_STAGE(PG8_SB(0, 1), b2 + hstep, voffB); PG8_STAGE(PG8_SA(0, 0), a2, voffA);
;             PG8_WAIT_V(8); PG8_WAIT_L(0); PG8_BAR; PG8_MMA(1, 0, At, B0); PG8_MMA(1, 1, At, B1); PG8_BAR; PG8_SCHED;
.LBB0_1069:
	ds_read_b128 v[130:133], v192
	ds_read_b128 v[134:137], v192 offset:1024
	ds_read_b128 v[156:159], v192 offset:2048
	ds_read_b128 v[160:163], v192 offset:3072
	ds_read_b128 v[164:167], v193
	ds_read_b128 v[168:171], v193 offset:1024
	ds_read_b128 v[172:175], v193 offset:2048
	ds_read_b128 v[176:179], v193 offset:3072
	s_add_u32 s0, s4, 0x200
	s_addc_u32 s1, s5, 0
	s_cmp_eq_u32 s37, 40
	s_cselect_b32 s31, s27, s1
	s_cselect_b32 s30, s26, s0
	s_cselect_b32 s7, s29, s36
	s_cselect_b32 s6, s28, s35
	v_lshl_add_u64 v[188:189], s[4:5], 0, v[148:149]
	s_add_i32 m0, s45, 0xc000
	ds_read_b128 v[180:183], v194
	ds_read_b128 v[184:187], v194 offset:1024
	ds_read_b128 v[196:199], v194 offset:2048
	ds_read_b128 v[200:203], v194 offset:3072
	ds_read_b128 v[204:207], v194 offset:4096
	ds_read_b128 v[208:211], v194 offset:5120
	ds_read_b128 v[212:215], v194 offset:6144
	ds_read_b128 v[216:219], v194 offset:7168
	global_load_lds_dwordx4 v[188:189], off
	v_lshl_add_u64 v[188:189], s[4:5], 0, v[150:151]
	s_add_i32 m0, s45, 0xe000
	s_nop 0
	global_load_lds_dwordx4 v[188:189], off
	s_waitcnt vmcnt(8)
	s_waitcnt lgkmcnt(0)
	s_barrier
	s_setprio 3
	s_waitcnt lgkmcnt(0)
	v_mfma_f32_16x16x32_bf16 v[126:129], v[130:133], v[180:183], v[126:129]
	v_mfma_f32_16x16x32_bf16 v[122:125], v[156:159], v[180:183], v[122:125]
	v_mfma_f32_16x16x32_bf16 v[110:113], v[130:133], v[196:199], v[110:113]
	v_mfma_f32_16x16x32_bf16 v[106:109], v[156:159], v[196:199], v[106:109]
	v_mfma_f32_16x16x32_bf16 v[94:97], v[130:133], v[204:207], v[94:97]
	v_mfma_f32_16x16x32_bf16 v[90:93], v[156:159], v[204:207], v[90:93]
	v_mfma_f32_16x16x32_bf16 v[78:81], v[130:133], v[212:215], v[78:81]
	v_mfma_f32_16x16x32_bf16 v[74:77], v[156:159], v[212:215], v[74:77]
	v_mfma_f32_16x16x32_bf16 v[126:129], v[134:137], v[184:187], v[126:129]
	v_mfma_f32_16x16x32_bf16 v[122:125], v[160:163], v[184:187], v[122:125]
	v_mfma_f32_16x16x32_bf16 v[110:113], v[134:137], v[200:203], v[110:113]
	v_mfma_f32_16x16x32_bf16 v[106:109], v[160:163], v[200:203], v[106:109]
	v_mfma_f32_16x16x32_bf16 v[94:97], v[134:137], v[208:211], v[94:97]
	v_mfma_f32_16x16x32_bf16 v[90:93], v[160:163], v[208:211], v[90:93]
	v_mfma_f32_16x16x32_bf16 v[78:81], v[134:137], v[216:219], v[78:81]
	v_mfma_f32_16x16x32_bf16 v[74:77], v[160:163], v[216:219], v[74:77]
	s_setprio 0
	s_setprio 3
	v_mfma_f32_16x16x32_bf16 v[118:121], v[164:167], v[180:183], v[118:121]
	v_mfma_f32_16x16x32_bf16 v[114:117], v[172:175], v[180:183], v[114:117]
	v_mfma_f32_16x16x32_bf16 v[102:105], v[164:167], v[196:199], v[102:105]
	v_mfma_f32_16x16x32_bf16 v[98:101], v[172:175], v[196:199], v[98:101]
	v_mfma_f32_16x16x32_bf16 v[86:89], v[164:167], v[204:207], v[86:89]
	v_mfma_f32_16x16x32_bf16 v[82:85], v[172:175], v[204:207], v[82:85]
	v_mfma_f32_16x16x32_bf16 v[70:73], v[164:167], v[212:215], v[70:73]
	v_mfma_f32_16x16x32_bf16 v[66:69], v[172:175], v[212:215], v[66:69]
	v_mfma_f32_16x16x32_bf16 v[118:121], v[168:171], v[184:187], v[118:121]
	v_mfma_f32_16x16x32_bf16 v[114:117], v[176:179], v[184:187], v[114:117]
	v_mfma_f32_16x16x32_bf16 v[102:105], v[168:171], v[200:203], v[102:105]
	v_mfma_f32_16x16x32_bf16 v[98:101], v[176:179], v[200:203], v[98:101]
	v_mfma_f32_16x16x32_bf16 v[86:89], v[168:171], v[208:211], v[86:89]
	v_mfma_f32_16x16x32_bf16 v[82:85], v[176:179], v[208:211], v[82:85]
	v_mfma_f32_16x16x32_bf16 v[70:73], v[168:171], v[216:219], v[70:73]
	v_mfma_f32_16x16x32_bf16 v[66:69], v[176:179], v[216:219], v[66:69]
	s_setprio 0
	s_barrier
	s_add_i32 s4, s61, s44
	v_lshl_add_u64 v[188:189], s[6:7], 0, v[140:141]
	s_mov_b32 m0, s4
	ds_read_b128 v[180:183], v194 offset:16384
	ds_read_b128 v[184:187], v194 offset:17408
	ds_read_b128 v[196:199], v194 offset:18432
	ds_read_b128 v[200:203], v194 offset:19456
	ds_read_b128 v[204:207], v194 offset:20480
	ds_read_b128 v[208:211], v194 offset:21504
	ds_read_b128 v[212:215], v194 offset:22528
	ds_read_b128 v[216:219], v194 offset:23552
	global_load_lds_dwordx4 v[188:189], off
	s_add_i32 m0, s4, 0x2000
	s_add_u32 s4, s6, 0xb0000
	v_lshl_add_u64 v[220:221], s[6:7], 0, v[144:145]
	s_addc_u32 s5, s7, 0
	s_add_i32 s38, s62, s44
	global_load_lds_dwordx4 v[220:221], off
	v_lshl_add_u64 v[222:223], s[4:5], 0, v[140:141]
	s_mov_b32 m0, s38
	v_lshl_add_u64 v[224:225], s[30:31], 0, v[142:143]
	global_load_lds_dwordx4 v[222:223], off
	v_lshl_add_u64 v[222:223], s[4:5], 0, v[144:145]
	s_add_i32 m0, s38, 0x2000
	s_nop 0
	global_load_lds_dwordx4 v[222:223], off
	v_lshl_add_u64 v[222:223], s[30:31], 0, v[138:139]
	s_mov_b32 m0, s45
	s_nop 0
	global_load_lds_dwordx4 v[222:223], off
	s_mov_b32 m0, s46
	s_nop 0
	global_load_lds_dwordx4 v[224:225], off
	s_waitcnt vmcnt(8)
	s_waitcnt lgkmcnt(0)
	s_barrier
	s_setprio 3
	s_waitcnt lgkmcnt(0)
	v_mfma_f32_16x16x32_bf16 v[62:65], v[130:133], v[180:183], v[62:65]
	v_mfma_f32_16x16x32_bf16 v[58:61], v[156:159], v[180:183], v[58:61]
	v_mfma_f32_16x16x32_bf16 v[46:49], v[130:133], v[196:199], v[46:49]
	v_mfma_f32_16x16x32_bf16 v[42:45], v[156:159], v[196:199], v[42:45]
	v_mfma_f32_16x16x32_bf16 v[30:33], v[130:133], v[204:207], v[30:33]
	v_mfma_f32_16x16x32_bf16 v[26:29], v[156:159], v[204:207], v[26:29]
	v_mfma_f32_16x16x32_bf16 v[14:17], v[130:133], v[212:215], v[14:17]
	v_mfma_f32_16x16x32_bf16 v[10:13], v[156:159], v[212:215], v[10:13]
	v_mfma_f32_16x16x32_bf16 v[62:65], v[134:137], v[184:187], v[62:65]
	v_mfma_f32_16x16x32_bf16 v[58:61], v[160:163], v[184:187], v[58:61]
	v_mfma_f32_16x16x32_bf16 v[46:49], v[134:137], v[200:203], v[46:49]
	v_mfma_f32_16x16x32_bf16 v[42:45], v[160:163], v[200:203], v[42:45]
	v_mfma_f32_16x16x32_bf16 v[30:33], v[134:137], v[208:211], v[30:33]
	v_mfma_f32_16x16x32_bf16 v[26:29], v[160:163], v[208:211], v[26:29]
	v_mfma_f32_16x16x32_bf16 v[14:17], v[134:137], v[216:219], v[14:17]
	v_mfma_f32_16x16x32_bf16 v[10:13], v[160:163], v[216:219], v[10:13]
	s_setprio 0
	s_setprio 3
	v_mfma_f32_16x16x32_bf16 v[54:57], v[164:167], v[180:183], v[54:57]
	v_mfma_f32_16x16x32_bf16 v[50:53], v[172:175], v[180:183], v[50:53]
	v_mfma_f32_16x16x32_bf16 v[38:41], v[164:167], v[196:199], v[38:41]
	v_mfma_f32_16x16x32_bf16 v[34:37], v[172:175], v[196:199], v[34:37]
	v_mfma_f32_16x16x32_bf16 v[22:25], v[164:167], v[204:207], v[22:25]
	v_mfma_f32_16x16x32_bf16 v[18:21], v[172:175], v[204:207], v[18:21]
	v_mfma_f32_16x16x32_bf16 v[6:9], v[164:167], v[212:215], v[6:9]
	v_mfma_f32_16x16x32_bf16 v[2:5], v[172:175], v[212:215], v[2:5]
	v_mfma_f32_16x16x32_bf16 v[54:57], v[168:171], v[184:187], v[54:57]
	v_mfma_f32_16x16x32_bf16 v[50:53], v[176:179], v[184:187], v[50:53]
	v_mfma_f32_16x16x32_bf16 v[38:41], v[168:171], v[200:203], v[38:41]
	v_mfma_f32_16x16x32_bf16 v[34:37], v[176:179], v[200:203], v[34:37]
	v_mfma_f32_16x16x32_bf16 v[22:25], v[168:171], v[208:211], v[22:25]
	v_mfma_f32_16x16x32_bf16 v[18:21], v[176:179], v[208:211], v[18:21]
	v_mfma_f32_16x16x32_bf16 v[6:9], v[168:171], v[216:219], v[6:9]
	v_mfma_f32_16x16x32_bf16 v[2:5], v[176:179], v[216:219], v[2:5]
	s_setprio 0
	s_barrier
; #define PG8_STAGE(bufoff, gbase, voff) do { _Pragma("unroll") for (int _i = 0; _i < 2; ++_i) \
;         __builtin_amdgcn_global_load_lds((const unsigned*)((const char*)(gbase) + (voff)[_i]), (PG8_LAS unsigned*)(lds + (bufoff) + ldsw + _i * 8192), 16, 0, 0); } while (0)
; #define PG8_LDA(dst, b, h) do { _Pragma("unroll") for (int m = 0; m < 4; ++m) _Pragma("unroll") for (int k = 0; k < 2; ++k) dst[m][k] = *(const PG8_LAS bf16x8*)(lds + PG8_SA(b, h) + aoff + m * 2048 + k * 1024); } while (0)
; #define PG8_LDB(dst, b, h) do { _Pragma("unroll") for (int n = 0; n < 2; ++n) _Pragma("unroll") for (int k = 0; k < 2; ++k) dst[n][k] = *(const PG8_LAS bf16x8*)(lds + PG8_SB(b, h) + boff + n * 2048 + k * 1024); } while (0)
; #define PG8_MMA(ai, bj, At, Bt) do { __builtin_amdgcn_s_setprio(1); _Pragma("unroll") for (int m = 0; m < 4; ++m) _Pragma("unroll") for (int n = 0; n < 2; ++n) _Pragma("unroll") for (int k = 0; k < 2; ++k) \
;         acc[ai][bj][m][n] = __builtin_amdgcn_mfma_f32_16x16x32_bf16(Bt[n][k], At[m][k], acc[ai][bj][m][n], 0, 0, 0); __builtin_amdgcn_s_setprio(0); } while (0)
; #define PG8_WAIT_V(n) asm volatile("s_waitcnt vmcnt(" #n ")" ::: "memory")
; #define PG8_WAIT_L(n) asm volatile("s_waitcnt lgkmcnt(" #n ")" ::: "memory")
; #define PG8_BAR __builtin_amdgcn_s_barrier()
; #define PG8_SCHED __builtin_amdgcn_sched_barrier(0)
; template <class Epi, class Sched, bool ALIGN_EPI = false, bool SP2 = false>
; __device__ __forceinline__ void gemm_phase(PG8_LAS unsigned char* lds, const Gemm g, const Sched& S, const Epi& E) {
;     ...
;             PG8_LDB(B0, 1, 0); PG8_LDB(B1, 1, 1); PG8_SCHED; PG8_LDA(At, 1, 0); PG8_STAGE(PG8_SA(0, 1), a2 + hstep, voffA);
;             PG8_WAIT_V(8); PG8_WAIT_L(0); PG8_BAR; PG8_MMA(0, 0, At, B0); PG8_MMA(0, 1, At, B1); PG8_BAR; PG8_SCHED;
.Lpz6_mid:
	s_add_i32 s38, 0, 0x18000
	v_add_u32_e32 v146, s38, v191
	s_add_i32 s39, 0, 0x1c000
	ds_read_b128 v[130:133], v146
	ds_read_b128 v[134:137], v146 offset:1024
	ds_read_b128 v[156:159], v146 offset:2048
	ds_read_b128 v[160:163], v146 offset:3072
	v_add_u32_e32 v146, s39, v191
	ds_read_b128 v[164:167], v146
	ds_read_b128 v[168:171], v146 offset:1024
	ds_read_b128 v[172:175], v146 offset:2048
	ds_read_b128 v[176:179], v146 offset:3072
	s_add_u32 s4, s30, 0xb0000
	s_addc_u32 s5, s31, 0
	s_mov_b32 m0, s47
	v_lshl_add_u64 v[226:227], s[4:5], 0, v[138:139]
	ds_read_b128 v[180:183], v194 offset:32768
	ds_read_b128 v[184:187], v194 offset:33792
	ds_read_b128 v[196:199], v194 offset:34816
	ds_read_b128 v[200:203], v194 offset:35840
	ds_read_b128 v[204:207], v194 offset:36864
	ds_read_b128 v[208:211], v194 offset:37888
	ds_read_b128 v[212:215], v194 offset:38912
	ds_read_b128 v[216:219], v194 offset:39936
	global_load_lds_dwordx4 v[226:227], off
	v_lshl_add_u64 v[226:227], s[4:5], 0, v[142:143]
	s_mov_b32 m0, s48
	s_nop 0
	global_load_lds_dwordx4 v[226:227], off
	s_waitcnt vmcnt(8)
	s_waitcnt lgkmcnt(0)
	s_barrier
	s_setprio 3
	s_waitcnt lgkmcnt(0)
	v_mfma_f32_16x16x32_bf16 v[126:129], v[130:133], v[180:183], v[126:129]
	v_mfma_f32_16x16x32_bf16 v[122:125], v[156:159], v[180:183], v[122:125]
	v_mfma_f32_16x16x32_bf16 v[110:113], v[130:133], v[196:199], v[110:113]
	v_mfma_f32_16x16x32_bf16 v[106:109], v[156:159], v[196:199], v[106:109]
	v_mfma_f32_16x16x32_bf16 v[94:97], v[130:133], v[204:207], v[94:97]
	v_mfma_f32_16x16x32_bf16 v[90:93], v[156:159], v[204:207], v[90:93]
	v_mfma_f32_16x16x32_bf16 v[78:81], v[130:133], v[212:215], v[78:81]
	v_mfma_f32_16x16x32_bf16 v[74:77], v[156:159], v[212:215], v[74:77]
	v_mfma_f32_16x16x32_bf16 v[126:129], v[134:137], v[184:187], v[126:129]
	v_mfma_f32_16x16x32_bf16 v[122:125], v[160:163], v[184:187], v[122:125]
	v_mfma_f32_16x16x32_bf16 v[110:113], v[134:137], v[200:203], v[110:113]
	v_mfma_f32_16x16x32_bf16 v[106:109], v[160:163], v[200:203], v[106:109]
	v_mfma_f32_16x16x32_bf16 v[94:97], v[134:137], v[208:211], v[94:97]
	v_mfma_f32_16x16x32_bf16 v[90:93], v[160:163], v[208:211], v[90:93]
	v_mfma_f32_16x16x32_bf16 v[78:81], v[134:137], v[216:219], v[78:81]
	v_mfma_f32_16x16x32_bf16 v[74:77], v[160:163], v[216:219], v[74:77]
	s_setprio 0
	s_setprio 3
	v_mfma_f32_16x16x32_bf16 v[118:121], v[164:167], v[180:183], v[118:121]
	v_mfma_f32_16x16x32_bf16 v[114:117], v[172:175], v[180:183], v[114:117]
	v_mfma_f32_16x16x32_bf16 v[102:105], v[164:167], v[196:199], v[102:105]
	v_mfma_f32_16x16x32_bf16 v[98:101], v[172:175], v[196:199], v[98:101]
	v_mfma_f32_16x16x32_bf16 v[86:89], v[164:167], v[204:207], v[86:89]
	v_mfma_f32_16x16x32_bf16 v[82:85], v[172:175], v[204:207], v[82:85]
	v_mfma_f32_16x16x32_bf16 v[70:73], v[164:167], v[212:215], v[70:73]
	v_mfma_f32_16x16x32_bf16 v[66:69], v[172:175], v[212:215], v[66:69]
	v_mfma_f32_16x16x32_bf16 v[118:121], v[168:171], v[184:187], v[118:121]
	v_mfma_f32_16x16x32_bf16 v[114:117], v[176:179], v[184:187], v[114:117]
	v_mfma_f32_16x16x32_bf16 v[102:105], v[168:171], v[200:203], v[102:105]
	v_mfma_f32_16x16x32_bf16 v[98:101], v[176:179], v[200:203], v[98:101]
	v_mfma_f32_16x16x32_bf16 v[86:89], v[168:171], v[208:211], v[86:89]
	v_mfma_f32_16x16x32_bf16 v[82:85], v[176:179], v[208:211], v[82:85]
	v_mfma_f32_16x16x32_bf16 v[70:73], v[168:171], v[216:219], v[70:73]
	v_mfma_f32_16x16x32_bf16 v[66:69], v[176:179], v[216:219], v[66:69]
	s_setprio 0
	s_barrier
; #define PG8_STAGE(bufoff, gbase, voff) do { _Pragma("unroll") for (int _i = 0; _i < 2; ++_i) \
;         __builtin_amdgcn_global_load_lds((const unsigned*)((const char*)(gbase) + (voff)[_i]), (PG8_LAS unsigned*)(lds + (bufoff) + ldsw + _i * 8192), 16, 0, 0); } while (0)
; #define PG8_LDA(dst, b, h) do { _Pragma("unroll") for (int m = 0; m < 4; ++m) _Pragma("unroll") for (int k = 0; k < 2; ++k) dst[m][k] = *(const PG8_LAS bf16x8*)(lds + PG8_SA(b, h) + aoff + m * 2048 + k * 1024); } while (0)
; #define PG8_MMA(ai, bj, At, Bt) do { __builtin_amdgcn_s_setprio(1); _Pragma("unroll") for (int m = 0; m < 4; ++m) _Pragma("unroll") for (int n = 0; n < 2; ++n) _Pragma("unroll") for (int k = 0; k < 2; ++k) \
;         acc[ai][bj][m][n] = __builtin_amdgcn_mfma_f32_16x16x32_bf16(Bt[n][k], At[m][k], acc[ai][bj][m][n], 0, 0, 0); __builtin_amdgcn_s_setprio(0); } while (0)
; #define PG8_WAIT_V(n) asm volatile("s_waitcnt vmcnt(" #n ")" ::: "memory")
; #define PG8_WAIT_L(n) asm volatile("s_waitcnt lgkmcnt(" #n ")" ::: "memory")
; #define PG8_BAR __builtin_amdgcn_s_barrier()
; #define PG8_SCHED __builtin_amdgcn_sched_barrier(0)
; template <class Epi, class Sched, bool ALIGN_EPI = false, bool SP2 = false>
; __device__ __forceinline__ void gemm_phase(PG8_LAS unsigned char* lds, const Gemm g, const Sched& S, const Epi& E) {
;     ...
;             PG8_LDA(At, 1, 1); PG8_STAGE(PG8_SB(1, 0), b3, voffB); PG8_STAGE(PG8_SB(1, 1), b3 + hstep, voffB); PG8_STAGE(PG8_SA(1, 0), a3, voffA);
;             PG8_WAIT_V(8); PG8_WAIT_L(0); PG8_BAR; PG8_MMA(1, 0, At, B0); PG8_MMA(1, 1, At, B1); PG8_BAR; PG8_SCHED;
;     ...
;         if constexpr (ALIGN_EPI) { if (wr == 0) PG8_BAR; }
	s_add_i32 s4, s38, s44
	v_lshl_add_u64 v[188:189], v[188:189], 0, s[18:19]
	s_mov_b32 m0, s4
	ds_read_b128 v[180:183], v194 offset:49152
	ds_read_b128 v[184:187], v194 offset:50176
	ds_read_b128 v[196:199], v194 offset:51200
	ds_read_b128 v[200:203], v194 offset:52224
	ds_read_b128 v[204:207], v194 offset:53248
	ds_read_b128 v[208:211], v194 offset:54272
	ds_read_b128 v[212:215], v194 offset:55296
	ds_read_b128 v[216:219], v194 offset:56320
	global_load_lds_dwordx4 v[188:189], off
	s_add_i32 m0, s4, 0x2000
	s_add_u32 s4, s6, 0xb0080
	v_lshl_add_u64 v[188:189], v[220:221], 0, s[18:19]
	s_addc_u32 s5, s7, 0
	s_add_i32 s6, s39, s44
	global_load_lds_dwordx4 v[188:189], off
	v_lshl_add_u64 v[188:189], s[4:5], 0, v[140:141]
	s_mov_b32 m0, s6
	s_nop 0
	global_load_lds_dwordx4 v[188:189], off
	v_lshl_add_u64 v[188:189], s[4:5], 0, v[144:145]
	s_add_i32 m0, s6, 0x2000
	s_nop 0
	global_load_lds_dwordx4 v[188:189], off
	v_lshl_add_u64 v[188:189], v[222:223], 0, s[20:21]
	s_mov_b32 m0, s55
	s_nop 0
	global_load_lds_dwordx4 v[188:189], off
	v_lshl_add_u64 v[188:189], v[224:225], 0, s[20:21]
	s_mov_b32 m0, s56
	s_nop 0
	global_load_lds_dwordx4 v[188:189], off
	s_waitcnt vmcnt(8)
	s_waitcnt lgkmcnt(0)
	s_barrier
	s_setprio 3
	s_waitcnt lgkmcnt(0)
	v_mfma_f32_16x16x32_bf16 v[62:65], v[130:133], v[180:183], v[62:65]
	v_mfma_f32_16x16x32_bf16 v[58:61], v[156:159], v[180:183], v[58:61]
	v_mfma_f32_16x16x32_bf16 v[46:49], v[130:133], v[196:199], v[46:49]
	v_mfma_f32_16x16x32_bf16 v[42:45], v[156:159], v[196:199], v[42:45]
	v_mfma_f32_16x16x32_bf16 v[30:33], v[130:133], v[204:207], v[30:33]
	v_mfma_f32_16x16x32_bf16 v[26:29], v[156:159], v[204:207], v[26:29]
	v_mfma_f32_16x16x32_bf16 v[14:17], v[130:133], v[212:215], v[14:17]
	v_mfma_f32_16x16x32_bf16 v[10:13], v[156:159], v[212:215], v[10:13]
	v_mfma_f32_16x16x32_bf16 v[62:65], v[134:137], v[184:187], v[62:65]
	v_mfma_f32_16x16x32_bf16 v[58:61], v[160:163], v[184:187], v[58:61]
	v_mfma_f32_16x16x32_bf16 v[46:49], v[134:137], v[200:203], v[46:49]
	v_mfma_f32_16x16x32_bf16 v[42:45], v[160:163], v[200:203], v[42:45]
	v_mfma_f32_16x16x32_bf16 v[30:33], v[134:137], v[208:211], v[30:33]
	v_mfma_f32_16x16x32_bf16 v[26:29], v[160:163], v[208:211], v[26:29]
	v_mfma_f32_16x16x32_bf16 v[14:17], v[134:137], v[216:219], v[14:17]
	v_mfma_f32_16x16x32_bf16 v[10:13], v[160:163], v[216:219], v[10:13]
	s_setprio 0
	s_setprio 3
	v_mfma_f32_16x16x32_bf16 v[54:57], v[164:167], v[180:183], v[54:57]
	v_mfma_f32_16x16x32_bf16 v[50:53], v[172:175], v[180:183], v[50:53]
	v_mfma_f32_16x16x32_bf16 v[38:41], v[164:167], v[196:199], v[38:41]
	v_mfma_f32_16x16x32_bf16 v[34:37], v[172:175], v[196:199], v[34:37]
	v_mfma_f32_16x16x32_bf16 v[22:25], v[164:167], v[204:207], v[22:25]
	v_mfma_f32_16x16x32_bf16 v[18:21], v[172:175], v[204:207], v[18:21]
	v_mfma_f32_16x16x32_bf16 v[6:9], v[164:167], v[212:215], v[6:9]
	v_mfma_f32_16x16x32_bf16 v[2:5], v[172:175], v[212:215], v[2:5]
	v_mfma_f32_16x16x32_bf16 v[54:57], v[168:171], v[184:187], v[54:57]
	v_mfma_f32_16x16x32_bf16 v[50:53], v[176:179], v[184:187], v[50:53]
	v_mfma_f32_16x16x32_bf16 v[38:41], v[168:171], v[200:203], v[38:41]
	v_mfma_f32_16x16x32_bf16 v[34:37], v[176:179], v[200:203], v[34:37]
	v_mfma_f32_16x16x32_bf16 v[22:25], v[168:171], v[208:211], v[22:25]
	v_mfma_f32_16x16x32_bf16 v[18:21], v[176:179], v[208:211], v[18:21]
	v_mfma_f32_16x16x32_bf16 v[6:9], v[168:171], v[216:219], v[6:9]
	v_mfma_f32_16x16x32_bf16 v[2:5], v[176:179], v[216:219], v[2:5]
	s_setprio 0
	s_barrier
	s_add_i32 s37, s37, 2
	s_add_u32 s35, s35, 0x100
	s_addc_u32 s36, s36, 0
	s_cmp_gt_u32 s37, 41
	s_mov_b64 s[4:5], s[0:1]
	s_cbranch_scc0 .LBB0_1069
	s_and_b64 vcc, exec, s[22:23]
	s_cbranch_vccz .LBB0_1072
	s_barrier
